# code placement: the 8 GEMM K-loop heads and the two heavy attention loop bodies aligned to 64 bytes; on top of v53
# speedup vs baseline: 1.0024x; 1.0019x over previous
; #define LDA8(dst, b, h) _Pragma("unroll") for (int m = 0; m < 4; ++m) _Pragma("unroll") for (int k = 0; k < 2; ++k) \
;     dst[m][k] = *(const bf16x8*)((const char*)SA8(b, h) + lds_byte8(wr * 64 + m * 16 + fr, k * 32 + fq * 8))
; #define LDB8(dst, b, h) _Pragma("unroll") for (int n = 0; n < 2; ++n) _Pragma("unroll") for (int k = 0; k < 2; ++k) \
;     dst[n][k] = *(const bf16x8*)((const char*)SB8(b, h) + lds_byte8(wc * 32 + n * 16 + fr, k * 32 + fq * 8))
; #define WAIT_V8(n) asm volatile("s_waitcnt vmcnt(" #n ")" ::: "memory")
; #define WAIT_L8(n) asm volatile("s_waitcnt lgkmcnt(" #n ")" ::: "memory")
; #define BAR8 __builtin_amdgcn_s_barrier()
; #define SCHED8 __builtin_amdgcn_sched_barrier(0)
;     ...
;   if (wr == 1) BAR8;
;   WAIT_V8(4); BAR8;
;   STAGE8(SB8(1, 0), Bt, K, bcol, 1); STAGE8(SA8(1, 0), A, lda, brow, 1); STAGE8(SB8(1, 1), Bt, K, bcol + 128, 1);
;   WAIT_V8(6); BAR8;
;   for (int tt = 0; tt < nt - 2; tt += 2) {
;     LDB8(B0, 0, 0); SCHED8; LDA8(At, 0, 0); STAGE8(SA8(1, 1), A, lda, brow + 128, tt + 1);
;     WAIT_L8(8); BAR8; WAIT_L8(0); MMA8(0, 0, At, B0); BAR8; SCHED8;
.LBB0_191:
	s_or_b64 exec, exec, s[14:15]
	s_mov_b64 s[60:61], 0x80
	v_lshl_add_u64 v[10:11], v[10:11], 0, s[60:61]
	s_or_b32 m0, s100, 0x18000
	s_waitcnt vmcnt(4)
	s_barrier
	global_load_lds_dwordx4 v[10:11], off
	v_lshl_add_u64 v[10:11], v[12:13], 0, s[60:61]
	s_or_b32 m0, s100, 0x1a000
	s_nop 0
	global_load_lds_dwordx4 v[10:11], off
	v_lshl_add_u64 v[10:11], v[14:15], 0, s[60:61]
	s_or_b32 m0, s100, 0x8000
	s_nop 0
	global_load_lds_dwordx4 v[10:11], off
	v_lshl_add_u64 v[10:11], v[16:17], 0, s[60:61]
	s_or_b32 m0, s100, 0xa000
	s_nop 0
	global_load_lds_dwordx4 v[10:11], off
	s_or_b32 m0, s100, 0x1c000
	v_lshl_add_u64 v[10:11], v[18:19], 0, s[60:61]
	global_load_lds_dwordx4 v[10:11], off
	v_lshl_add_u64 v[10:11], v[20:21], 0, s[60:61]
	s_or_b32 m0, s100, 0x1e000
	v_and_b32_e32 v147, 15, v3
	global_load_lds_dwordx4 v[10:11], off
	v_bfe_u32 v148, v3, 4, 2
	v_lshlrev_b32_e32 v10, 4, v148
	v_lshlrev_b32_e32 v11, 6, v147
	v_lshlrev_b32_e32 v14, 2, v3
	v_or_b32_e32 v13, v10, v11
	v_and_b32_e32 v14, 32, v14
	s_mov_b32 s14, 0x10000
	v_bitop3_b32 v16, v13, s14, v14 bitop3:0xde
	s_mov_b32 s14, 0x14000
	v_bitop3_b32 v15, v10, v14, v11 bitop3:0x36
	v_bitop3_b32 v17, v13, s14, v14 bitop3:0xde
	s_mov_b32 s14, 0x18000
	v_lshlrev_b32_e32 v11, 6, v3
	v_bitop3_b32 v18, v13, s14, v14 bitop3:0xde
	s_mov_b32 s14, 0x1c000
	v_and_b32_e32 v11, 0x3c0, v11
	v_bitop3_b32 v13, v13, s14, v14 bitop3:0xde
	v_bitop3_b32 v14, v11, v14, v10 bitop3:0x36
	v_lshl_add_u64 v[10:11], s[30:31], 0, v[136:137]
	v_lshl_add_u64 v[10:11], v[10:11], 0, v[8:9]
	v_lshl_add_u64 v[138:139], s[12:13], 0, v[10:11]
	v_lshl_add_u64 v[10:11], s[30:31], 0, v[132:133]
	v_lshl_add_u64 v[10:11], v[10:11], 0, v[6:7]
	v_lshl_add_u64 v[140:141], s[12:13], 0, v[10:11]
	v_lshl_add_u64 v[10:11], s[56:57], 0, v[132:133]
	v_lshl_add_u64 v[6:7], v[10:11], 0, v[6:7]
	v_bfe_u32 v146, v3, 6, 2
	s_waitcnt vmcnt(6)
	v_lshlrev_b32_e32 v149, 6, v5
	v_lshlrev_b32_e32 v5, 13, v5
	v_lshl_add_u64 v[142:143], s[46:47], 0, v[6:7]
	v_lshl_add_u64 v[6:7], s[56:57], 0, v[136:137]
	v_lshlrev_b32_e32 v12, 12, v146
	v_or_b32_e32 v19, 0x800, v5
	v_or_b32_e32 v20, 0x1000, v5
	v_or_b32_e32 v21, 0x1800, v5
	v_lshl_add_u64 v[6:7], v[6:7], 0, v[8:9]
	v_lshl_add_u64 v[144:145], s[46:47], 0, v[6:7]
	s_mov_b32 s14, -2
	s_mov_b64 s[12:13], 0
	v_add_u32_e32 v173, v16, v12
	v_add_u32_e32 v156, v15, v5
	v_add_u32_e32 v154, v14, v19
	v_add_u32_e32 v153, v14, v20
	v_add_u32_e32 v152, v14, v21
	v_add_u32_e32 v169, v17, v12
	v_add_u32_e32 v159, v18, v12
	v_add_u32_e32 v158, v13, v12
	s_mov_b64 s[60:61], 0xc000100
	s_mov_b64 s[62:63], 0xc040100
	s_mov_b64 s[64:65], 0xc000180
	s_mov_b64 s[66:67], 0xc040180
	s_barrier
	ds_read_b128 v[174:177], v173
	ds_read_b128 v[178:181], v173 offset:1024
	ds_read_b128 v[182:185], v173 offset:2048
	ds_read_b128 v[186:189], v173 offset:3072
	v_lshl_add_u64 v[222:223], v[140:141], 0, s[12:13]
	v_lshl_add_u64 v[226:227], v[222:223], 0, s[34:35]
	s_or_b32 m0, s100, 0xc000
	ds_read_b128 v[190:193], v156
	ds_read_b128 v[194:197], v156 offset:1024
	ds_read_b128 v[198:201], v154
	ds_read_b128 v[202:205], v154 offset:1024
	ds_read_b128 v[206:209], v153
	ds_read_b128 v[210:213], v153 offset:1024
	ds_read_b128 v[214:217], v152
	ds_read_b128 v[218:221], v152 offset:1024
	global_load_lds_dwordx4 v[226:227], off
	v_lshl_add_u64 v[226:227], v[138:139], 0, s[12:13]
	s_or_b32 m0, s100, 0xe000
	v_lshl_add_u64 v[228:229], v[226:227], 0, s[34:35]
	global_load_lds_dwordx4 v[228:229], off
	s_waitcnt lgkmcnt(8)
	s_barrier
	s_waitcnt lgkmcnt(0)
	v_mfma_f32_16x16x32_f16 v[128:131], v[190:193], v[174:177], 0
	v_mfma_f32_16x16x32_f16 v[124:127], v[190:193], v[182:185], 0
	v_mfma_f32_16x16x32_f16 v[120:123], v[198:201], v[174:177], 0
	v_mfma_f32_16x16x32_f16 v[116:119], v[198:201], v[182:185], 0
	v_mfma_f32_16x16x32_f16 v[112:115], v[206:209], v[174:177], 0
	v_mfma_f32_16x16x32_f16 v[108:111], v[206:209], v[182:185], 0
	v_mfma_f32_16x16x32_f16 v[104:107], v[214:217], v[174:177], 0
	v_mfma_f32_16x16x32_f16 v[100:103], v[214:217], v[182:185], 0
	v_mfma_f32_16x16x32_f16 v[128:131], v[194:197], v[178:181], v[128:131]
	v_mfma_f32_16x16x32_f16 v[124:127], v[194:197], v[186:189], v[124:127]
	v_mfma_f32_16x16x32_f16 v[120:123], v[202:205], v[178:181], v[120:123]
	v_mfma_f32_16x16x32_f16 v[116:119], v[202:205], v[186:189], v[116:119]
	v_mfma_f32_16x16x32_f16 v[112:115], v[210:213], v[178:181], v[112:115]
	v_mfma_f32_16x16x32_f16 v[108:111], v[210:213], v[186:189], v[108:111]
	v_mfma_f32_16x16x32_f16 v[104:107], v[218:221], v[178:181], v[104:107]
	v_mfma_f32_16x16x32_f16 v[100:103], v[218:221], v[186:189], v[100:103]
	s_barrier
	v_lshl_add_u64 v[228:229], v[142:143], 0, s[12:13]
	v_lshl_add_u64 v[236:237], v[228:229], 0, s[60:61]
	s_or_b32 m0, s100, 0x10000
	ds_read_b128 v[238:241], v169
	ds_read_b128 v[242:245], v169 offset:1024
	ds_read_b128 v[246:249], v169 offset:2048
	ds_read_b128 v[230:233], v169 offset:3072
	global_load_lds_dwordx4 v[236:237], off
	v_lshl_add_u64 v[236:237], v[144:145], 0, s[12:13]
	s_or_b32 m0, s100, 0x12000
	v_lshl_add_u64 v[250:251], v[236:237], 0, s[60:61]
	global_load_lds_dwordx4 v[250:251], off
	s_barrier
; #define LDA8(dst, b, h) _Pragma("unroll") for (int m = 0; m < 4; ++m) _Pragma("unroll") for (int k = 0; k < 2; ++k) \
;     dst[m][k] = *(const bf16x8*)((const char*)SA8(b, h) + lds_byte8(wr * 64 + m * 16 + fr, k * 32 + fq * 8))
; #define LDB8(dst, b, h) _Pragma("unroll") for (int n = 0; n < 2; ++n) _Pragma("unroll") for (int k = 0; k < 2; ++k) \
;     dst[n][k] = *(const bf16x8*)((const char*)SB8(b, h) + lds_byte8(wc * 32 + n * 16 + fr, k * 32 + fq * 8))
; #define WAIT_V8(n) asm volatile("s_waitcnt vmcnt(" #n ")" ::: "memory")
; #define WAIT_L8(n) asm volatile("s_waitcnt lgkmcnt(" #n ")" ::: "memory")
; #define BAR8 __builtin_amdgcn_s_barrier()
; #define SCHED8 __builtin_amdgcn_sched_barrier(0)
;     ...
;     WAIT_L8(8); BAR8; WAIT_L8(0); MMA8(0, 0, At, B0); BAR8; SCHED8;
;     LDB8(B1, 0, 1); STAGE8(SB8(0, 0), Bt, K, bcol, tt + 2);
;     BAR8; WAIT_L8(0); MMA8(0, 1, At, B1); BAR8;
;     LDA8(At, 0, 1); STAGE8(SA8(0, 0), A, lda, brow, tt + 2);
;     BAR8; WAIT_L8(0); MMA8(1, 0, At, B0); BAR8; SCHED8;
;     STAGE8(SB8(0, 1), Bt, K, bcol + 128, tt + 2);
;     WAIT_V8(6); BAR8; MMA8(1, 1, At, B1); BAR8;
	s_waitcnt lgkmcnt(0)
	v_mfma_f32_16x16x32_f16 v[96:99], v[190:193], v[238:241], 0
	v_mfma_f32_16x16x32_f16 v[92:95], v[190:193], v[246:249], 0
	v_mfma_f32_16x16x32_f16 v[88:91], v[198:201], v[238:241], 0
	v_mfma_f32_16x16x32_f16 v[84:87], v[198:201], v[246:249], 0
	v_mfma_f32_16x16x32_f16 v[80:83], v[206:209], v[238:241], 0
	v_mfma_f32_16x16x32_f16 v[76:79], v[206:209], v[246:249], 0
	v_mfma_f32_16x16x32_f16 v[72:75], v[214:217], v[238:241], 0
	v_mfma_f32_16x16x32_f16 v[68:71], v[214:217], v[246:249], 0
	v_mfma_f32_16x16x32_f16 v[96:99], v[194:197], v[242:245], v[96:99]
	v_mfma_f32_16x16x32_f16 v[92:95], v[194:197], v[230:233], v[92:95]
	v_mfma_f32_16x16x32_f16 v[88:91], v[202:205], v[242:245], v[88:91]
	v_mfma_f32_16x16x32_f16 v[84:87], v[202:205], v[230:233], v[84:87]
	v_mfma_f32_16x16x32_f16 v[80:83], v[210:213], v[242:245], v[80:83]
	v_mfma_f32_16x16x32_f16 v[76:79], v[210:213], v[230:233], v[76:79]
	v_mfma_f32_16x16x32_f16 v[72:75], v[218:221], v[242:245], v[72:75]
	v_mfma_f32_16x16x32_f16 v[68:71], v[218:221], v[230:233], v[68:71]
	v_lshl_add_u64 v[250:251], v[222:223], 0, s[10:11]
	s_mov_b32 m0, s100
	s_barrier
	ds_read_b128 v[190:193], v156 offset:16384
	ds_read_b128 v[194:197], v156 offset:17408
	ds_read_b128 v[198:201], v154 offset:16384
	ds_read_b128 v[202:205], v154 offset:17408
	ds_read_b128 v[206:209], v153 offset:16384
	ds_read_b128 v[210:213], v153 offset:17408
	ds_read_b128 v[214:217], v152 offset:16384
	ds_read_b128 v[218:221], v152 offset:17408
	global_load_lds_dwordx4 v[250:251], off
	s_or_b32 m0, s100, 0x2000
	v_lshl_add_u64 v[250:251], v[226:227], 0, s[10:11]
	global_load_lds_dwordx4 v[250:251], off
	s_barrier
	s_waitcnt lgkmcnt(0)
	v_mfma_f32_16x16x32_f16 v[64:67], v[190:193], v[174:177], 0
	v_mfma_f32_16x16x32_f16 v[60:63], v[190:193], v[182:185], 0
	v_mfma_f32_16x16x32_f16 v[56:59], v[198:201], v[174:177], 0
	v_mfma_f32_16x16x32_f16 v[52:55], v[198:201], v[182:185], 0
	v_mfma_f32_16x16x32_f16 v[48:51], v[206:209], v[174:177], 0
	v_mfma_f32_16x16x32_f16 v[44:47], v[206:209], v[182:185], 0
	v_mfma_f32_16x16x32_f16 v[40:43], v[214:217], v[174:177], 0
	v_mfma_f32_16x16x32_f16 v[36:39], v[214:217], v[182:185], 0
	v_mfma_f32_16x16x32_f16 v[64:67], v[194:197], v[178:181], v[64:67]
	v_mfma_f32_16x16x32_f16 v[60:63], v[194:197], v[186:189], v[60:63]
	v_mfma_f32_16x16x32_f16 v[56:59], v[202:205], v[178:181], v[56:59]
	v_mfma_f32_16x16x32_f16 v[52:55], v[202:205], v[186:189], v[52:55]
	v_mfma_f32_16x16x32_f16 v[48:51], v[210:213], v[178:181], v[48:51]
	v_mfma_f32_16x16x32_f16 v[44:47], v[210:213], v[186:189], v[44:47]
	v_mfma_f32_16x16x32_f16 v[40:43], v[218:221], v[178:181], v[40:43]
	v_mfma_f32_16x16x32_f16 v[36:39], v[218:221], v[186:189], v[36:39]
	s_barrier
	s_or_b32 m0, s100, 0x14000
	v_lshl_add_u64 v[174:175], v[228:229], 0, s[62:63]
	global_load_lds_dwordx4 v[174:175], off
	s_or_b32 m0, s100, 0x16000
	v_lshl_add_u64 v[174:175], v[236:237], 0, s[62:63]
	global_load_lds_dwordx4 v[174:175], off
	s_waitcnt vmcnt(6)
	s_barrier
	v_mfma_f32_16x16x32_f16 v[32:35], v[190:193], v[238:241], 0
	v_mfma_f32_16x16x32_f16 v[28:31], v[190:193], v[246:249], 0
	v_mfma_f32_16x16x32_f16 v[24:27], v[198:201], v[238:241], 0
	v_mfma_f32_16x16x32_f16 v[20:23], v[198:201], v[246:249], 0
	v_mfma_f32_16x16x32_f16 v[16:19], v[206:209], v[238:241], 0
	v_mfma_f32_16x16x32_f16 v[12:15], v[206:209], v[246:249], 0
	v_mfma_f32_16x16x32_f16 v[8:11], v[214:217], v[238:241], 0
	v_mfma_f32_16x16x32_f16 v[4:7], v[214:217], v[246:249], 0
	v_mfma_f32_16x16x32_f16 v[32:35], v[194:197], v[242:245], v[32:35]
	v_mfma_f32_16x16x32_f16 v[28:31], v[194:197], v[230:233], v[28:31]
	v_mfma_f32_16x16x32_f16 v[24:27], v[202:205], v[242:245], v[24:27]
	v_mfma_f32_16x16x32_f16 v[20:23], v[202:205], v[230:233], v[20:23]
	v_mfma_f32_16x16x32_f16 v[16:19], v[210:213], v[242:245], v[16:19]
	v_mfma_f32_16x16x32_f16 v[12:15], v[210:213], v[230:233], v[12:15]
	v_mfma_f32_16x16x32_f16 v[8:11], v[218:221], v[242:245], v[8:11]
	v_mfma_f32_16x16x32_f16 v[4:7], v[218:221], v[230:233], v[4:7]
	s_barrier
	ds_read_b128 v[174:177], v159
	ds_read_b128 v[178:181], v159 offset:1024
	ds_read_b128 v[182:185], v159 offset:2048
	ds_read_b128 v[186:189], v159 offset:3072
	v_lshl_add_u64 v[230:231], v[222:223], 0, s[18:19]
	s_or_b32 m0, s100, 0x4000
	ds_read_b128 v[190:193], v156 offset:32768
	ds_read_b128 v[194:197], v156 offset:33792
	ds_read_b128 v[198:201], v154 offset:32768
	ds_read_b128 v[202:205], v154 offset:33792
	ds_read_b128 v[206:209], v153 offset:32768
	ds_read_b128 v[210:213], v153 offset:33792
	ds_read_b128 v[214:217], v152 offset:32768
	ds_read_b128 v[218:221], v152 offset:33792
	global_load_lds_dwordx4 v[230:231], off
	s_or_b32 m0, s100, 0x6000
	v_lshl_add_u64 v[230:231], v[226:227], 0, s[18:19]
	global_load_lds_dwordx4 v[230:231], off
	s_waitcnt lgkmcnt(8)
	s_barrier
; #define LDA8(dst, b, h) _Pragma("unroll") for (int m = 0; m < 4; ++m) _Pragma("unroll") for (int k = 0; k < 2; ++k) \
;     dst[m][k] = *(const bf16x8*)((const char*)SA8(b, h) + lds_byte8(wr * 64 + m * 16 + fr, k * 32 + fq * 8))
; #define LDB8(dst, b, h) _Pragma("unroll") for (int n = 0; n < 2; ++n) _Pragma("unroll") for (int k = 0; k < 2; ++k) \
;     dst[n][k] = *(const bf16x8*)((const char*)SB8(b, h) + lds_byte8(wc * 32 + n * 16 + fr, k * 32 + fq * 8))
; #define WAIT_V8(n) asm volatile("s_waitcnt vmcnt(" #n ")" ::: "memory")
; #define WAIT_L8(n) asm volatile("s_waitcnt lgkmcnt(" #n ")" ::: "memory")
; #define BAR8 __builtin_amdgcn_s_barrier()
; #define SCHED8 __builtin_amdgcn_sched_barrier(0)
;     ...
;     WAIT_V8(6); BAR8; MMA8(1, 1, At, B1); BAR8;
;     LDB8(B0, 1, 0); SCHED8; LDA8(At, 1, 0); STAGE8(SA8(0, 1), A, lda, brow + 128, tt + 2);
;     WAIT_L8(8); BAR8; WAIT_L8(0); MMA8(0, 0, At, B0); BAR8; SCHED8;
;     LDB8(B1, 1, 1); STAGE8(SB8(1, 0), Bt, K, bcol, tt + 3);
;     BAR8; WAIT_L8(0); MMA8(0, 1, At, B1); BAR8;
;     LDA8(At, 1, 1); STAGE8(SA8(1, 0), A, lda, brow, tt + 3);
;     BAR8; WAIT_L8(0); MMA8(1, 0, At, B0); BAR8; SCHED8;
;     STAGE8(SB8(1, 1), Bt, K, bcol + 128, tt + 3);
;     WAIT_V8(6); BAR8; MMA8(1, 1, At, B1); BAR8;
;   }
	s_waitcnt lgkmcnt(0)
	v_mfma_f32_16x16x32_f16 v[128:131], v[190:193], v[174:177], v[128:131]
	v_mfma_f32_16x16x32_f16 v[124:127], v[190:193], v[182:185], v[124:127]
	v_mfma_f32_16x16x32_f16 v[120:123], v[198:201], v[174:177], v[120:123]
	v_mfma_f32_16x16x32_f16 v[116:119], v[198:201], v[182:185], v[116:119]
	v_mfma_f32_16x16x32_f16 v[112:115], v[206:209], v[174:177], v[112:115]
	v_mfma_f32_16x16x32_f16 v[108:111], v[206:209], v[182:185], v[108:111]
	v_mfma_f32_16x16x32_f16 v[104:107], v[214:217], v[174:177], v[104:107]
	v_mfma_f32_16x16x32_f16 v[100:103], v[214:217], v[182:185], v[100:103]
	v_mfma_f32_16x16x32_f16 v[128:131], v[194:197], v[178:181], v[128:131]
	v_mfma_f32_16x16x32_f16 v[124:127], v[194:197], v[186:189], v[124:127]
	v_mfma_f32_16x16x32_f16 v[120:123], v[202:205], v[178:181], v[120:123]
	v_mfma_f32_16x16x32_f16 v[116:119], v[202:205], v[186:189], v[116:119]
	v_mfma_f32_16x16x32_f16 v[112:115], v[210:213], v[178:181], v[112:115]
	v_mfma_f32_16x16x32_f16 v[108:111], v[210:213], v[186:189], v[108:111]
	v_mfma_f32_16x16x32_f16 v[104:107], v[218:221], v[178:181], v[104:107]
	v_mfma_f32_16x16x32_f16 v[100:103], v[218:221], v[186:189], v[100:103]
	s_barrier
	v_lshl_add_u64 v[250:251], v[228:229], 0, s[64:65]
	s_or_b32 m0, s100, 0x18000
	ds_read_b128 v[230:233], v158
	ds_read_b128 v[238:241], v158 offset:1024
	ds_read_b128 v[242:245], v158 offset:2048
	ds_read_b128 v[246:249], v158 offset:3072
	global_load_lds_dwordx4 v[250:251], off
	s_or_b32 m0, s100, 0x1a000
	v_lshl_add_u64 v[250:251], v[236:237], 0, s[64:65]
	global_load_lds_dwordx4 v[250:251], off
	s_barrier
	s_waitcnt lgkmcnt(0)
	v_mfma_f32_16x16x32_f16 v[96:99], v[190:193], v[230:233], v[96:99]
	v_mfma_f32_16x16x32_f16 v[92:95], v[190:193], v[242:245], v[92:95]
	v_mfma_f32_16x16x32_f16 v[88:91], v[198:201], v[230:233], v[88:91]
	v_mfma_f32_16x16x32_f16 v[84:87], v[198:201], v[242:245], v[84:87]
	v_mfma_f32_16x16x32_f16 v[80:83], v[206:209], v[230:233], v[80:83]
	v_mfma_f32_16x16x32_f16 v[76:79], v[206:209], v[242:245], v[76:79]
	v_mfma_f32_16x16x32_f16 v[72:75], v[214:217], v[230:233], v[72:75]
	v_mfma_f32_16x16x32_f16 v[68:71], v[214:217], v[242:245], v[68:71]
	v_mfma_f32_16x16x32_f16 v[96:99], v[194:197], v[238:241], v[96:99]
	v_mfma_f32_16x16x32_f16 v[92:95], v[194:197], v[246:249], v[92:95]
	v_mfma_f32_16x16x32_f16 v[88:91], v[202:205], v[238:241], v[88:91]
	v_mfma_f32_16x16x32_f16 v[84:87], v[202:205], v[246:249], v[84:87]
	v_mfma_f32_16x16x32_f16 v[80:83], v[210:213], v[238:241], v[80:83]
	v_mfma_f32_16x16x32_f16 v[76:79], v[210:213], v[246:249], v[76:79]
	v_mfma_f32_16x16x32_f16 v[72:75], v[218:221], v[238:241], v[72:75]
	v_mfma_f32_16x16x32_f16 v[68:71], v[218:221], v[246:249], v[68:71]
	v_lshl_add_u64 v[222:223], v[222:223], 0, s[22:23]
	s_or_b32 m0, s100, 0x8000
	s_barrier
	ds_read_b128 v[190:193], v156 offset:49152
	ds_read_b128 v[194:197], v156 offset:50176
	ds_read_b128 v[198:201], v154 offset:49152
	ds_read_b128 v[202:205], v154 offset:50176
	ds_read_b128 v[206:209], v153 offset:49152
	ds_read_b128 v[210:213], v153 offset:50176
	ds_read_b128 v[214:217], v152 offset:49152
	ds_read_b128 v[218:221], v152 offset:50176
	global_load_lds_dwordx4 v[222:223], off
	s_or_b32 m0, s100, 0xa000
	v_lshl_add_u64 v[222:223], v[226:227], 0, s[22:23]
	global_load_lds_dwordx4 v[222:223], off
	s_barrier
	s_waitcnt lgkmcnt(0)
	v_mfma_f32_16x16x32_f16 v[64:67], v[190:193], v[174:177], v[64:67]
	v_mfma_f32_16x16x32_f16 v[60:63], v[190:193], v[182:185], v[60:63]
	v_mfma_f32_16x16x32_f16 v[56:59], v[198:201], v[174:177], v[56:59]
	v_mfma_f32_16x16x32_f16 v[52:55], v[198:201], v[182:185], v[52:55]
	v_mfma_f32_16x16x32_f16 v[48:51], v[206:209], v[174:177], v[48:51]
	v_mfma_f32_16x16x32_f16 v[44:47], v[206:209], v[182:185], v[44:47]
	v_mfma_f32_16x16x32_f16 v[40:43], v[214:217], v[174:177], v[40:43]
	v_mfma_f32_16x16x32_f16 v[36:39], v[214:217], v[182:185], v[36:39]
	v_mfma_f32_16x16x32_f16 v[64:67], v[194:197], v[178:181], v[64:67]
	v_mfma_f32_16x16x32_f16 v[60:63], v[194:197], v[186:189], v[60:63]
	v_mfma_f32_16x16x32_f16 v[56:59], v[202:205], v[178:181], v[56:59]
	v_mfma_f32_16x16x32_f16 v[52:55], v[202:205], v[186:189], v[52:55]
	v_mfma_f32_16x16x32_f16 v[48:51], v[210:213], v[178:181], v[48:51]
	v_mfma_f32_16x16x32_f16 v[44:47], v[210:213], v[186:189], v[44:47]
	v_mfma_f32_16x16x32_f16 v[40:43], v[218:221], v[178:181], v[40:43]
	v_mfma_f32_16x16x32_f16 v[36:39], v[218:221], v[186:189], v[36:39]
	s_barrier
	s_or_b32 m0, s100, 0x1c000
	v_lshl_add_u64 v[174:175], v[228:229], 0, s[66:67]
	global_load_lds_dwordx4 v[174:175], off
	s_or_b32 m0, s100, 0x1e000
	v_lshl_add_u64 v[174:175], v[236:237], 0, s[66:67]
	global_load_lds_dwordx4 v[174:175], off
	s_waitcnt vmcnt(6)
	s_barrier
	v_mfma_f32_16x16x32_f16 v[32:35], v[190:193], v[230:233], v[32:35]
	v_mfma_f32_16x16x32_f16 v[28:31], v[190:193], v[242:245], v[28:31]
	v_mfma_f32_16x16x32_f16 v[24:27], v[198:201], v[230:233], v[24:27]
	v_mfma_f32_16x16x32_f16 v[20:23], v[198:201], v[242:245], v[20:23]
	v_mfma_f32_16x16x32_f16 v[16:19], v[206:209], v[230:233], v[16:19]
	v_mfma_f32_16x16x32_f16 v[12:15], v[206:209], v[242:245], v[12:15]
	v_mfma_f32_16x16x32_f16 v[8:11], v[214:217], v[230:233], v[8:11]
	v_mfma_f32_16x16x32_f16 v[4:7], v[214:217], v[242:245], v[4:7]
	v_mfma_f32_16x16x32_f16 v[32:35], v[194:197], v[238:241], v[32:35]
	v_mfma_f32_16x16x32_f16 v[28:31], v[194:197], v[246:249], v[28:31]
	v_mfma_f32_16x16x32_f16 v[24:27], v[202:205], v[238:241], v[24:27]
	v_mfma_f32_16x16x32_f16 v[20:23], v[202:205], v[246:249], v[20:23]
	v_mfma_f32_16x16x32_f16 v[16:19], v[210:213], v[238:241], v[16:19]
	v_mfma_f32_16x16x32_f16 v[12:15], v[210:213], v[246:249], v[12:15]
	v_mfma_f32_16x16x32_f16 v[8:11], v[218:221], v[238:241], v[8:11]
	v_mfma_f32_16x16x32_f16 v[4:7], v[218:221], v[246:249], v[4:7]
	s_add_i32 s14, s14, 2
	s_add_u32 s12, s12, 0x100
	s_addc_u32 s13, s13, 0
	s_cmp_lt_u32 s14, 12
	s_cbranch_scc0 .Lpk_exitb_0
	.p2align	6

; #define LDA8(dst, b, h) _Pragma("unroll") for (int m = 0; m < 4; ++m) _Pragma("unroll") for (int k = 0; k < 2; ++k) \
;     dst[m][k] = *(const bf16x8*)((const char*)SA8(b, h) + lds_byte8(wr * 64 + m * 16 + fr, k * 32 + fq * 8))
; #define LDB8(dst, b, h) _Pragma("unroll") for (int n = 0; n < 2; ++n) _Pragma("unroll") for (int k = 0; k < 2; ++k) \
;     dst[n][k] = *(const bf16x8*)((const char*)SB8(b, h) + lds_byte8(wc * 32 + n * 16 + fr, k * 32 + fq * 8))
; #define WAIT_V8(n) asm volatile("s_waitcnt vmcnt(" #n ")" ::: "memory")
; #define WAIT_L8(n) asm volatile("s_waitcnt lgkmcnt(" #n ")" ::: "memory")
; #define BAR8 __builtin_amdgcn_s_barrier()
; #define SCHED8 __builtin_amdgcn_sched_barrier(0)
;     ...
;   if (wr == 1) BAR8;
;   WAIT_V8(4); BAR8;
;   STAGE8(SB8(1, 0), Bt, K, bcol, 1); STAGE8(SA8(1, 0), A, lda, brow, 1); STAGE8(SB8(1, 1), Bt, K, bcol + 128, 1);
;   WAIT_V8(6); BAR8;
;   for (int tt = 0; tt < nt - 2; tt += 2) {
;     LDB8(B0, 0, 0); SCHED8; LDA8(At, 0, 0); STAGE8(SA8(1, 1), A, lda, brow + 128, tt + 1);
;     WAIT_L8(8); BAR8; WAIT_L8(0); MMA8(0, 0, At, B0); BAR8; SCHED8;
.LBB0_241:
	s_or_b64 exec, exec, s[20:21]
	s_mov_b64 s[20:21], 0x80
	v_lshl_add_u64 v[10:11], v[10:11], 0, s[20:21]
	s_or_b32 m0, s100, 0x18000
	s_waitcnt vmcnt(4)
	s_barrier
	global_load_lds_dwordx4 v[10:11], off
	v_lshl_add_u64 v[10:11], v[12:13], 0, s[20:21]
	s_or_b32 m0, s100, 0x1a000
	s_nop 0
	global_load_lds_dwordx4 v[10:11], off
	v_lshl_add_u64 v[10:11], v[14:15], 0, s[20:21]
	s_or_b32 m0, s100, 0x8000
	s_nop 0
	global_load_lds_dwordx4 v[10:11], off
	v_lshl_add_u64 v[10:11], v[16:17], 0, s[20:21]
	s_or_b32 m0, s100, 0xa000
	s_nop 0
	global_load_lds_dwordx4 v[10:11], off
	s_or_b32 m0, s100, 0x1c000
	v_lshl_add_u64 v[10:11], v[18:19], 0, s[20:21]
	global_load_lds_dwordx4 v[10:11], off
	v_lshl_add_u64 v[10:11], v[20:21], 0, s[20:21]
	s_or_b32 m0, s100, 0x1e000
	v_and_b32_e32 v147, 15, v3
	global_load_lds_dwordx4 v[10:11], off
	v_bfe_u32 v148, v3, 4, 2
	v_lshlrev_b32_e32 v10, 4, v148
	v_lshlrev_b32_e32 v11, 6, v147
	v_lshlrev_b32_e32 v14, 2, v3
	v_or_b32_e32 v13, v10, v11
	v_and_b32_e32 v14, 32, v14
	s_mov_b32 s1, 0x10000
	v_bitop3_b32 v16, v13, s1, v14 bitop3:0xde
	s_mov_b32 s1, 0x14000
	v_bitop3_b32 v15, v10, v14, v11 bitop3:0x36
	v_bitop3_b32 v17, v13, s1, v14 bitop3:0xde
	s_mov_b32 s1, 0x18000
	v_lshlrev_b32_e32 v11, 6, v3
	v_bitop3_b32 v18, v13, s1, v14 bitop3:0xde
	s_mov_b32 s1, 0x1c000
	v_and_b32_e32 v11, 0x3c0, v11
	v_bitop3_b32 v13, v13, s1, v14 bitop3:0xde
	v_bitop3_b32 v14, v11, v14, v10 bitop3:0x36
	v_lshl_add_u64 v[10:11], s[30:31], 0, v[136:137]
	v_lshl_add_u64 v[10:11], v[10:11], 0, v[8:9]
	v_lshl_add_u64 v[138:139], s[14:15], 0, v[10:11]
	v_lshl_add_u64 v[10:11], s[30:31], 0, v[132:133]
	v_lshl_add_u64 v[10:11], v[10:11], 0, v[6:7]
	v_lshl_add_u64 v[140:141], s[14:15], 0, v[10:11]
	v_lshl_add_u64 v[10:11], s[56:57], 0, v[132:133]
	v_lshl_add_u64 v[6:7], v[10:11], 0, v[6:7]
	v_bfe_u32 v146, v3, 6, 2
	s_waitcnt vmcnt(6)
	v_lshlrev_b32_e32 v149, 6, v5
	v_lshlrev_b32_e32 v5, 13, v5
	v_lshl_add_u64 v[142:143], s[46:47], 0, v[6:7]
	v_lshl_add_u64 v[6:7], s[56:57], 0, v[136:137]
	v_lshlrev_b32_e32 v12, 12, v146
	v_or_b32_e32 v19, 0x800, v5
	v_or_b32_e32 v20, 0x1000, v5
	v_or_b32_e32 v21, 0x1800, v5
	v_lshl_add_u64 v[6:7], v[6:7], 0, v[8:9]
	v_lshl_add_u64 v[144:145], s[46:47], 0, v[6:7]
	s_mov_b32 s1, -2
	s_mov_b64 s[14:15], 0
	v_add_u32_e32 v171, v16, v12
	v_add_u32_e32 v156, v15, v5
	v_add_u32_e32 v154, v14, v19
	v_add_u32_e32 v153, v14, v20
	v_add_u32_e32 v152, v14, v21
	v_add_u32_e32 v168, v17, v12
	v_add_u32_e32 v159, v18, v12
	v_add_u32_e32 v157, v13, v12
	s_mov_b64 s[30:31], 0xc000100
	s_mov_b64 s[56:57], 0xc040100
	s_mov_b64 s[58:59], 0xc000180
	s_mov_b64 s[60:61], 0xc040180
	s_barrier
	ds_read_b128 v[174:177], v171
	ds_read_b128 v[178:181], v171 offset:1024
	ds_read_b128 v[182:185], v171 offset:2048
	ds_read_b128 v[186:189], v171 offset:3072
	v_lshl_add_u64 v[222:223], v[140:141], 0, s[14:15]
	v_lshl_add_u64 v[226:227], v[222:223], 0, s[34:35]
	s_or_b32 m0, s100, 0xc000
	ds_read_b128 v[190:193], v156
	ds_read_b128 v[194:197], v156 offset:1024
	ds_read_b128 v[198:201], v154
	ds_read_b128 v[202:205], v154 offset:1024
	ds_read_b128 v[206:209], v153
	ds_read_b128 v[210:213], v153 offset:1024
	ds_read_b128 v[214:217], v152
	ds_read_b128 v[218:221], v152 offset:1024
	global_load_lds_dwordx4 v[226:227], off
	v_lshl_add_u64 v[226:227], v[138:139], 0, s[14:15]
	s_or_b32 m0, s100, 0xe000
	v_lshl_add_u64 v[228:229], v[226:227], 0, s[34:35]
	global_load_lds_dwordx4 v[228:229], off
	s_waitcnt lgkmcnt(8)
	s_barrier
	s_waitcnt lgkmcnt(0)
	v_mfma_f32_16x16x32_f16 v[128:131], v[190:193], v[174:177], 0
	v_mfma_f32_16x16x32_f16 v[124:127], v[190:193], v[182:185], 0
	v_mfma_f32_16x16x32_f16 v[120:123], v[198:201], v[174:177], 0
	v_mfma_f32_16x16x32_f16 v[116:119], v[198:201], v[182:185], 0
	v_mfma_f32_16x16x32_f16 v[112:115], v[206:209], v[174:177], 0
	v_mfma_f32_16x16x32_f16 v[108:111], v[206:209], v[182:185], 0
	v_mfma_f32_16x16x32_f16 v[104:107], v[214:217], v[174:177], 0
	v_mfma_f32_16x16x32_f16 v[100:103], v[214:217], v[182:185], 0
	v_mfma_f32_16x16x32_f16 v[128:131], v[194:197], v[178:181], v[128:131]
	v_mfma_f32_16x16x32_f16 v[124:127], v[194:197], v[186:189], v[124:127]
	v_mfma_f32_16x16x32_f16 v[120:123], v[202:205], v[178:181], v[120:123]
	v_mfma_f32_16x16x32_f16 v[116:119], v[202:205], v[186:189], v[116:119]
	v_mfma_f32_16x16x32_f16 v[112:115], v[210:213], v[178:181], v[112:115]
	v_mfma_f32_16x16x32_f16 v[108:111], v[210:213], v[186:189], v[108:111]
	v_mfma_f32_16x16x32_f16 v[104:107], v[218:221], v[178:181], v[104:107]
	v_mfma_f32_16x16x32_f16 v[100:103], v[218:221], v[186:189], v[100:103]
	s_barrier
	v_lshl_add_u64 v[228:229], v[142:143], 0, s[14:15]
	v_lshl_add_u64 v[236:237], v[228:229], 0, s[30:31]
	s_or_b32 m0, s100, 0x10000
	ds_read_b128 v[230:233], v168
	ds_read_b128 v[238:241], v168 offset:1024
	ds_read_b128 v[242:245], v168 offset:2048
	ds_read_b128 v[246:249], v168 offset:3072
	global_load_lds_dwordx4 v[236:237], off
	v_lshl_add_u64 v[236:237], v[144:145], 0, s[14:15]
	s_or_b32 m0, s100, 0x12000
	v_lshl_add_u64 v[250:251], v[236:237], 0, s[30:31]
	global_load_lds_dwordx4 v[250:251], off
	s_barrier
; #define LDA8(dst, b, h) _Pragma("unroll") for (int m = 0; m < 4; ++m) _Pragma("unroll") for (int k = 0; k < 2; ++k) \
;     dst[m][k] = *(const bf16x8*)((const char*)SA8(b, h) + lds_byte8(wr * 64 + m * 16 + fr, k * 32 + fq * 8))
; #define LDB8(dst, b, h) _Pragma("unroll") for (int n = 0; n < 2; ++n) _Pragma("unroll") for (int k = 0; k < 2; ++k) \
;     dst[n][k] = *(const bf16x8*)((const char*)SB8(b, h) + lds_byte8(wc * 32 + n * 16 + fr, k * 32 + fq * 8))
; #define WAIT_V8(n) asm volatile("s_waitcnt vmcnt(" #n ")" ::: "memory")
; #define WAIT_L8(n) asm volatile("s_waitcnt lgkmcnt(" #n ")" ::: "memory")
; #define BAR8 __builtin_amdgcn_s_barrier()
; #define SCHED8 __builtin_amdgcn_sched_barrier(0)
;     ...
;     WAIT_L8(8); BAR8; WAIT_L8(0); MMA8(0, 0, At, B0); BAR8; SCHED8;
;     LDB8(B1, 0, 1); STAGE8(SB8(0, 0), Bt, K, bcol, tt + 2);
;     BAR8; WAIT_L8(0); MMA8(0, 1, At, B1); BAR8;
;     LDA8(At, 0, 1); STAGE8(SA8(0, 0), A, lda, brow, tt + 2);
;     BAR8; WAIT_L8(0); MMA8(1, 0, At, B0); BAR8; SCHED8;
;     STAGE8(SB8(0, 1), Bt, K, bcol + 128, tt + 2);
;     WAIT_V8(6); BAR8; MMA8(1, 1, At, B1); BAR8;
	s_waitcnt lgkmcnt(0)
	v_mfma_f32_16x16x32_f16 v[96:99], v[190:193], v[230:233], 0
	v_mfma_f32_16x16x32_f16 v[92:95], v[190:193], v[242:245], 0
	v_mfma_f32_16x16x32_f16 v[88:91], v[198:201], v[230:233], 0
	v_mfma_f32_16x16x32_f16 v[84:87], v[198:201], v[242:245], 0
	v_mfma_f32_16x16x32_f16 v[80:83], v[206:209], v[230:233], 0
	v_mfma_f32_16x16x32_f16 v[76:79], v[206:209], v[242:245], 0
	v_mfma_f32_16x16x32_f16 v[72:75], v[214:217], v[230:233], 0
	v_mfma_f32_16x16x32_f16 v[68:71], v[214:217], v[242:245], 0
	v_mfma_f32_16x16x32_f16 v[96:99], v[194:197], v[238:241], v[96:99]
	v_mfma_f32_16x16x32_f16 v[92:95], v[194:197], v[246:249], v[92:95]
	v_mfma_f32_16x16x32_f16 v[88:91], v[202:205], v[238:241], v[88:91]
	v_mfma_f32_16x16x32_f16 v[84:87], v[202:205], v[246:249], v[84:87]
	v_mfma_f32_16x16x32_f16 v[80:83], v[210:213], v[238:241], v[80:83]
	v_mfma_f32_16x16x32_f16 v[76:79], v[210:213], v[246:249], v[76:79]
	v_mfma_f32_16x16x32_f16 v[72:75], v[218:221], v[238:241], v[72:75]
	v_mfma_f32_16x16x32_f16 v[68:71], v[218:221], v[246:249], v[68:71]
	v_lshl_add_u64 v[250:251], v[222:223], 0, s[10:11]
	s_mov_b32 m0, s100
	s_barrier
	ds_read_b128 v[190:193], v156 offset:16384
	ds_read_b128 v[194:197], v156 offset:17408
	ds_read_b128 v[198:201], v154 offset:16384
	ds_read_b128 v[202:205], v154 offset:17408
	ds_read_b128 v[206:209], v153 offset:16384
	ds_read_b128 v[210:213], v153 offset:17408
	ds_read_b128 v[214:217], v152 offset:16384
	ds_read_b128 v[218:221], v152 offset:17408
	global_load_lds_dwordx4 v[250:251], off
	s_or_b32 m0, s100, 0x2000
	v_lshl_add_u64 v[250:251], v[226:227], 0, s[10:11]
	global_load_lds_dwordx4 v[250:251], off
	s_barrier
	s_waitcnt lgkmcnt(0)
	v_mfma_f32_16x16x32_f16 v[64:67], v[190:193], v[174:177], 0
	v_mfma_f32_16x16x32_f16 v[60:63], v[190:193], v[182:185], 0
	v_mfma_f32_16x16x32_f16 v[56:59], v[198:201], v[174:177], 0
	v_mfma_f32_16x16x32_f16 v[52:55], v[198:201], v[182:185], 0
	v_mfma_f32_16x16x32_f16 v[48:51], v[206:209], v[174:177], 0
	v_mfma_f32_16x16x32_f16 v[44:47], v[206:209], v[182:185], 0
	v_mfma_f32_16x16x32_f16 v[40:43], v[214:217], v[174:177], 0
	v_mfma_f32_16x16x32_f16 v[36:39], v[214:217], v[182:185], 0
	v_mfma_f32_16x16x32_f16 v[64:67], v[194:197], v[178:181], v[64:67]
	v_mfma_f32_16x16x32_f16 v[60:63], v[194:197], v[186:189], v[60:63]
	v_mfma_f32_16x16x32_f16 v[56:59], v[202:205], v[178:181], v[56:59]
	v_mfma_f32_16x16x32_f16 v[52:55], v[202:205], v[186:189], v[52:55]
	v_mfma_f32_16x16x32_f16 v[48:51], v[210:213], v[178:181], v[48:51]
	v_mfma_f32_16x16x32_f16 v[44:47], v[210:213], v[186:189], v[44:47]
	v_mfma_f32_16x16x32_f16 v[40:43], v[218:221], v[178:181], v[40:43]
	v_mfma_f32_16x16x32_f16 v[36:39], v[218:221], v[186:189], v[36:39]
	s_barrier
	s_or_b32 m0, s100, 0x14000
	v_lshl_add_u64 v[174:175], v[228:229], 0, s[56:57]
	global_load_lds_dwordx4 v[174:175], off
	s_or_b32 m0, s100, 0x16000
	v_lshl_add_u64 v[174:175], v[236:237], 0, s[56:57]
	global_load_lds_dwordx4 v[174:175], off
	s_waitcnt vmcnt(6)
	s_barrier
	v_mfma_f32_16x16x32_f16 v[32:35], v[190:193], v[230:233], 0
	v_mfma_f32_16x16x32_f16 v[28:31], v[190:193], v[242:245], 0
	v_mfma_f32_16x16x32_f16 v[24:27], v[198:201], v[230:233], 0
	v_mfma_f32_16x16x32_f16 v[20:23], v[198:201], v[242:245], 0
	v_mfma_f32_16x16x32_f16 v[16:19], v[206:209], v[230:233], 0
	v_mfma_f32_16x16x32_f16 v[12:15], v[206:209], v[242:245], 0
	v_mfma_f32_16x16x32_f16 v[8:11], v[214:217], v[230:233], 0
	v_mfma_f32_16x16x32_f16 v[4:7], v[214:217], v[242:245], 0
	v_mfma_f32_16x16x32_f16 v[32:35], v[194:197], v[238:241], v[32:35]
	v_mfma_f32_16x16x32_f16 v[28:31], v[194:197], v[246:249], v[28:31]
	v_mfma_f32_16x16x32_f16 v[24:27], v[202:205], v[238:241], v[24:27]
	v_mfma_f32_16x16x32_f16 v[20:23], v[202:205], v[246:249], v[20:23]
	v_mfma_f32_16x16x32_f16 v[16:19], v[210:213], v[238:241], v[16:19]
	v_mfma_f32_16x16x32_f16 v[12:15], v[210:213], v[246:249], v[12:15]
	v_mfma_f32_16x16x32_f16 v[8:11], v[218:221], v[238:241], v[8:11]
	v_mfma_f32_16x16x32_f16 v[4:7], v[218:221], v[246:249], v[4:7]
	s_barrier
	ds_read_b128 v[174:177], v159
	ds_read_b128 v[178:181], v159 offset:1024
	ds_read_b128 v[182:185], v159 offset:2048
	ds_read_b128 v[186:189], v159 offset:3072
	v_lshl_add_u64 v[230:231], v[222:223], 0, s[18:19]
	s_or_b32 m0, s100, 0x4000
	ds_read_b128 v[190:193], v156 offset:32768
	ds_read_b128 v[194:197], v156 offset:33792
	ds_read_b128 v[198:201], v154 offset:32768
	ds_read_b128 v[202:205], v154 offset:33792
	ds_read_b128 v[206:209], v153 offset:32768
	ds_read_b128 v[210:213], v153 offset:33792
	ds_read_b128 v[214:217], v152 offset:32768
	ds_read_b128 v[218:221], v152 offset:33792
	global_load_lds_dwordx4 v[230:231], off
	s_or_b32 m0, s100, 0x6000
	v_lshl_add_u64 v[230:231], v[226:227], 0, s[18:19]
	global_load_lds_dwordx4 v[230:231], off
	s_waitcnt lgkmcnt(8)
	s_barrier
; #define LDA8(dst, b, h) _Pragma("unroll") for (int m = 0; m < 4; ++m) _Pragma("unroll") for (int k = 0; k < 2; ++k) \
;     dst[m][k] = *(const bf16x8*)((const char*)SA8(b, h) + lds_byte8(wr * 64 + m * 16 + fr, k * 32 + fq * 8))
; #define LDB8(dst, b, h) _Pragma("unroll") for (int n = 0; n < 2; ++n) _Pragma("unroll") for (int k = 0; k < 2; ++k) \
;     dst[n][k] = *(const bf16x8*)((const char*)SB8(b, h) + lds_byte8(wc * 32 + n * 16 + fr, k * 32 + fq * 8))
; #define WAIT_V8(n) asm volatile("s_waitcnt vmcnt(" #n ")" ::: "memory")
; #define WAIT_L8(n) asm volatile("s_waitcnt lgkmcnt(" #n ")" ::: "memory")
; #define BAR8 __builtin_amdgcn_s_barrier()
; #define SCHED8 __builtin_amdgcn_sched_barrier(0)
;     ...
;     WAIT_V8(6); BAR8; MMA8(1, 1, At, B1); BAR8;
;     LDB8(B0, 1, 0); SCHED8; LDA8(At, 1, 0); STAGE8(SA8(0, 1), A, lda, brow + 128, tt + 2);
;     WAIT_L8(8); BAR8; WAIT_L8(0); MMA8(0, 0, At, B0); BAR8; SCHED8;
;     LDB8(B1, 1, 1); STAGE8(SB8(1, 0), Bt, K, bcol, tt + 3);
;     BAR8; WAIT_L8(0); MMA8(0, 1, At, B1); BAR8;
;     LDA8(At, 1, 1); STAGE8(SA8(1, 0), A, lda, brow, tt + 3);
;     BAR8; WAIT_L8(0); MMA8(1, 0, At, B0); BAR8; SCHED8;
;     STAGE8(SB8(1, 1), Bt, K, bcol + 128, tt + 3);
;     WAIT_V8(6); BAR8; MMA8(1, 1, At, B1); BAR8;
;   }
	s_waitcnt lgkmcnt(0)
	v_mfma_f32_16x16x32_f16 v[128:131], v[190:193], v[174:177], v[128:131]
	v_mfma_f32_16x16x32_f16 v[124:127], v[190:193], v[182:185], v[124:127]
	v_mfma_f32_16x16x32_f16 v[120:123], v[198:201], v[174:177], v[120:123]
	v_mfma_f32_16x16x32_f16 v[116:119], v[198:201], v[182:185], v[116:119]
	v_mfma_f32_16x16x32_f16 v[112:115], v[206:209], v[174:177], v[112:115]
	v_mfma_f32_16x16x32_f16 v[108:111], v[206:209], v[182:185], v[108:111]
	v_mfma_f32_16x16x32_f16 v[104:107], v[214:217], v[174:177], v[104:107]
	v_mfma_f32_16x16x32_f16 v[100:103], v[214:217], v[182:185], v[100:103]
	v_mfma_f32_16x16x32_f16 v[128:131], v[194:197], v[178:181], v[128:131]
	v_mfma_f32_16x16x32_f16 v[124:127], v[194:197], v[186:189], v[124:127]
	v_mfma_f32_16x16x32_f16 v[120:123], v[202:205], v[178:181], v[120:123]
	v_mfma_f32_16x16x32_f16 v[116:119], v[202:205], v[186:189], v[116:119]
	v_mfma_f32_16x16x32_f16 v[112:115], v[210:213], v[178:181], v[112:115]
	v_mfma_f32_16x16x32_f16 v[108:111], v[210:213], v[186:189], v[108:111]
	v_mfma_f32_16x16x32_f16 v[104:107], v[218:221], v[178:181], v[104:107]
	v_mfma_f32_16x16x32_f16 v[100:103], v[218:221], v[186:189], v[100:103]
	s_barrier
	v_lshl_add_u64 v[250:251], v[228:229], 0, s[58:59]
	s_or_b32 m0, s100, 0x18000
	ds_read_b128 v[230:233], v157
	ds_read_b128 v[238:241], v157 offset:1024
	ds_read_b128 v[242:245], v157 offset:2048
	ds_read_b128 v[246:249], v157 offset:3072
	global_load_lds_dwordx4 v[250:251], off
	s_or_b32 m0, s100, 0x1a000
	v_lshl_add_u64 v[250:251], v[236:237], 0, s[58:59]
	global_load_lds_dwordx4 v[250:251], off
	s_barrier
	s_waitcnt lgkmcnt(0)
	v_mfma_f32_16x16x32_f16 v[96:99], v[190:193], v[230:233], v[96:99]
	v_mfma_f32_16x16x32_f16 v[92:95], v[190:193], v[242:245], v[92:95]
	v_mfma_f32_16x16x32_f16 v[88:91], v[198:201], v[230:233], v[88:91]
	v_mfma_f32_16x16x32_f16 v[84:87], v[198:201], v[242:245], v[84:87]
	v_mfma_f32_16x16x32_f16 v[80:83], v[206:209], v[230:233], v[80:83]
	v_mfma_f32_16x16x32_f16 v[76:79], v[206:209], v[242:245], v[76:79]
	v_mfma_f32_16x16x32_f16 v[72:75], v[214:217], v[230:233], v[72:75]
	v_mfma_f32_16x16x32_f16 v[68:71], v[214:217], v[242:245], v[68:71]
	v_mfma_f32_16x16x32_f16 v[96:99], v[194:197], v[238:241], v[96:99]
	v_mfma_f32_16x16x32_f16 v[92:95], v[194:197], v[246:249], v[92:95]
	v_mfma_f32_16x16x32_f16 v[88:91], v[202:205], v[238:241], v[88:91]
	v_mfma_f32_16x16x32_f16 v[84:87], v[202:205], v[246:249], v[84:87]
	v_mfma_f32_16x16x32_f16 v[80:83], v[210:213], v[238:241], v[80:83]
	v_mfma_f32_16x16x32_f16 v[76:79], v[210:213], v[246:249], v[76:79]
	v_mfma_f32_16x16x32_f16 v[72:75], v[218:221], v[238:241], v[72:75]
	v_mfma_f32_16x16x32_f16 v[68:71], v[218:221], v[246:249], v[68:71]
	v_lshl_add_u64 v[222:223], v[222:223], 0, s[22:23]
	s_or_b32 m0, s100, 0x8000
	s_barrier
	ds_read_b128 v[190:193], v156 offset:49152
	ds_read_b128 v[194:197], v156 offset:50176
	ds_read_b128 v[198:201], v154 offset:49152
	ds_read_b128 v[202:205], v154 offset:50176
	ds_read_b128 v[206:209], v153 offset:49152
	ds_read_b128 v[210:213], v153 offset:50176
	ds_read_b128 v[214:217], v152 offset:49152
	ds_read_b128 v[218:221], v152 offset:50176
	global_load_lds_dwordx4 v[222:223], off
	s_or_b32 m0, s100, 0xa000
	v_lshl_add_u64 v[222:223], v[226:227], 0, s[22:23]
	global_load_lds_dwordx4 v[222:223], off
	s_barrier
	s_waitcnt lgkmcnt(0)
	v_mfma_f32_16x16x32_f16 v[64:67], v[190:193], v[174:177], v[64:67]
	v_mfma_f32_16x16x32_f16 v[60:63], v[190:193], v[182:185], v[60:63]
	v_mfma_f32_16x16x32_f16 v[56:59], v[198:201], v[174:177], v[56:59]
	v_mfma_f32_16x16x32_f16 v[52:55], v[198:201], v[182:185], v[52:55]
	v_mfma_f32_16x16x32_f16 v[48:51], v[206:209], v[174:177], v[48:51]
	v_mfma_f32_16x16x32_f16 v[44:47], v[206:209], v[182:185], v[44:47]
	v_mfma_f32_16x16x32_f16 v[40:43], v[214:217], v[174:177], v[40:43]
	v_mfma_f32_16x16x32_f16 v[36:39], v[214:217], v[182:185], v[36:39]
	v_mfma_f32_16x16x32_f16 v[64:67], v[194:197], v[178:181], v[64:67]
	v_mfma_f32_16x16x32_f16 v[60:63], v[194:197], v[186:189], v[60:63]
	v_mfma_f32_16x16x32_f16 v[56:59], v[202:205], v[178:181], v[56:59]
	v_mfma_f32_16x16x32_f16 v[52:55], v[202:205], v[186:189], v[52:55]
	v_mfma_f32_16x16x32_f16 v[48:51], v[210:213], v[178:181], v[48:51]
	v_mfma_f32_16x16x32_f16 v[44:47], v[210:213], v[186:189], v[44:47]
	v_mfma_f32_16x16x32_f16 v[40:43], v[218:221], v[178:181], v[40:43]
	v_mfma_f32_16x16x32_f16 v[36:39], v[218:221], v[186:189], v[36:39]
	s_barrier
	s_or_b32 m0, s100, 0x1c000
	v_lshl_add_u64 v[174:175], v[228:229], 0, s[60:61]
	global_load_lds_dwordx4 v[174:175], off
	s_or_b32 m0, s100, 0x1e000
	v_lshl_add_u64 v[174:175], v[236:237], 0, s[60:61]
	global_load_lds_dwordx4 v[174:175], off
	s_waitcnt vmcnt(6)
	s_barrier
	v_mfma_f32_16x16x32_f16 v[32:35], v[190:193], v[230:233], v[32:35]
	v_mfma_f32_16x16x32_f16 v[28:31], v[190:193], v[242:245], v[28:31]
	v_mfma_f32_16x16x32_f16 v[24:27], v[198:201], v[230:233], v[24:27]
	v_mfma_f32_16x16x32_f16 v[20:23], v[198:201], v[242:245], v[20:23]
	v_mfma_f32_16x16x32_f16 v[16:19], v[206:209], v[230:233], v[16:19]
	v_mfma_f32_16x16x32_f16 v[12:15], v[206:209], v[242:245], v[12:15]
	v_mfma_f32_16x16x32_f16 v[8:11], v[214:217], v[230:233], v[8:11]
	v_mfma_f32_16x16x32_f16 v[4:7], v[214:217], v[242:245], v[4:7]
	v_mfma_f32_16x16x32_f16 v[32:35], v[194:197], v[238:241], v[32:35]
	v_mfma_f32_16x16x32_f16 v[28:31], v[194:197], v[246:249], v[28:31]
	v_mfma_f32_16x16x32_f16 v[24:27], v[202:205], v[238:241], v[24:27]
	v_mfma_f32_16x16x32_f16 v[20:23], v[202:205], v[246:249], v[20:23]
	v_mfma_f32_16x16x32_f16 v[16:19], v[210:213], v[238:241], v[16:19]
	v_mfma_f32_16x16x32_f16 v[12:15], v[210:213], v[246:249], v[12:15]
	v_mfma_f32_16x16x32_f16 v[8:11], v[218:221], v[238:241], v[8:11]
	v_mfma_f32_16x16x32_f16 v[4:7], v[218:221], v[246:249], v[4:7]
	s_add_i32 s1, s1, 2
	s_add_u32 s14, s14, 0x100
	s_addc_u32 s15, s15, 0
	s_cmp_lt_u32 s1, 12
	s_cbranch_scc0 .Lpk_exitb_1
	.p2align	6

; template <int DK, int DV, int MODE>
; DI void att_gload(const AttArgs& a, int tile, u32x4 (&kr)[(64 * (DK / 8) + NT - 1) / NT], u32x4 (&vr)[(64 * (DV / 8) + NT - 1) / NT]) {
;     ...
; #pragma unroll
;   for (int i = 0; i < NKL; ++i) {
;     const int id = min(t + NT * i, 64 * CK - 1);
;     const int row = id / CK, c = id % CK;
;     if constexpr (MODE == 3) {
;       const bf16_t* src = (c < 8) ? (a.k + (size_t)(kbase + row) * a.ldk + c * 8) : (a.k2 + (size_t)(kbase + row) * a.ldk2 + (c - 8) * 8);
;       kr[i] = *(const u32x4*)src;
;     } else {
;       kr[i] = *(const u32x4*)(a.k + (size_t)(kbase + row) * a.ldk + c * 8);
;     }
;   }
; #pragma unroll
;   for (int i = 0; i < NVL; ++i) {
;     const int id = t + NT * i;
;     const int row = id / CV, c = id % CV;
;     vr[i] = *(const u32x4*)(a.v + (size_t)(kbase + row) * a.ldv + c * 8);
;   }
; }
; template <int DK, int DV>
; DI void att_swrite(int buf, const u32x4 (&kr)[(64 * (DK / 8) + NT - 1) / NT], const u32x4 (&vr)[(64 * (DV / 8) + NT - 1) / NT]) {
;   constexpr int CK = DK / 8, CV = DV / 8;
;   constexpr int KST = DK * 2 + 16, VST = DV * 2 + 16;
;   constexpr int KBYTES = 64 * KST, VBYTES = 64 * VST, BUFB = KBYTES + VBYTES;
;   constexpr int NKL = (64 * CK + NT - 1) / NT, NVL = (64 * CV + NT - 1) / NT;
;   const int t = tid_opaque();
; #pragma unroll
;   for (int i = 0; i < NKL; ++i) {
;     const int id = t + NT * i;
;     const int row = id / CK, c = id % CK;
;     if (id < 64 * CK) *(u32x4*)(smem + buf * BUFB + row * KST + c * 16) = kr[i];
;   }
; #pragma unroll
;   for (int i = 0; i < NVL; ++i) {
;     const int id = t + NT * i;
;     const int row = id / CV, c = id % CV;
;     *(u32x4*)(smem + buf * BUFB + KBYTES + row * VST + c * 16) = vr[i];
;   }
; template <int DK, int DV, int MODE, int QB, bool PACK = false>
; DI void attn_item(const AttArgs& a, int q0, int t_lo, int t_hi) {
;     ...
;   f32x16 o[QB][NDB];
;   float m[QB], lsum[QB];
; #pragma unroll
;   for (int qb = 0; qb < QB; ++qb) {
;     m[qb] = -1e30f; lsum[qb] = 0.f;
; #pragma unroll
;     for (int d = 0; d < NDB; ++d)
; #pragma unroll
;       for (int i = 0; i < 16; ++i) o[qb][d][i] = 0.f;
;   }
;   u32x4 kr[NKL], vr[NVL];
;   att_gload<DK, DV, MODE>(a, t_lo, kr, vr);
;   att_swrite<DK, DV>(0, kr, vr);
;   if (t_lo + 1 < t_hi) att_gload<DK, DV, MODE>(a, t_lo + 1, kr, vr);
;   __syncthreads();
;   const float scale = a.scale;
.LBB0_765:
	s_or_b64 exec, exec, s[6:7]
	v_ashrrev_i32_e32 v1, 31, v0
	v_lshrrev_b32_e32 v1, 29, v1
	v_add_u32_e32 v1, v0, v1
	s_waitcnt vmcnt(2)
	v_lshrrev_b32_e32 v4, 3, v1
	v_and_b32_e32 v1, 0xffffff8, v1
	s_movk_i32 s6, 0x90
	v_sub_u32_e32 v0, v0, v1
	v_mul_lo_u32 v1, v4, s6
	v_lshl_add_u32 v0, v0, 4, v1
	s_waitcnt vmcnt(1)
	v_mov_b32_e32 v8, v224
	s_waitcnt vmcnt(0)
	ds_write_b128 v0, v[12:15] offset:13312
	s_mov_b32 s6, 0x2aaaaaab
	v_min_i32_e32 v0, 0x2ff, v8
	v_mul_hi_i32 v1, v0, s6
	v_lshrrev_b32_e32 v4, 31, v1
	v_ashrrev_i32_e32 v1, 1, v1
	v_add_u32_e32 v1, v1, v4
	v_mul_lo_u32 v4, v1, 12
	v_sub_u32_e32 v0, v0, v4
	v_add_u32_e32 v6, 64, v1
	v_cmp_lt_i32_e32 vcc, 7, v0
	v_ashrrev_i32_e32 v7, 31, v6
	v_lshlrev_b32_e32 v0, 3, v0
	s_and_saveexec_b64 s[6:7], vcc
	s_xor_b64 s[6:7], exec, s[6:7]
	v_lshlrev_b64 v[4:5], 12, v[6:7]
	v_lshl_add_u64 v[4:5], s[30:31], 0, v[4:5]
	v_mov_b32_e32 v1, v2
	v_lshl_add_u64 v[0:1], v[0:1], 1, v[4:5]
	s_mov_b64 s[8:9], 0x280
	v_lshl_add_u64 v[4:5], v[0:1], 0, s[8:9]
	s_andn2_saveexec_b64 s[6:7], s[6:7]
	v_lshlrev_b64 v[4:5], 11, v[6:7]
	v_lshl_add_u64 v[4:5], s[0:1], 0, v[4:5]
	v_ashrrev_i32_e32 v1, 31, v0
	v_lshl_add_u64 v[4:5], v[0:1], 1, v[4:5]
	s_or_b64 exec, exec, s[6:7]
	global_load_dwordx4 v[192:195], v[4:5], off
	v_mov_b32_e32 v226, v4
	v_mov_b32_e32 v227, v5
	v_mov_b32_e32 v236, 0x20000
	v_mov_b32_e32 v237, 0x40000
	v_cndmask_b32_e32 v236, v236, v237, vcc
	v_min_i32_e32 v0, 0xff, v8
	v_add_u32_e32 v0, 0x200, v0
	s_mov_b32 s6, 0x2aaaaaab
	v_mul_hi_i32 v1, v0, s6
	v_lshrrev_b32_e32 v4, 31, v1
	v_ashrrev_i32_e32 v1, 1, v1
	v_add_u32_e32 v1, v1, v4
	v_mul_lo_u32 v4, v1, 12
	v_sub_u32_e32 v0, v0, v4
	v_add_u32_e32 v6, 64, v1
	v_cmp_lt_i32_e32 vcc, 7, v0
	v_ashrrev_i32_e32 v7, 31, v6
	v_lshlrev_b32_e32 v4, 3, v0
	s_and_saveexec_b64 s[6:7], vcc
	s_xor_b64 s[6:7], exec, s[6:7]
	v_lshlrev_b64 v[0:1], 12, v[6:7]
	v_lshl_add_u64 v[0:1], s[30:31], 0, v[0:1]
	v_mov_b32_e32 v5, v2
	v_lshl_add_u64 v[0:1], v[4:5], 1, v[0:1]
	s_mov_b64 s[8:9], 0x280
	v_lshl_add_u64 v[0:1], v[0:1], 0, s[8:9]
	s_andn2_saveexec_b64 s[6:7], s[6:7]
	v_lshlrev_b64 v[0:1], 11, v[6:7]
	v_lshl_add_u64 v[0:1], s[0:1], 0, v[0:1]
	v_ashrrev_i32_e32 v5, 31, v4
	v_lshl_add_u64 v[0:1], v[4:5], 1, v[0:1]
	s_or_b64 exec, exec, s[6:7]
	global_load_dwordx4 v[196:199], v[0:1], off
	v_mov_b32_e32 v228, v0
	v_mov_b32_e32 v229, v1
	v_mov_b32_e32 v237, 0x20000
	v_mov_b32_e32 v0, 0x40000
	v_cndmask_b32_e32 v237, v237, v0, vcc
	v_ashrrev_i32_e32 v0, 31, v8
	v_lshrrev_b32_e32 v0, 29, v0
	v_add_u32_e32 v1, v8, v0
	v_ashrrev_i32_e32 v0, 3, v1
	v_and_b32_e32 v1, 0x1ffffff8, v1
	v_sub_u32_e32 v4, v8, v1
	v_ashrrev_i32_e32 v1, 31, v0
	v_lshlrev_b64 v[0:1], 11, v[0:1]
	v_lshlrev_b32_e32 v4, 3, v4
	v_ashrrev_i32_e32 v5, 31, v4
	v_lshl_add_u64 v[0:1], s[2:3], 0, v[0:1]
	v_lshl_add_u64 v[0:1], v[4:5], 1, v[0:1]
	s_mov_b32 s6, 0x20000
	v_add_co_u32_e32 v0, vcc, s6, v0
	v_lshlrev_b32_e32 v4, 2, v16
	s_nop 0
	v_addc_co_u32_e32 v1, vcc, 0, v1, vcc
	global_load_dwordx4 v[200:203], v[0:1], off
	v_bfe_u32 v0, v16, 2, 2
	v_and_b32_e32 v1, 16, v16
	v_lshl_or_b32 v0, v17, 2, v0
	v_and_or_b32 v1, v4, 12, v1
	v_mov_b32_e32 v14, v2
	v_mov_b32_e32 v15, v2
	v_lshlrev_b32_e32 v209, 3, v17
	v_lshlrev_b32_e32 v238, 1, v1
	v_mul_u32_u24_e32 v242, 0xd0, v3
	v_mul_u32_u24_e32 v239, 0x90, v0
	v_mov_b32_e32 v0, v2
	v_mov_b32_e32 v1, v2
	v_mov_b32_e32 v3, v2
	v_mov_b32_e32 v4, v2
	v_mov_b32_e32 v5, v2
	v_mov_b32_e32 v6, v2
	v_mov_b32_e32 v7, v2
	v_mov_b32_e32 v8, v2
	v_mov_b32_e32 v9, v2
	v_mov_b32_e32 v10, v2
	v_mov_b32_e32 v11, v2
	v_mov_b32_e32 v12, v2
	v_mov_b32_e32 v13, v2
	v_mov_b64_e32 v[30:31], v[14:15]
	v_mov_b64_e32 v[46:47], v[14:15]
	v_mov_b64_e32 v[62:63], v[14:15]
	v_mov_b64_e32 v[78:79], v[14:15]
	v_ashrrev_i32_e32 v207, 31, v206
	v_ashrrev_i32_e32 v205, 31, v204
	s_mov_b32 s14, 0
	v_mov_b32_e32 v240, 0
	v_mov_b32_e32 v211, 0xf149f2ca
	s_add_u32 s6, s2, 0x40000
	s_addc_u32 s7, s3, 0
	v_mov_b64_e32 v[28:29], v[12:13]
	v_mov_b64_e32 v[26:27], v[10:11]
	v_mov_b64_e32 v[24:25], v[8:9]
	v_mov_b64_e32 v[22:23], v[6:7]
	v_mov_b64_e32 v[20:21], v[4:5]
	v_mov_b64_e32 v[18:19], v[2:3]
	v_mov_b64_e32 v[16:17], v[0:1]
	v_mov_b64_e32 v[44:45], v[12:13]
	v_mov_b64_e32 v[42:43], v[10:11]
	v_mov_b64_e32 v[40:41], v[8:9]
	v_mov_b64_e32 v[38:39], v[6:7]
	v_mov_b64_e32 v[36:37], v[4:5]
	v_mov_b64_e32 v[34:35], v[2:3]
	v_mov_b64_e32 v[32:33], v[0:1]
	v_mov_b64_e32 v[60:61], v[12:13]
	v_mov_b64_e32 v[58:59], v[10:11]
	v_mov_b64_e32 v[56:57], v[8:9]
	v_mov_b64_e32 v[54:55], v[6:7]
	v_mov_b64_e32 v[52:53], v[4:5]
	v_mov_b64_e32 v[50:51], v[2:3]
	v_mov_b64_e32 v[48:49], v[0:1]
	v_mov_b64_e32 v[76:77], v[12:13]
	v_mov_b64_e32 v[74:75], v[10:11]
	v_mov_b64_e32 v[72:73], v[8:9]
	v_mov_b64_e32 v[70:71], v[6:7]
	v_mov_b64_e32 v[68:69], v[4:5]
	v_mov_b64_e32 v[66:67], v[2:3]
	v_mov_b64_e32 v[64:65], v[0:1]
	v_mov_b32_e32 v243, 0xf149f2ca
	v_mov_b32_e32 v241, 0
	s_mov_b32 s8, 0x2aaaaaab
	v_mul_hi_i32 v0, v224, s8
	v_ashrrev_i32_e32 v0, 1, v0
	v_mul_lo_u32 v1, v0, 12
	v_sub_u32_e32 v1, v224, v1
	v_mul_u32_u24_e32 v0, 0xd0, v0
	v_lshl_add_u32 v248, v1, 4, v0
	v_add_u32_e32 v3, 0x200, v224
	v_mul_hi_i32 v0, v3, s8
	v_ashrrev_i32_e32 v0, 1, v0
	v_mul_lo_u32 v1, v0, 12
	v_sub_u32_e32 v1, v3, v1
	v_mul_u32_u24_e32 v0, 0xd0, v0
	v_lshl_add_u32 v249, v1, 4, v0
	v_lshrrev_b32_e32 v0, 3, v224
	v_and_b32_e32 v1, 7, v224
	v_mul_u32_u24_e32 v3, 0x90, v0
	v_lshl_add_u32 v250, v1, 4, v3
	v_lshlrev_b32_e32 v0, 11, v0
	v_lshl_or_b32 v251, v1, 4, v0
	s_movk_i32 s8, 0x100
	v_cmp_gt_i32_e64 s[100:101], s8, v224
	s_waitcnt lgkmcnt(0)
	s_barrier
	s_branch .LBB0_775
	.p2align	6

; template <int DK, int DV, int MODE>
; DI void att_gload(const AttArgs& a, int tile, u32x4 (&kr)[(64 * (DK / 8) + NT - 1) / NT], u32x4 (&vr)[(64 * (DV / 8) + NT - 1) / NT]) {
;     ...
; #pragma unroll
;   for (int i = 0; i < NKL; ++i) {
;     const int id = min(t + NT * i, 64 * CK - 1);
;     const int row = id / CK, c = id % CK;
;     if constexpr (MODE == 3) {
;       const bf16_t* src = (c < 8) ? (a.k + (size_t)(kbase + row) * a.ldk + c * 8) : (a.k2 + (size_t)(kbase + row) * a.ldk2 + (c - 8) * 8);
;       kr[i] = *(const u32x4*)src;
;     } else {
;       kr[i] = *(const u32x4*)(a.k + (size_t)(kbase + row) * a.ldk + c * 8);
;     }
;   }
; #pragma unroll
;   for (int i = 0; i < NVL; ++i) {
;     const int id = t + NT * i;
;     const int row = id / CV, c = id % CV;
;     vr[i] = *(const u32x4*)(a.v + (size_t)(kbase + row) * a.ldv + c * 8);
;   }
; }
; template <int DK, int DV>
; DI void att_swrite(int buf, const u32x4 (&kr)[(64 * (DK / 8) + NT - 1) / NT], const u32x4 (&vr)[(64 * (DV / 8) + NT - 1) / NT]) {
;   constexpr int CK = DK / 8, CV = DV / 8;
;   constexpr int KST = DK * 2 + 16, VST = DV * 2 + 16;
;   constexpr int KBYTES = 64 * KST, VBYTES = 64 * VST, BUFB = KBYTES + VBYTES;
;   constexpr int NKL = (64 * CK + NT - 1) / NT, NVL = (64 * CV + NT - 1) / NT;
;   const int t = tid_opaque();
; #pragma unroll
;   for (int i = 0; i < NKL; ++i) {
;     const int id = t + NT * i;
;     const int row = id / CK, c = id % CK;
;     if (id < 64 * CK) *(u32x4*)(smem + buf * BUFB + row * KST + c * 16) = kr[i];
;   }
; #pragma unroll
;   for (int i = 0; i < NVL; ++i) {
;     const int id = t + NT * i;
;     const int row = id / CV, c = id % CV;
;     *(u32x4*)(smem + buf * BUFB + KBYTES + row * VST + c * 16) = vr[i];
;   }
; template <int DK, int DV, int MODE, int QB, bool PACK = false>
; DI void attn_item(const AttArgs& a, int q0, int t_lo, int t_hi) {
;     ...
;   f32x16 o[QB][NDB];
;   float m[QB], lsum[QB];
; #pragma unroll
;   for (int qb = 0; qb < QB; ++qb) {
;     m[qb] = -1e30f; lsum[qb] = 0.f;
; #pragma unroll
;     for (int d = 0; d < NDB; ++d)
; #pragma unroll
;       for (int i = 0; i < 16; ++i) o[qb][d][i] = 0.f;
;   }
;   u32x4 kr[NKL], vr[NVL];
;   att_gload<DK, DV, MODE>(a, t_lo, kr, vr);
;   att_swrite<DK, DV>(0, kr, vr);
;   if (t_lo + 1 < t_hi) att_gload<DK, DV, MODE>(a, t_lo + 1, kr, vr);
;   __syncthreads();
;   const float scale = a.scale;
.LBB0_834:
	s_or_b64 exec, exec, s[4:5]
	s_waitcnt vmcnt(1)
	v_add_u32_e32 v8, v12, v14
	s_waitcnt vmcnt(0)
	ds_write_b128 v8, v[4:7] offset:9216
	v_mov_b32_e32 v8, v224
	s_mov_b32 s4, 0x40000
	v_min_i32_e32 v5, 0x1ff, v8
	v_ashrrev_i32_e32 v4, 31, v5
	v_lshrrev_b32_e32 v4, 29, v4
	v_add_u32_e32 v6, v5, v4
	v_ashrrev_i32_e32 v4, 3, v6
	v_and_b32_e32 v6, 0x1ffffff8, v6
	v_sub_u32_e32 v6, v5, v6
	v_ashrrev_i32_e32 v5, 31, v4
	v_lshlrev_b64 v[4:5], 12, v[4:5]
	v_lshlrev_b32_e32 v6, 3, v6
	v_ashrrev_i32_e32 v7, 31, v6
	v_lshl_add_u64 v[4:5], s[2:3], 0, v[4:5]
	v_lshl_add_u64 v[4:5], v[6:7], 1, v[4:5]
	v_ashrrev_i32_e32 v6, 31, v8
	v_lshrrev_b32_e32 v6, 29, v6
	v_add_u32_e32 v7, v8, v6
	v_ashrrev_i32_e32 v6, 3, v7
	v_and_b32_e32 v7, 0x1ffffff8, v7
	v_sub_u32_e32 v8, v8, v7
	v_ashrrev_i32_e32 v7, 31, v6
	v_lshlrev_b64 v[6:7], 12, v[6:7]
	v_lshlrev_b32_e32 v8, 3, v8
	v_add_co_u32_e32 v4, vcc, s4, v4
	v_ashrrev_i32_e32 v9, 31, v8
	v_lshl_add_u64 v[6:7], s[2:3], 0, v[6:7]
	v_addc_co_u32_e32 v5, vcc, 0, v5, vcc
	v_lshl_add_u64 v[6:7], v[8:9], 1, v[6:7]
	v_add_co_u32_e32 v6, vcc, s4, v6
	v_lshlrev_b32_e32 v189, 3, v3
	s_nop 0
	v_addc_co_u32_e32 v7, vcc, 0, v7, vcc
	global_load_dwordx4 v[176:179], v[4:5], off offset:1024
	global_load_dwordx4 v[180:183], v[6:7], off offset:1280
	v_bfe_u32 v4, v1, 2, 2
	v_and_b32_e32 v5, 16, v1
	v_lshlrev_b32_e32 v1, 2, v1
	v_lshl_or_b32 v3, v3, 2, v4
	v_and_or_b32 v1, v1, 12, v5
	v_mov_b32_e32 v14, v2
	v_mov_b32_e32 v15, v2
	v_lshlrev_b32_e32 v204, 1, v1
	v_mul_u32_u24_e32 v208, 0x90, v0
	v_mul_u32_u24_e32 v205, 0x90, v3
	v_mov_b32_e32 v0, v2
	v_mov_b32_e32 v1, v2
	v_mov_b32_e32 v3, v2
	v_mov_b32_e32 v4, v2
	v_mov_b32_e32 v5, v2
	v_mov_b32_e32 v6, v2
	v_mov_b32_e32 v7, v2
	v_mov_b32_e32 v8, v2
	v_mov_b32_e32 v9, v2
	v_mov_b32_e32 v10, v2
	v_mov_b32_e32 v11, v2
	v_mov_b32_e32 v12, v2
	v_mov_b32_e32 v13, v2
	v_mov_b64_e32 v[30:31], v[14:15]
	v_mov_b64_e32 v[46:47], v[14:15]
	v_mov_b64_e32 v[62:63], v[14:15]
	v_mov_b64_e32 v[78:79], v[14:15]
	s_lshl_b32 s8, s6, 6
	s_mov_b32 s9, 0
	v_mov_b32_e32 v206, 0
	v_mov_b32_e32 v191, 0xf149f2ca
	s_add_u32 s4, s2, 0x80000
	s_addc_u32 s5, s3, 0
	v_lshrrev_b32_e32 v210, 3, v224
	v_and_b32_e32 v211, 7, v224
	v_lshlrev_b32_e32 v212, 12, v210
	v_lshl_or_b32 v212, v211, 4, v212
	v_mul_u32_u24_e32 v210, 0x90, v210
	v_lshl_add_u32 v210, v211, 4, v210
	v_mov_b64_e32 v[28:29], v[12:13]
	v_mov_b64_e32 v[26:27], v[10:11]
	v_mov_b64_e32 v[24:25], v[8:9]
	v_mov_b64_e32 v[22:23], v[6:7]
	v_mov_b64_e32 v[20:21], v[4:5]
	v_mov_b64_e32 v[18:19], v[2:3]
	v_mov_b64_e32 v[16:17], v[0:1]
	v_mov_b64_e32 v[44:45], v[12:13]
	v_mov_b64_e32 v[42:43], v[10:11]
	v_mov_b64_e32 v[40:41], v[8:9]
	v_mov_b64_e32 v[38:39], v[6:7]
	v_mov_b64_e32 v[36:37], v[4:5]
	v_mov_b64_e32 v[34:35], v[2:3]
	v_mov_b64_e32 v[32:33], v[0:1]
	v_mov_b64_e32 v[60:61], v[12:13]
	v_mov_b64_e32 v[58:59], v[10:11]
	v_mov_b64_e32 v[56:57], v[8:9]
	v_mov_b64_e32 v[54:55], v[6:7]
	v_mov_b64_e32 v[52:53], v[4:5]
	v_mov_b64_e32 v[50:51], v[2:3]
	v_mov_b64_e32 v[48:49], v[0:1]
	v_mov_b64_e32 v[76:77], v[12:13]
	v_mov_b64_e32 v[74:75], v[10:11]
	v_mov_b64_e32 v[72:73], v[8:9]
	v_mov_b64_e32 v[70:71], v[6:7]
	v_mov_b64_e32 v[68:69], v[4:5]
	v_mov_b64_e32 v[66:67], v[2:3]
	v_mov_b64_e32 v[64:65], v[0:1]
	v_mov_b32_e32 v1, 0xf149f2ca
	v_mov_b32_e32 v207, 0
	s_waitcnt lgkmcnt(0)
	s_barrier
	s_branch .LBB0_836
	.p2align	6

; #define LDA8(dst, b, h) _Pragma("unroll") for (int m = 0; m < 4; ++m) _Pragma("unroll") for (int k = 0; k < 2; ++k) \
;     dst[m][k] = *(const bf16x8*)((const char*)SA8(b, h) + lds_byte8(wr * 64 + m * 16 + fr, k * 32 + fq * 8))
; #define LDB8(dst, b, h) _Pragma("unroll") for (int n = 0; n < 2; ++n) _Pragma("unroll") for (int k = 0; k < 2; ++k) \
;     dst[n][k] = *(const bf16x8*)((const char*)SB8(b, h) + lds_byte8(wc * 32 + n * 16 + fr, k * 32 + fq * 8))
; #define WAIT_V8(n) asm volatile("s_waitcnt vmcnt(" #n ")" ::: "memory")
; #define WAIT_L8(n) asm volatile("s_waitcnt lgkmcnt(" #n ")" ::: "memory")
; #define BAR8 __builtin_amdgcn_s_barrier()
; #define SCHED8 __builtin_amdgcn_sched_barrier(0)
;     ...
;   if (wr == 1) BAR8;
;   WAIT_V8(4); BAR8;
;   STAGE8(SB8(1, 0), Bt, K, bcol, 1); STAGE8(SA8(1, 0), A, lda, brow, 1); STAGE8(SB8(1, 1), Bt, K, bcol + 128, 1);
;   WAIT_V8(6); BAR8;
;   for (int tt = 0; tt < nt - 2; tt += 2) {
;     LDB8(B0, 0, 0); SCHED8; LDA8(At, 0, 0); STAGE8(SA8(1, 1), A, lda, brow + 128, tt + 1);
;     WAIT_L8(8); BAR8; WAIT_L8(0); MMA8(0, 0, At, B0); BAR8; SCHED8;
;     LDB8(B1, 0, 1); STAGE8(SB8(0, 0), Bt, K, bcol, tt + 2);
.LBB0_907:
	s_or_b64 exec, exec, s[12:13]
	s_lshl_b32 s29, s20, 11
	s_waitcnt vmcnt(0)
	s_and_b32 s36, s29, 0x1f80000
	s_mov_b64 s[38:39], 0x80
	v_lshl_add_u64 v[14:15], v[14:15], 0, s[38:39]
	s_or_b32 m0, s100, 0x18000
	s_waitcnt vmcnt(4)
	s_barrier
	global_load_lds_dwordx4 v[14:15], off
	v_lshl_add_u64 v[14:15], v[18:19], 0, s[38:39]
	s_or_b32 m0, s100, 0x1a000
	s_nop 0
	global_load_lds_dwordx4 v[14:15], off
	v_lshl_add_u64 v[14:15], v[20:21], 0, s[38:39]
	s_or_b32 m0, s100, 0x8000
	s_nop 0
	global_load_lds_dwordx4 v[14:15], off
	v_lshl_add_u64 v[14:15], v[22:23], 0, s[38:39]
	s_or_b32 m0, s100, 0xa000
	s_nop 0
	global_load_lds_dwordx4 v[14:15], off
	s_or_b32 m0, s100, 0x1c000
	v_lshl_add_u64 v[14:15], v[26:27], 0, s[38:39]
	global_load_lds_dwordx4 v[14:15], off
	v_lshl_add_u64 v[14:15], v[28:29], 0, s[38:39]
	s_or_b32 m0, s100, 0x1e000
	v_and_b32_e32 v147, 15, v3
	global_load_lds_dwordx4 v[14:15], off
	v_bfe_u32 v148, v3, 4, 2
	v_lshlrev_b32_e32 v14, 4, v148
	v_lshlrev_b32_e32 v15, 6, v147
	v_lshlrev_b32_e32 v18, 2, v3
	v_lshlrev_b64 v[136:137], 10, v[16:17]
	v_or_b32_e32 v17, v14, v15
	v_and_b32_e32 v18, 32, v18
	s_mov_b32 s29, 0x10000
	s_and_b32 s12, s21, 0xffffff00
	v_bitop3_b32 v20, v17, s29, v18 bitop3:0xde
	s_mov_b32 s29, 0x14000
	s_ashr_i32 s13, s12, 31
	v_readlane_b32 s40, v254, 35
	v_bitop3_b32 v19, v14, v18, v15 bitop3:0x36
	v_bitop3_b32 v21, v17, s29, v18 bitop3:0xde
	s_mov_b32 s29, 0x18000
	v_lshlrev_b32_e32 v15, 6, v3
	s_lshl_b64 s[12:13], s[12:13], 11
	s_mov_b32 s37, s40
	v_bitop3_b32 v22, v17, s29, v18 bitop3:0xde
	s_mov_b32 s29, 0x1c000
	v_and_b32_e32 v15, 0x3c0, v15
	v_bitop3_b32 v17, v17, s29, v18 bitop3:0xde
	v_bitop3_b32 v18, v15, v18, v14 bitop3:0x36
	v_lshl_add_u64 v[14:15], s[12:13], 0, v[6:7]
	v_lshl_add_u64 v[6:7], s[36:37], 0, v[6:7]
	v_lshl_add_u64 v[14:15], v[14:15], 0, v[8:9]
	v_lshl_add_u64 v[6:7], v[6:7], 0, v[8:9]
	v_bfe_u32 v146, v3, 6, 2
	s_waitcnt vmcnt(6)
	v_lshlrev_b32_e32 v149, 6, v5
	v_lshlrev_b32_e32 v5, 13, v5
	v_lshl_add_u64 v[138:139], s[4:5], 0, v[14:15]
	v_lshl_add_u64 v[14:15], s[12:13], 0, v[10:11]
	v_lshl_add_u64 v[142:143], s[2:3], 0, v[6:7]
	v_lshl_add_u64 v[6:7], s[36:37], 0, v[10:11]
	v_lshlrev_b64 v[134:135], 10, v[24:25]
	v_readlane_b32 s41, v254, 36
	v_readlane_b32 s42, v254, 37
	v_readlane_b32 s43, v254, 38
	v_lshlrev_b32_e32 v16, 12, v146
	v_or_b32_e32 v23, 0x800, v5
	v_or_b32_e32 v24, 0x1000, v5
	v_or_b32_e32 v25, 0x1800, v5
	v_lshl_add_u64 v[14:15], v[14:15], 0, v[12:13]
	v_lshl_add_u64 v[6:7], v[6:7], 0, v[12:13]
	v_lshl_add_u64 v[140:141], s[4:5], 0, v[14:15]
	v_lshl_add_u64 v[144:145], s[2:3], 0, v[6:7]
	s_mov_b32 s29, -2
	s_mov_b64 s[12:13], 0
	v_add_u32_e32 v171, v20, v16
	v_add_u32_e32 v156, v19, v5
	v_add_u32_e32 v155, v18, v23
	v_add_u32_e32 v154, v18, v24
	v_add_u32_e32 v153, v18, v25
	v_add_u32_e32 v167, v21, v16
	v_add_u32_e32 v160, v22, v16
	v_add_u32_e32 v158, v17, v16
	s_mov_b64 s[36:37], 0x6040080
	s_mov_b64 s[38:39], 0xc4a0100
	s_mov_b64 s[40:41], 0x6000100
	s_mov_b64 s[42:43], 0xc4e0100
	s_mov_b64 s[44:45], 0x6040100
	s_mov_b64 s[46:47], 0xc4a0180
	s_mov_b64 s[48:49], 0x6000180
	s_mov_b64 s[50:51], 0xc4e0180
	s_barrier
	ds_read_b128 v[174:177], v171
	ds_read_b128 v[178:181], v171 offset:1024
	ds_read_b128 v[182:185], v171 offset:2048
	ds_read_b128 v[186:189], v171 offset:3072
	v_lshl_add_u64 v[222:223], v[142:143], 0, s[12:13]
	v_lshl_add_u64 v[226:227], v[222:223], 0, s[36:37]
	s_or_b32 m0, s100, 0xc000
	ds_read_b128 v[190:193], v156
	ds_read_b128 v[194:197], v156 offset:1024
	ds_read_b128 v[198:201], v155
	ds_read_b128 v[202:205], v155 offset:1024
	ds_read_b128 v[206:209], v154
	ds_read_b128 v[210:213], v154 offset:1024
	ds_read_b128 v[214:217], v153
	ds_read_b128 v[218:221], v153 offset:1024
	global_load_lds_dwordx4 v[226:227], off
	v_lshl_add_u64 v[226:227], v[144:145], 0, s[12:13]
	s_or_b32 m0, s100, 0xe000
	v_lshl_add_u64 v[228:229], v[226:227], 0, s[36:37]
	global_load_lds_dwordx4 v[228:229], off
	s_waitcnt lgkmcnt(8)
	s_barrier
	s_waitcnt lgkmcnt(0)
	v_mfma_f32_16x16x32_bf16 v[128:131], v[190:193], v[174:177], 0
	v_mfma_f32_16x16x32_bf16 v[124:127], v[190:193], v[182:185], 0
	v_mfma_f32_16x16x32_bf16 v[120:123], v[198:201], v[174:177], 0
	v_mfma_f32_16x16x32_bf16 v[116:119], v[198:201], v[182:185], 0
	v_mfma_f32_16x16x32_bf16 v[112:115], v[206:209], v[174:177], 0
	v_mfma_f32_16x16x32_bf16 v[108:111], v[206:209], v[182:185], 0
	v_mfma_f32_16x16x32_bf16 v[104:107], v[214:217], v[174:177], 0
	v_mfma_f32_16x16x32_bf16 v[100:103], v[214:217], v[182:185], 0
	v_mfma_f32_16x16x32_bf16 v[128:131], v[194:197], v[178:181], v[128:131]
	v_mfma_f32_16x16x32_bf16 v[124:127], v[194:197], v[186:189], v[124:127]
	v_mfma_f32_16x16x32_bf16 v[120:123], v[202:205], v[178:181], v[120:123]
	v_mfma_f32_16x16x32_bf16 v[116:119], v[202:205], v[186:189], v[116:119]
	v_mfma_f32_16x16x32_bf16 v[112:115], v[210:213], v[178:181], v[112:115]
	v_mfma_f32_16x16x32_bf16 v[108:111], v[210:213], v[186:189], v[108:111]
	v_mfma_f32_16x16x32_bf16 v[104:107], v[218:221], v[178:181], v[104:107]
	v_mfma_f32_16x16x32_bf16 v[100:103], v[218:221], v[186:189], v[100:103]
	s_barrier
	v_lshl_add_u64 v[228:229], v[138:139], 0, s[12:13]
	v_lshl_add_u64 v[236:237], v[228:229], 0, s[38:39]
	s_or_b32 m0, s100, 0x10000
	ds_read_b128 v[230:233], v167
	ds_read_b128 v[238:241], v167 offset:1024
	ds_read_b128 v[242:245], v167 offset:2048
	ds_read_b128 v[246:249], v167 offset:3072
	global_load_lds_dwordx4 v[236:237], off
	v_lshl_add_u64 v[236:237], v[140:141], 0, s[12:13]
	s_or_b32 m0, s100, 0x12000
	v_lshl_add_u64 v[250:251], v[236:237], 0, s[38:39]
	global_load_lds_dwordx4 v[250:251], off
	s_barrier
; #define LDA8(dst, b, h) _Pragma("unroll") for (int m = 0; m < 4; ++m) _Pragma("unroll") for (int k = 0; k < 2; ++k) \
;     dst[m][k] = *(const bf16x8*)((const char*)SA8(b, h) + lds_byte8(wr * 64 + m * 16 + fr, k * 32 + fq * 8))
; #define LDB8(dst, b, h) _Pragma("unroll") for (int n = 0; n < 2; ++n) _Pragma("unroll") for (int k = 0; k < 2; ++k) \
;     dst[n][k] = *(const bf16x8*)((const char*)SB8(b, h) + lds_byte8(wc * 32 + n * 16 + fr, k * 32 + fq * 8))
; #define WAIT_V8(n) asm volatile("s_waitcnt vmcnt(" #n ")" ::: "memory")
; #define WAIT_L8(n) asm volatile("s_waitcnt lgkmcnt(" #n ")" ::: "memory")
; #define BAR8 __builtin_amdgcn_s_barrier()
; #define SCHED8 __builtin_amdgcn_sched_barrier(0)
;     ...
;     BAR8; WAIT_L8(0); MMA8(0, 1, At, B1); BAR8;
;     LDA8(At, 0, 1); STAGE8(SA8(0, 0), A, lda, brow, tt + 2);
;     BAR8; WAIT_L8(0); MMA8(1, 0, At, B0); BAR8; SCHED8;
;     STAGE8(SB8(0, 1), Bt, K, bcol + 128, tt + 2);
;     WAIT_V8(6); BAR8; MMA8(1, 1, At, B1); BAR8;
;     LDB8(B0, 1, 0); SCHED8; LDA8(At, 1, 0); STAGE8(SA8(0, 1), A, lda, brow + 128, tt + 2);
;     WAIT_L8(8); BAR8; WAIT_L8(0); MMA8(0, 0, At, B0); BAR8; SCHED8;
	s_waitcnt lgkmcnt(0)
	v_mfma_f32_16x16x32_bf16 v[96:99], v[190:193], v[230:233], 0
	v_mfma_f32_16x16x32_bf16 v[92:95], v[190:193], v[242:245], 0
	v_mfma_f32_16x16x32_bf16 v[88:91], v[198:201], v[230:233], 0
	v_mfma_f32_16x16x32_bf16 v[84:87], v[198:201], v[242:245], 0
	v_mfma_f32_16x16x32_bf16 v[80:83], v[206:209], v[230:233], 0
	v_mfma_f32_16x16x32_bf16 v[76:79], v[206:209], v[242:245], 0
	v_mfma_f32_16x16x32_bf16 v[72:75], v[214:217], v[230:233], 0
	v_mfma_f32_16x16x32_bf16 v[68:71], v[214:217], v[242:245], 0
	v_mfma_f32_16x16x32_bf16 v[96:99], v[194:197], v[238:241], v[96:99]
	v_mfma_f32_16x16x32_bf16 v[92:95], v[194:197], v[246:249], v[92:95]
	v_mfma_f32_16x16x32_bf16 v[88:91], v[202:205], v[238:241], v[88:91]
	v_mfma_f32_16x16x32_bf16 v[84:87], v[202:205], v[246:249], v[84:87]
	v_mfma_f32_16x16x32_bf16 v[80:83], v[210:213], v[238:241], v[80:83]
	v_mfma_f32_16x16x32_bf16 v[76:79], v[210:213], v[246:249], v[76:79]
	v_mfma_f32_16x16x32_bf16 v[72:75], v[218:221], v[238:241], v[72:75]
	v_mfma_f32_16x16x32_bf16 v[68:71], v[218:221], v[246:249], v[68:71]
	v_lshl_add_u64 v[250:251], v[222:223], 0, s[40:41]
	s_mov_b32 m0, s100
	s_barrier
	ds_read_b128 v[190:193], v156 offset:16384
	ds_read_b128 v[194:197], v156 offset:17408
	ds_read_b128 v[198:201], v155 offset:16384
	ds_read_b128 v[202:205], v155 offset:17408
	ds_read_b128 v[206:209], v154 offset:16384
	ds_read_b128 v[210:213], v154 offset:17408
	ds_read_b128 v[214:217], v153 offset:16384
	ds_read_b128 v[218:221], v153 offset:17408
	global_load_lds_dwordx4 v[250:251], off
	s_or_b32 m0, s100, 0x2000
	v_lshl_add_u64 v[250:251], v[226:227], 0, s[40:41]
	global_load_lds_dwordx4 v[250:251], off
	s_barrier
	s_waitcnt lgkmcnt(0)
	v_mfma_f32_16x16x32_bf16 v[64:67], v[190:193], v[174:177], 0
	v_mfma_f32_16x16x32_bf16 v[60:63], v[190:193], v[182:185], 0
	v_mfma_f32_16x16x32_bf16 v[56:59], v[198:201], v[174:177], 0
	v_mfma_f32_16x16x32_bf16 v[52:55], v[198:201], v[182:185], 0
	v_mfma_f32_16x16x32_bf16 v[48:51], v[206:209], v[174:177], 0
	v_mfma_f32_16x16x32_bf16 v[44:47], v[206:209], v[182:185], 0
	v_mfma_f32_16x16x32_bf16 v[40:43], v[214:217], v[174:177], 0
	v_mfma_f32_16x16x32_bf16 v[36:39], v[214:217], v[182:185], 0
	v_mfma_f32_16x16x32_bf16 v[64:67], v[194:197], v[178:181], v[64:67]
	v_mfma_f32_16x16x32_bf16 v[60:63], v[194:197], v[186:189], v[60:63]
	v_mfma_f32_16x16x32_bf16 v[56:59], v[202:205], v[178:181], v[56:59]
	v_mfma_f32_16x16x32_bf16 v[52:55], v[202:205], v[186:189], v[52:55]
	v_mfma_f32_16x16x32_bf16 v[48:51], v[210:213], v[178:181], v[48:51]
	v_mfma_f32_16x16x32_bf16 v[44:47], v[210:213], v[186:189], v[44:47]
	v_mfma_f32_16x16x32_bf16 v[40:43], v[218:221], v[178:181], v[40:43]
	v_mfma_f32_16x16x32_bf16 v[36:39], v[218:221], v[186:189], v[36:39]
	s_barrier
	s_or_b32 m0, s100, 0x14000
	v_lshl_add_u64 v[174:175], v[228:229], 0, s[42:43]
	global_load_lds_dwordx4 v[174:175], off
	s_or_b32 m0, s100, 0x16000
	v_lshl_add_u64 v[174:175], v[236:237], 0, s[42:43]
	global_load_lds_dwordx4 v[174:175], off
	s_waitcnt vmcnt(6)
	s_barrier
	v_mfma_f32_16x16x32_bf16 v[32:35], v[190:193], v[230:233], 0
	v_mfma_f32_16x16x32_bf16 v[28:31], v[190:193], v[242:245], 0
	v_mfma_f32_16x16x32_bf16 v[24:27], v[198:201], v[230:233], 0
	v_mfma_f32_16x16x32_bf16 v[20:23], v[198:201], v[242:245], 0
	v_mfma_f32_16x16x32_bf16 v[16:19], v[206:209], v[230:233], 0
	v_mfma_f32_16x16x32_bf16 v[12:15], v[206:209], v[242:245], 0
	v_mfma_f32_16x16x32_bf16 v[8:11], v[214:217], v[230:233], 0
	v_mfma_f32_16x16x32_bf16 v[4:7], v[214:217], v[242:245], 0
	v_mfma_f32_16x16x32_bf16 v[32:35], v[194:197], v[238:241], v[32:35]
	v_mfma_f32_16x16x32_bf16 v[28:31], v[194:197], v[246:249], v[28:31]
	v_mfma_f32_16x16x32_bf16 v[24:27], v[202:205], v[238:241], v[24:27]
	v_mfma_f32_16x16x32_bf16 v[20:23], v[202:205], v[246:249], v[20:23]
	v_mfma_f32_16x16x32_bf16 v[16:19], v[210:213], v[238:241], v[16:19]
	v_mfma_f32_16x16x32_bf16 v[12:15], v[210:213], v[246:249], v[12:15]
	v_mfma_f32_16x16x32_bf16 v[8:11], v[218:221], v[238:241], v[8:11]
	v_mfma_f32_16x16x32_bf16 v[4:7], v[218:221], v[246:249], v[4:7]
	s_barrier
	ds_read_b128 v[174:177], v160
	ds_read_b128 v[178:181], v160 offset:1024
	ds_read_b128 v[182:185], v160 offset:2048
	ds_read_b128 v[186:189], v160 offset:3072
	v_lshl_add_u64 v[230:231], v[222:223], 0, s[44:45]
	s_or_b32 m0, s100, 0x4000
	ds_read_b128 v[190:193], v156 offset:32768
	ds_read_b128 v[194:197], v156 offset:33792
	ds_read_b128 v[198:201], v155 offset:32768
	ds_read_b128 v[202:205], v155 offset:33792
	ds_read_b128 v[206:209], v154 offset:32768
	ds_read_b128 v[210:213], v154 offset:33792
	ds_read_b128 v[214:217], v153 offset:32768
	ds_read_b128 v[218:221], v153 offset:33792
	global_load_lds_dwordx4 v[230:231], off
	s_or_b32 m0, s100, 0x6000
	v_lshl_add_u64 v[230:231], v[226:227], 0, s[44:45]
	global_load_lds_dwordx4 v[230:231], off
	s_waitcnt lgkmcnt(8)
	s_barrier
; #define LDA8(dst, b, h) _Pragma("unroll") for (int m = 0; m < 4; ++m) _Pragma("unroll") for (int k = 0; k < 2; ++k) \
;     dst[m][k] = *(const bf16x8*)((const char*)SA8(b, h) + lds_byte8(wr * 64 + m * 16 + fr, k * 32 + fq * 8))
; #define LDB8(dst, b, h) _Pragma("unroll") for (int n = 0; n < 2; ++n) _Pragma("unroll") for (int k = 0; k < 2; ++k) \
;     dst[n][k] = *(const bf16x8*)((const char*)SB8(b, h) + lds_byte8(wc * 32 + n * 16 + fr, k * 32 + fq * 8))
; #define WAIT_V8(n) asm volatile("s_waitcnt vmcnt(" #n ")" ::: "memory")
; #define WAIT_L8(n) asm volatile("s_waitcnt lgkmcnt(" #n ")" ::: "memory")
; #define BAR8 __builtin_amdgcn_s_barrier()
; #define SCHED8 __builtin_amdgcn_sched_barrier(0)
;     ...
;     WAIT_L8(8); BAR8; WAIT_L8(0); MMA8(0, 0, At, B0); BAR8; SCHED8;
;     LDB8(B1, 1, 1); STAGE8(SB8(1, 0), Bt, K, bcol, tt + 3);
;     BAR8; WAIT_L8(0); MMA8(0, 1, At, B1); BAR8;
;     LDA8(At, 1, 1); STAGE8(SA8(1, 0), A, lda, brow, tt + 3);
;     BAR8; WAIT_L8(0); MMA8(1, 0, At, B0); BAR8; SCHED8;
;     STAGE8(SB8(1, 1), Bt, K, bcol + 128, tt + 3);
;     WAIT_V8(6); BAR8; MMA8(1, 1, At, B1); BAR8;
	s_waitcnt lgkmcnt(0)
	v_mfma_f32_16x16x32_bf16 v[128:131], v[190:193], v[174:177], v[128:131]
	v_mfma_f32_16x16x32_bf16 v[124:127], v[190:193], v[182:185], v[124:127]
	v_mfma_f32_16x16x32_bf16 v[120:123], v[198:201], v[174:177], v[120:123]
	v_mfma_f32_16x16x32_bf16 v[116:119], v[198:201], v[182:185], v[116:119]
	v_mfma_f32_16x16x32_bf16 v[112:115], v[206:209], v[174:177], v[112:115]
	v_mfma_f32_16x16x32_bf16 v[108:111], v[206:209], v[182:185], v[108:111]
	v_mfma_f32_16x16x32_bf16 v[104:107], v[214:217], v[174:177], v[104:107]
	v_mfma_f32_16x16x32_bf16 v[100:103], v[214:217], v[182:185], v[100:103]
	v_mfma_f32_16x16x32_bf16 v[128:131], v[194:197], v[178:181], v[128:131]
	v_mfma_f32_16x16x32_bf16 v[124:127], v[194:197], v[186:189], v[124:127]
	v_mfma_f32_16x16x32_bf16 v[120:123], v[202:205], v[178:181], v[120:123]
	v_mfma_f32_16x16x32_bf16 v[116:119], v[202:205], v[186:189], v[116:119]
	v_mfma_f32_16x16x32_bf16 v[112:115], v[210:213], v[178:181], v[112:115]
	v_mfma_f32_16x16x32_bf16 v[108:111], v[210:213], v[186:189], v[108:111]
	v_mfma_f32_16x16x32_bf16 v[104:107], v[218:221], v[178:181], v[104:107]
	v_mfma_f32_16x16x32_bf16 v[100:103], v[218:221], v[186:189], v[100:103]
	s_barrier
	v_lshl_add_u64 v[250:251], v[228:229], 0, s[46:47]
	s_or_b32 m0, s100, 0x18000
	ds_read_b128 v[230:233], v158
	ds_read_b128 v[238:241], v158 offset:1024
	ds_read_b128 v[242:245], v158 offset:2048
	ds_read_b128 v[246:249], v158 offset:3072
	global_load_lds_dwordx4 v[250:251], off
	s_or_b32 m0, s100, 0x1a000
	v_lshl_add_u64 v[250:251], v[236:237], 0, s[46:47]
	global_load_lds_dwordx4 v[250:251], off
	s_barrier
	s_waitcnt lgkmcnt(0)
	v_mfma_f32_16x16x32_bf16 v[96:99], v[190:193], v[230:233], v[96:99]
	v_mfma_f32_16x16x32_bf16 v[92:95], v[190:193], v[242:245], v[92:95]
	v_mfma_f32_16x16x32_bf16 v[88:91], v[198:201], v[230:233], v[88:91]
	v_mfma_f32_16x16x32_bf16 v[84:87], v[198:201], v[242:245], v[84:87]
	v_mfma_f32_16x16x32_bf16 v[80:83], v[206:209], v[230:233], v[80:83]
	v_mfma_f32_16x16x32_bf16 v[76:79], v[206:209], v[242:245], v[76:79]
	v_mfma_f32_16x16x32_bf16 v[72:75], v[214:217], v[230:233], v[72:75]
	v_mfma_f32_16x16x32_bf16 v[68:71], v[214:217], v[242:245], v[68:71]
	v_mfma_f32_16x16x32_bf16 v[96:99], v[194:197], v[238:241], v[96:99]
	v_mfma_f32_16x16x32_bf16 v[92:95], v[194:197], v[246:249], v[92:95]
	v_mfma_f32_16x16x32_bf16 v[88:91], v[202:205], v[238:241], v[88:91]
	v_mfma_f32_16x16x32_bf16 v[84:87], v[202:205], v[246:249], v[84:87]
	v_mfma_f32_16x16x32_bf16 v[80:83], v[210:213], v[238:241], v[80:83]
	v_mfma_f32_16x16x32_bf16 v[76:79], v[210:213], v[246:249], v[76:79]
	v_mfma_f32_16x16x32_bf16 v[72:75], v[218:221], v[238:241], v[72:75]
	v_mfma_f32_16x16x32_bf16 v[68:71], v[218:221], v[246:249], v[68:71]
	v_lshl_add_u64 v[222:223], v[222:223], 0, s[48:49]
	s_or_b32 m0, s100, 0x8000
	s_barrier
	ds_read_b128 v[190:193], v156 offset:49152
	ds_read_b128 v[194:197], v156 offset:50176
	ds_read_b128 v[198:201], v155 offset:49152
	ds_read_b128 v[202:205], v155 offset:50176
	ds_read_b128 v[206:209], v154 offset:49152
	ds_read_b128 v[210:213], v154 offset:50176
	ds_read_b128 v[214:217], v153 offset:49152
	ds_read_b128 v[218:221], v153 offset:50176
	global_load_lds_dwordx4 v[222:223], off
	s_or_b32 m0, s100, 0xa000
	v_lshl_add_u64 v[222:223], v[226:227], 0, s[48:49]
	global_load_lds_dwordx4 v[222:223], off
	s_barrier
	s_waitcnt lgkmcnt(0)
	v_mfma_f32_16x16x32_bf16 v[64:67], v[190:193], v[174:177], v[64:67]
	v_mfma_f32_16x16x32_bf16 v[60:63], v[190:193], v[182:185], v[60:63]
	v_mfma_f32_16x16x32_bf16 v[56:59], v[198:201], v[174:177], v[56:59]
	v_mfma_f32_16x16x32_bf16 v[52:55], v[198:201], v[182:185], v[52:55]
	v_mfma_f32_16x16x32_bf16 v[48:51], v[206:209], v[174:177], v[48:51]
	v_mfma_f32_16x16x32_bf16 v[44:47], v[206:209], v[182:185], v[44:47]
	v_mfma_f32_16x16x32_bf16 v[40:43], v[214:217], v[174:177], v[40:43]
	v_mfma_f32_16x16x32_bf16 v[36:39], v[214:217], v[182:185], v[36:39]
	v_mfma_f32_16x16x32_bf16 v[64:67], v[194:197], v[178:181], v[64:67]
	v_mfma_f32_16x16x32_bf16 v[60:63], v[194:197], v[186:189], v[60:63]
	v_mfma_f32_16x16x32_bf16 v[56:59], v[202:205], v[178:181], v[56:59]
	v_mfma_f32_16x16x32_bf16 v[52:55], v[202:205], v[186:189], v[52:55]
	v_mfma_f32_16x16x32_bf16 v[48:51], v[210:213], v[178:181], v[48:51]
	v_mfma_f32_16x16x32_bf16 v[44:47], v[210:213], v[186:189], v[44:47]
	v_mfma_f32_16x16x32_bf16 v[40:43], v[218:221], v[178:181], v[40:43]
	v_mfma_f32_16x16x32_bf16 v[36:39], v[218:221], v[186:189], v[36:39]
	s_barrier
	s_or_b32 m0, s100, 0x1c000
	v_lshl_add_u64 v[174:175], v[228:229], 0, s[50:51]
	global_load_lds_dwordx4 v[174:175], off
	s_or_b32 m0, s100, 0x1e000
	v_lshl_add_u64 v[174:175], v[236:237], 0, s[50:51]
	global_load_lds_dwordx4 v[174:175], off
	s_waitcnt vmcnt(6)
	s_barrier
	v_mfma_f32_16x16x32_bf16 v[32:35], v[190:193], v[230:233], v[32:35]
	v_mfma_f32_16x16x32_bf16 v[28:31], v[190:193], v[242:245], v[28:31]
	v_mfma_f32_16x16x32_bf16 v[24:27], v[198:201], v[230:233], v[24:27]
	v_mfma_f32_16x16x32_bf16 v[20:23], v[198:201], v[242:245], v[20:23]
	v_mfma_f32_16x16x32_bf16 v[16:19], v[206:209], v[230:233], v[16:19]
	v_mfma_f32_16x16x32_bf16 v[12:15], v[206:209], v[242:245], v[12:15]
	v_mfma_f32_16x16x32_bf16 v[8:11], v[214:217], v[230:233], v[8:11]
	v_mfma_f32_16x16x32_bf16 v[4:7], v[214:217], v[242:245], v[4:7]
	v_mfma_f32_16x16x32_bf16 v[32:35], v[194:197], v[238:241], v[32:35]
	v_mfma_f32_16x16x32_bf16 v[28:31], v[194:197], v[246:249], v[28:31]
	v_mfma_f32_16x16x32_bf16 v[24:27], v[202:205], v[238:241], v[24:27]
	v_mfma_f32_16x16x32_bf16 v[20:23], v[202:205], v[246:249], v[20:23]
	v_mfma_f32_16x16x32_bf16 v[16:19], v[210:213], v[238:241], v[16:19]
	v_mfma_f32_16x16x32_bf16 v[12:15], v[210:213], v[246:249], v[12:15]
	v_mfma_f32_16x16x32_bf16 v[8:11], v[218:221], v[238:241], v[8:11]
	v_mfma_f32_16x16x32_bf16 v[4:7], v[218:221], v[246:249], v[4:7]
	s_add_i32 s29, s29, 2
	s_add_u32 s12, s12, 0x100
	s_addc_u32 s13, s13, 0
	s_cmp_lt_u32 s29, 12
	s_cbranch_scc0 .Lpk_exitb_2
	.p2align	6

; #define LDA8(dst, b, h) _Pragma("unroll") for (int m = 0; m < 4; ++m) _Pragma("unroll") for (int k = 0; k < 2; ++k) \
;     dst[m][k] = *(const bf16x8*)((const char*)SA8(b, h) + lds_byte8(wr * 64 + m * 16 + fr, k * 32 + fq * 8))
; #define LDB8(dst, b, h) _Pragma("unroll") for (int n = 0; n < 2; ++n) _Pragma("unroll") for (int k = 0; k < 2; ++k) \
;     dst[n][k] = *(const bf16x8*)((const char*)SB8(b, h) + lds_byte8(wc * 32 + n * 16 + fr, k * 32 + fq * 8))
; #define WAIT_V8(n) asm volatile("s_waitcnt vmcnt(" #n ")" ::: "memory")
; #define WAIT_L8(n) asm volatile("s_waitcnt lgkmcnt(" #n ")" ::: "memory")
; #define BAR8 __builtin_amdgcn_s_barrier()
; #define SCHED8 __builtin_amdgcn_sched_barrier(0)
;     ...
;   if (wr == 1) BAR8;
;   WAIT_V8(4); BAR8;
;   STAGE8(SB8(1, 0), Bt, K, bcol, 1); STAGE8(SA8(1, 0), A, lda, brow, 1); STAGE8(SB8(1, 1), Bt, K, bcol + 128, 1);
;   WAIT_V8(6); BAR8;
;   for (int tt = 0; tt < nt - 2; tt += 2) {
;     LDB8(B0, 0, 0); SCHED8; LDA8(At, 0, 0); STAGE8(SA8(1, 1), A, lda, brow + 128, tt + 1);
;     WAIT_L8(8); BAR8; WAIT_L8(0); MMA8(0, 0, At, B0); BAR8; SCHED8;
;     LDB8(B1, 0, 1); STAGE8(SB8(0, 0), Bt, K, bcol, tt + 2);
.LBB0_1004:
	s_or_b64 exec, exec, s[20:21]
	v_readlane_b32 s40, v254, 35
	s_lshl_b32 s20, s36, 10
	v_readlane_b32 s42, v254, 37
	v_readlane_b32 s43, v254, 38
	s_waitcnt vmcnt(0)
	s_and_b32 s20, s20, 0xfffc0000
	s_mov_b32 s21, s40
	s_mov_b64 s[42:43], 0x80
	s_and_b32 s1, s27, 7
	s_add_i32 s20, s20, 0xffc00000
	v_lshl_add_u64 v[10:11], v[10:11], 0, s[42:43]
	s_or_b32 m0, s100, 0x18000
	s_lshl_b32 s1, s1, 19
	s_lshl_b64 s[20:21], s[20:21], 1
	s_waitcnt vmcnt(4)
	s_barrier
	global_load_lds_dwordx4 v[10:11], off
	v_lshl_add_u64 v[10:11], v[12:13], 0, s[42:43]
	s_or_b32 m0, s100, 0x1a000
	s_nop 0
	global_load_lds_dwordx4 v[10:11], off
	v_lshl_add_u64 v[10:11], v[16:17], 0, s[42:43]
	s_or_b32 m0, s100, 0x8000
	s_add_u32 s14, s14, 0x40080
	global_load_lds_dwordx4 v[10:11], off
	v_lshl_add_u64 v[10:11], v[14:15], 0, s[42:43]
	s_addc_u32 s15, s15, 0
	s_or_b32 m0, s100, 0xa000
	s_nop 0
	global_load_lds_dwordx4 v[10:11], off
	v_lshl_add_u64 v[10:11], s[14:15], 0, v[132:133]
	v_lshl_add_u64 v[10:11], v[10:11], 0, v[6:7]
	s_or_b32 m0, s100, 0x1c000
	s_nop 0
	global_load_lds_dwordx4 v[10:11], off
	v_lshl_add_u64 v[10:11], s[14:15], 0, v[136:137]
	v_lshl_add_u64 v[10:11], v[10:11], 0, v[8:9]
	s_or_b32 m0, s100, 0x1e000
	v_and_b32_e32 v147, 15, v3
	global_load_lds_dwordx4 v[10:11], off
	v_bfe_u32 v148, v3, 4, 2
	v_lshlrev_b32_e32 v11, 4, v148
	v_lshlrev_b32_e32 v12, 6, v147
	v_lshlrev_b32_e32 v14, 2, v3
	v_or_b32_e32 v13, v11, v12
	v_and_b32_e32 v14, 32, v14
	s_mov_b32 s14, 0x10000
	v_bitop3_b32 v15, v13, s14, v14 bitop3:0xde
	s_mov_b32 s14, 0x14000
	s_add_u32 s12, s12, s1
	v_bitop3_b32 v16, v13, s14, v14 bitop3:0xde
	s_mov_b32 s14, 0x18000
	v_lshlrev_b32_e32 v18, 6, v3
	s_addc_u32 s13, s13, 0
	v_lshl_add_u64 v[8:9], v[136:137], 0, v[8:9]
	v_lshl_add_u64 v[6:7], v[132:133], 0, v[6:7]
	v_bfe_u32 v146, v3, 6, 2
	s_waitcnt vmcnt(6)
	v_lshlrev_b32_e32 v149, 6, v5
	v_bitop3_b32 v17, v13, s14, v14 bitop3:0xde
	s_mov_b32 s14, 0x1c000
	v_lshlrev_b32_e32 v5, 13, v5
	v_and_b32_e32 v18, 0x3c0, v18
	v_lshl_add_u64 v[138:139], s[12:13], 0, v[8:9]
	v_lshl_add_u64 v[140:141], s[12:13], 0, v[6:7]
	s_add_u32 s12, s4, s20
	v_readlane_b32 s41, v254, 36
	v_lshlrev_b32_e32 v10, 12, v146
	v_bitop3_b32 v12, v11, v14, v12 bitop3:0x36
	v_bitop3_b32 v13, v13, s14, v14 bitop3:0xde
	v_bitop3_b32 v11, v18, v14, v11 bitop3:0x36
	v_or_b32_e32 v14, 0x800, v5
	v_or_b32_e32 v18, 0x1000, v5
	v_or_b32_e32 v19, 0x1800, v5
	s_addc_u32 s13, s5, s21
	v_lshl_add_u64 v[142:143], s[12:13], 0, v[6:7]
	v_lshl_add_u64 v[144:145], s[12:13], 0, v[8:9]
	s_mov_b32 s1, -2
	s_mov_b64 s[12:13], 0
	v_add_u32_e32 v171, v15, v10
	v_add_u32_e32 v156, v12, v5
	v_add_u32_e32 v155, v11, v14
	v_add_u32_e32 v154, v11, v18
	v_add_u32_e32 v153, v11, v19
	v_add_u32_e32 v168, v16, v10
	v_add_u32_e32 v161, v17, v10
	v_add_u32_e32 v158, v13, v10
	s_mov_b64 s[20:21], 0xb840080
	s_mov_b64 s[40:41], 0xc7a0100
	s_mov_b64 s[42:43], 0xb800100
	s_mov_b64 s[44:45], 0xc7e0100
	s_mov_b64 s[46:47], 0xb840100
	s_mov_b64 s[48:49], 0xc7a0180
	s_mov_b64 s[50:51], 0xb800180
	s_mov_b64 s[52:53], 0xc7e0180
	s_barrier
	ds_read_b128 v[174:177], v171
	ds_read_b128 v[178:181], v171 offset:1024
	ds_read_b128 v[182:185], v171 offset:2048
	ds_read_b128 v[186:189], v171 offset:3072
	v_lshl_add_u64 v[222:223], v[140:141], 0, s[12:13]
	v_lshl_add_u64 v[226:227], v[222:223], 0, s[20:21]
	s_or_b32 m0, s100, 0xc000
	v_lshl_add_u64 v[236:237], v[138:139], 0, s[12:13]
	ds_read_b128 v[190:193], v156
	ds_read_b128 v[194:197], v156 offset:1024
	ds_read_b128 v[198:201], v155
	ds_read_b128 v[202:205], v155 offset:1024
	ds_read_b128 v[206:209], v154
	ds_read_b128 v[210:213], v154 offset:1024
	ds_read_b128 v[214:217], v153
	ds_read_b128 v[218:221], v153 offset:1024
	global_load_lds_dwordx4 v[226:227], off
	s_or_b32 m0, s100, 0xe000
	v_lshl_add_u64 v[226:227], v[236:237], 0, s[20:21]
	global_load_lds_dwordx4 v[226:227], off
	s_waitcnt lgkmcnt(8)
	s_barrier
	s_waitcnt lgkmcnt(0)
	v_mfma_f32_16x16x32_bf16 v[128:131], v[190:193], v[174:177], 0
	v_mfma_f32_16x16x32_bf16 v[124:127], v[190:193], v[182:185], 0
	v_mfma_f32_16x16x32_bf16 v[120:123], v[198:201], v[174:177], 0
	v_mfma_f32_16x16x32_bf16 v[116:119], v[198:201], v[182:185], 0
	v_mfma_f32_16x16x32_bf16 v[112:115], v[206:209], v[174:177], 0
	v_mfma_f32_16x16x32_bf16 v[108:111], v[206:209], v[182:185], 0
	v_mfma_f32_16x16x32_bf16 v[104:107], v[214:217], v[174:177], 0
	v_mfma_f32_16x16x32_bf16 v[100:103], v[214:217], v[182:185], 0
	v_mfma_f32_16x16x32_bf16 v[128:131], v[194:197], v[178:181], v[128:131]
	v_mfma_f32_16x16x32_bf16 v[124:127], v[194:197], v[186:189], v[124:127]
	v_mfma_f32_16x16x32_bf16 v[120:123], v[202:205], v[178:181], v[120:123]
	v_mfma_f32_16x16x32_bf16 v[116:119], v[202:205], v[186:189], v[116:119]
	v_mfma_f32_16x16x32_bf16 v[112:115], v[210:213], v[178:181], v[112:115]
	v_mfma_f32_16x16x32_bf16 v[108:111], v[210:213], v[186:189], v[108:111]
	v_mfma_f32_16x16x32_bf16 v[104:107], v[218:221], v[178:181], v[104:107]
	v_mfma_f32_16x16x32_bf16 v[100:103], v[218:221], v[186:189], v[100:103]
	s_barrier
	v_lshl_add_u64 v[246:247], v[142:143], 0, s[12:13]
	v_lshl_add_u64 v[248:249], v[246:247], 0, s[40:41]
	s_or_b32 m0, s100, 0x10000
	ds_read_b128 v[226:229], v168
	ds_read_b128 v[230:233], v168 offset:1024
	ds_read_b128 v[238:241], v168 offset:2048
	ds_read_b128 v[242:245], v168 offset:3072
	global_load_lds_dwordx4 v[248:249], off
	v_lshl_add_u64 v[248:249], v[144:145], 0, s[12:13]
	s_or_b32 m0, s100, 0x12000
	v_lshl_add_u64 v[250:251], v[248:249], 0, s[40:41]
	global_load_lds_dwordx4 v[250:251], off
	s_barrier
; #define LDA8(dst, b, h) _Pragma("unroll") for (int m = 0; m < 4; ++m) _Pragma("unroll") for (int k = 0; k < 2; ++k) \
;     dst[m][k] = *(const bf16x8*)((const char*)SA8(b, h) + lds_byte8(wr * 64 + m * 16 + fr, k * 32 + fq * 8))
; #define LDB8(dst, b, h) _Pragma("unroll") for (int n = 0; n < 2; ++n) _Pragma("unroll") for (int k = 0; k < 2; ++k) \
;     dst[n][k] = *(const bf16x8*)((const char*)SB8(b, h) + lds_byte8(wc * 32 + n * 16 + fr, k * 32 + fq * 8))
; #define WAIT_V8(n) asm volatile("s_waitcnt vmcnt(" #n ")" ::: "memory")
; #define WAIT_L8(n) asm volatile("s_waitcnt lgkmcnt(" #n ")" ::: "memory")
; #define BAR8 __builtin_amdgcn_s_barrier()
; #define SCHED8 __builtin_amdgcn_sched_barrier(0)
;     ...
;     BAR8; WAIT_L8(0); MMA8(0, 1, At, B1); BAR8;
;     LDA8(At, 0, 1); STAGE8(SA8(0, 0), A, lda, brow, tt + 2);
;     BAR8; WAIT_L8(0); MMA8(1, 0, At, B0); BAR8; SCHED8;
;     STAGE8(SB8(0, 1), Bt, K, bcol + 128, tt + 2);
;     WAIT_V8(6); BAR8; MMA8(1, 1, At, B1); BAR8;
;     LDB8(B0, 1, 0); SCHED8; LDA8(At, 1, 0); STAGE8(SA8(0, 1), A, lda, brow + 128, tt + 2);
;     WAIT_L8(8); BAR8; WAIT_L8(0); MMA8(0, 0, At, B0); BAR8; SCHED8;
	s_waitcnt lgkmcnt(0)
	v_mfma_f32_16x16x32_bf16 v[96:99], v[190:193], v[226:229], 0
	v_mfma_f32_16x16x32_bf16 v[92:95], v[190:193], v[238:241], 0
	v_mfma_f32_16x16x32_bf16 v[88:91], v[198:201], v[226:229], 0
	v_mfma_f32_16x16x32_bf16 v[84:87], v[198:201], v[238:241], 0
	v_mfma_f32_16x16x32_bf16 v[80:83], v[206:209], v[226:229], 0
	v_mfma_f32_16x16x32_bf16 v[76:79], v[206:209], v[238:241], 0
	v_mfma_f32_16x16x32_bf16 v[72:75], v[214:217], v[226:229], 0
	v_mfma_f32_16x16x32_bf16 v[68:71], v[214:217], v[238:241], 0
	v_mfma_f32_16x16x32_bf16 v[96:99], v[194:197], v[230:233], v[96:99]
	v_mfma_f32_16x16x32_bf16 v[92:95], v[194:197], v[242:245], v[92:95]
	v_mfma_f32_16x16x32_bf16 v[88:91], v[202:205], v[230:233], v[88:91]
	v_mfma_f32_16x16x32_bf16 v[84:87], v[202:205], v[242:245], v[84:87]
	v_mfma_f32_16x16x32_bf16 v[80:83], v[210:213], v[230:233], v[80:83]
	v_mfma_f32_16x16x32_bf16 v[76:79], v[210:213], v[242:245], v[76:79]
	v_mfma_f32_16x16x32_bf16 v[72:75], v[218:221], v[230:233], v[72:75]
	v_mfma_f32_16x16x32_bf16 v[68:71], v[218:221], v[242:245], v[68:71]
	v_lshl_add_u64 v[250:251], v[222:223], 0, s[42:43]
	s_mov_b32 m0, s100
	s_barrier
	ds_read_b128 v[190:193], v156 offset:16384
	ds_read_b128 v[194:197], v156 offset:17408
	ds_read_b128 v[198:201], v155 offset:16384
	ds_read_b128 v[202:205], v155 offset:17408
	ds_read_b128 v[206:209], v154 offset:16384
	ds_read_b128 v[210:213], v154 offset:17408
	ds_read_b128 v[214:217], v153 offset:16384
	ds_read_b128 v[218:221], v153 offset:17408
	global_load_lds_dwordx4 v[250:251], off
	s_or_b32 m0, s100, 0x2000
	v_lshl_add_u64 v[250:251], v[236:237], 0, s[42:43]
	global_load_lds_dwordx4 v[250:251], off
	s_barrier
	s_waitcnt lgkmcnt(0)
	v_mfma_f32_16x16x32_bf16 v[64:67], v[190:193], v[174:177], 0
	v_mfma_f32_16x16x32_bf16 v[60:63], v[190:193], v[182:185], 0
	v_mfma_f32_16x16x32_bf16 v[56:59], v[198:201], v[174:177], 0
	v_mfma_f32_16x16x32_bf16 v[52:55], v[198:201], v[182:185], 0
	v_mfma_f32_16x16x32_bf16 v[48:51], v[206:209], v[174:177], 0
	v_mfma_f32_16x16x32_bf16 v[44:47], v[206:209], v[182:185], 0
	v_mfma_f32_16x16x32_bf16 v[40:43], v[214:217], v[174:177], 0
	v_mfma_f32_16x16x32_bf16 v[36:39], v[214:217], v[182:185], 0
	v_mfma_f32_16x16x32_bf16 v[64:67], v[194:197], v[178:181], v[64:67]
	v_mfma_f32_16x16x32_bf16 v[60:63], v[194:197], v[186:189], v[60:63]
	v_mfma_f32_16x16x32_bf16 v[56:59], v[202:205], v[178:181], v[56:59]
	v_mfma_f32_16x16x32_bf16 v[52:55], v[202:205], v[186:189], v[52:55]
	v_mfma_f32_16x16x32_bf16 v[48:51], v[210:213], v[178:181], v[48:51]
	v_mfma_f32_16x16x32_bf16 v[44:47], v[210:213], v[186:189], v[44:47]
	v_mfma_f32_16x16x32_bf16 v[40:43], v[218:221], v[178:181], v[40:43]
	v_mfma_f32_16x16x32_bf16 v[36:39], v[218:221], v[186:189], v[36:39]
	s_barrier
	s_or_b32 m0, s100, 0x14000
	v_lshl_add_u64 v[174:175], v[246:247], 0, s[44:45]
	global_load_lds_dwordx4 v[174:175], off
	s_or_b32 m0, s100, 0x16000
	v_lshl_add_u64 v[174:175], v[248:249], 0, s[44:45]
	global_load_lds_dwordx4 v[174:175], off
	s_waitcnt vmcnt(6)
	s_barrier
	v_mfma_f32_16x16x32_bf16 v[32:35], v[190:193], v[226:229], 0
	v_mfma_f32_16x16x32_bf16 v[28:31], v[190:193], v[238:241], 0
	v_mfma_f32_16x16x32_bf16 v[24:27], v[198:201], v[226:229], 0
	v_mfma_f32_16x16x32_bf16 v[20:23], v[198:201], v[238:241], 0
	v_mfma_f32_16x16x32_bf16 v[16:19], v[206:209], v[226:229], 0
	v_mfma_f32_16x16x32_bf16 v[12:15], v[206:209], v[238:241], 0
	v_mfma_f32_16x16x32_bf16 v[8:11], v[214:217], v[226:229], 0
	v_mfma_f32_16x16x32_bf16 v[4:7], v[214:217], v[238:241], 0
	v_mfma_f32_16x16x32_bf16 v[32:35], v[194:197], v[230:233], v[32:35]
	v_mfma_f32_16x16x32_bf16 v[28:31], v[194:197], v[242:245], v[28:31]
	v_mfma_f32_16x16x32_bf16 v[24:27], v[202:205], v[230:233], v[24:27]
	v_mfma_f32_16x16x32_bf16 v[20:23], v[202:205], v[242:245], v[20:23]
	v_mfma_f32_16x16x32_bf16 v[16:19], v[210:213], v[230:233], v[16:19]
	v_mfma_f32_16x16x32_bf16 v[12:15], v[210:213], v[242:245], v[12:15]
	v_mfma_f32_16x16x32_bf16 v[8:11], v[218:221], v[230:233], v[8:11]
	v_mfma_f32_16x16x32_bf16 v[4:7], v[218:221], v[242:245], v[4:7]
	s_barrier
	ds_read_b128 v[174:177], v161
	ds_read_b128 v[178:181], v161 offset:1024
	ds_read_b128 v[182:185], v161 offset:2048
	ds_read_b128 v[186:189], v161 offset:3072
	v_lshl_add_u64 v[226:227], v[222:223], 0, s[46:47]
	s_or_b32 m0, s100, 0x4000
	ds_read_b128 v[190:193], v156 offset:32768
	ds_read_b128 v[194:197], v156 offset:33792
	ds_read_b128 v[198:201], v155 offset:32768
	ds_read_b128 v[202:205], v155 offset:33792
	ds_read_b128 v[206:209], v154 offset:32768
	ds_read_b128 v[210:213], v154 offset:33792
	ds_read_b128 v[214:217], v153 offset:32768
	ds_read_b128 v[218:221], v153 offset:33792
	global_load_lds_dwordx4 v[226:227], off
	s_or_b32 m0, s100, 0x6000
	v_lshl_add_u64 v[226:227], v[236:237], 0, s[46:47]
	global_load_lds_dwordx4 v[226:227], off
	s_waitcnt lgkmcnt(8)
	s_barrier
; #define LDA8(dst, b, h) _Pragma("unroll") for (int m = 0; m < 4; ++m) _Pragma("unroll") for (int k = 0; k < 2; ++k) \
;     dst[m][k] = *(const bf16x8*)((const char*)SA8(b, h) + lds_byte8(wr * 64 + m * 16 + fr, k * 32 + fq * 8))
; #define LDB8(dst, b, h) _Pragma("unroll") for (int n = 0; n < 2; ++n) _Pragma("unroll") for (int k = 0; k < 2; ++k) \
;     dst[n][k] = *(const bf16x8*)((const char*)SB8(b, h) + lds_byte8(wc * 32 + n * 16 + fr, k * 32 + fq * 8))
; #define WAIT_V8(n) asm volatile("s_waitcnt vmcnt(" #n ")" ::: "memory")
; #define WAIT_L8(n) asm volatile("s_waitcnt lgkmcnt(" #n ")" ::: "memory")
; #define BAR8 __builtin_amdgcn_s_barrier()
; #define SCHED8 __builtin_amdgcn_sched_barrier(0)
;     ...
;     WAIT_L8(8); BAR8; WAIT_L8(0); MMA8(0, 0, At, B0); BAR8; SCHED8;
;     LDB8(B1, 1, 1); STAGE8(SB8(1, 0), Bt, K, bcol, tt + 3);
;     BAR8; WAIT_L8(0); MMA8(0, 1, At, B1); BAR8;
;     LDA8(At, 1, 1); STAGE8(SA8(1, 0), A, lda, brow, tt + 3);
;     BAR8; WAIT_L8(0); MMA8(1, 0, At, B0); BAR8; SCHED8;
;     STAGE8(SB8(1, 1), Bt, K, bcol + 128, tt + 3);
;     WAIT_V8(6); BAR8; MMA8(1, 1, At, B1); BAR8;
	s_waitcnt lgkmcnt(0)
	v_mfma_f32_16x16x32_bf16 v[128:131], v[190:193], v[174:177], v[128:131]
	v_mfma_f32_16x16x32_bf16 v[124:127], v[190:193], v[182:185], v[124:127]
	v_mfma_f32_16x16x32_bf16 v[120:123], v[198:201], v[174:177], v[120:123]
	v_mfma_f32_16x16x32_bf16 v[116:119], v[198:201], v[182:185], v[116:119]
	v_mfma_f32_16x16x32_bf16 v[112:115], v[206:209], v[174:177], v[112:115]
	v_mfma_f32_16x16x32_bf16 v[108:111], v[206:209], v[182:185], v[108:111]
	v_mfma_f32_16x16x32_bf16 v[104:107], v[214:217], v[174:177], v[104:107]
	v_mfma_f32_16x16x32_bf16 v[100:103], v[214:217], v[182:185], v[100:103]
	v_mfma_f32_16x16x32_bf16 v[128:131], v[194:197], v[178:181], v[128:131]
	v_mfma_f32_16x16x32_bf16 v[124:127], v[194:197], v[186:189], v[124:127]
	v_mfma_f32_16x16x32_bf16 v[120:123], v[202:205], v[178:181], v[120:123]
	v_mfma_f32_16x16x32_bf16 v[116:119], v[202:205], v[186:189], v[116:119]
	v_mfma_f32_16x16x32_bf16 v[112:115], v[210:213], v[178:181], v[112:115]
	v_mfma_f32_16x16x32_bf16 v[108:111], v[210:213], v[186:189], v[108:111]
	v_mfma_f32_16x16x32_bf16 v[104:107], v[218:221], v[178:181], v[104:107]
	v_mfma_f32_16x16x32_bf16 v[100:103], v[218:221], v[186:189], v[100:103]
	s_barrier
	v_lshl_add_u64 v[250:251], v[246:247], 0, s[48:49]
	s_or_b32 m0, s100, 0x18000
	ds_read_b128 v[226:229], v158
	ds_read_b128 v[230:233], v158 offset:1024
	ds_read_b128 v[238:241], v158 offset:2048
	ds_read_b128 v[242:245], v158 offset:3072
	global_load_lds_dwordx4 v[250:251], off
	s_or_b32 m0, s100, 0x1a000
	v_lshl_add_u64 v[250:251], v[248:249], 0, s[48:49]
	global_load_lds_dwordx4 v[250:251], off
	s_barrier
	s_waitcnt lgkmcnt(0)
	v_mfma_f32_16x16x32_bf16 v[96:99], v[190:193], v[226:229], v[96:99]
	v_mfma_f32_16x16x32_bf16 v[92:95], v[190:193], v[238:241], v[92:95]
	v_mfma_f32_16x16x32_bf16 v[88:91], v[198:201], v[226:229], v[88:91]
	v_mfma_f32_16x16x32_bf16 v[84:87], v[198:201], v[238:241], v[84:87]
	v_mfma_f32_16x16x32_bf16 v[80:83], v[206:209], v[226:229], v[80:83]
	v_mfma_f32_16x16x32_bf16 v[76:79], v[206:209], v[238:241], v[76:79]
	v_mfma_f32_16x16x32_bf16 v[72:75], v[214:217], v[226:229], v[72:75]
	v_mfma_f32_16x16x32_bf16 v[68:71], v[214:217], v[238:241], v[68:71]
	v_mfma_f32_16x16x32_bf16 v[96:99], v[194:197], v[230:233], v[96:99]
	v_mfma_f32_16x16x32_bf16 v[92:95], v[194:197], v[242:245], v[92:95]
	v_mfma_f32_16x16x32_bf16 v[88:91], v[202:205], v[230:233], v[88:91]
	v_mfma_f32_16x16x32_bf16 v[84:87], v[202:205], v[242:245], v[84:87]
	v_mfma_f32_16x16x32_bf16 v[80:83], v[210:213], v[230:233], v[80:83]
	v_mfma_f32_16x16x32_bf16 v[76:79], v[210:213], v[242:245], v[76:79]
	v_mfma_f32_16x16x32_bf16 v[72:75], v[218:221], v[230:233], v[72:75]
	v_mfma_f32_16x16x32_bf16 v[68:71], v[218:221], v[242:245], v[68:71]
	v_lshl_add_u64 v[222:223], v[222:223], 0, s[50:51]
	s_or_b32 m0, s100, 0x8000
	s_barrier
	ds_read_b128 v[190:193], v156 offset:49152
	ds_read_b128 v[194:197], v156 offset:50176
	ds_read_b128 v[198:201], v155 offset:49152
	ds_read_b128 v[202:205], v155 offset:50176
	ds_read_b128 v[206:209], v154 offset:49152
	ds_read_b128 v[210:213], v154 offset:50176
	ds_read_b128 v[214:217], v153 offset:49152
	ds_read_b128 v[218:221], v153 offset:50176
	global_load_lds_dwordx4 v[222:223], off
	s_or_b32 m0, s100, 0xa000
	v_lshl_add_u64 v[222:223], v[236:237], 0, s[50:51]
	global_load_lds_dwordx4 v[222:223], off
	s_barrier
	s_waitcnt lgkmcnt(0)
	v_mfma_f32_16x16x32_bf16 v[64:67], v[190:193], v[174:177], v[64:67]
	v_mfma_f32_16x16x32_bf16 v[60:63], v[190:193], v[182:185], v[60:63]
	v_mfma_f32_16x16x32_bf16 v[56:59], v[198:201], v[174:177], v[56:59]
	v_mfma_f32_16x16x32_bf16 v[52:55], v[198:201], v[182:185], v[52:55]
	v_mfma_f32_16x16x32_bf16 v[48:51], v[206:209], v[174:177], v[48:51]
	v_mfma_f32_16x16x32_bf16 v[44:47], v[206:209], v[182:185], v[44:47]
	v_mfma_f32_16x16x32_bf16 v[40:43], v[214:217], v[174:177], v[40:43]
	v_mfma_f32_16x16x32_bf16 v[36:39], v[214:217], v[182:185], v[36:39]
	v_mfma_f32_16x16x32_bf16 v[64:67], v[194:197], v[178:181], v[64:67]
	v_mfma_f32_16x16x32_bf16 v[60:63], v[194:197], v[186:189], v[60:63]
	v_mfma_f32_16x16x32_bf16 v[56:59], v[202:205], v[178:181], v[56:59]
	v_mfma_f32_16x16x32_bf16 v[52:55], v[202:205], v[186:189], v[52:55]
	v_mfma_f32_16x16x32_bf16 v[48:51], v[210:213], v[178:181], v[48:51]
	v_mfma_f32_16x16x32_bf16 v[44:47], v[210:213], v[186:189], v[44:47]
	v_mfma_f32_16x16x32_bf16 v[40:43], v[218:221], v[178:181], v[40:43]
	v_mfma_f32_16x16x32_bf16 v[36:39], v[218:221], v[186:189], v[36:39]
	s_barrier
	s_or_b32 m0, s100, 0x1c000
	v_lshl_add_u64 v[174:175], v[246:247], 0, s[52:53]
	global_load_lds_dwordx4 v[174:175], off
	s_or_b32 m0, s100, 0x1e000
	v_lshl_add_u64 v[174:175], v[248:249], 0, s[52:53]
	global_load_lds_dwordx4 v[174:175], off
	s_waitcnt vmcnt(6)
	s_barrier
	v_mfma_f32_16x16x32_bf16 v[32:35], v[190:193], v[226:229], v[32:35]
	v_mfma_f32_16x16x32_bf16 v[28:31], v[190:193], v[238:241], v[28:31]
	v_mfma_f32_16x16x32_bf16 v[24:27], v[198:201], v[226:229], v[24:27]
	v_mfma_f32_16x16x32_bf16 v[20:23], v[198:201], v[238:241], v[20:23]
	v_mfma_f32_16x16x32_bf16 v[16:19], v[206:209], v[226:229], v[16:19]
	v_mfma_f32_16x16x32_bf16 v[12:15], v[206:209], v[238:241], v[12:15]
	v_mfma_f32_16x16x32_bf16 v[8:11], v[214:217], v[226:229], v[8:11]
	v_mfma_f32_16x16x32_bf16 v[4:7], v[214:217], v[238:241], v[4:7]
	v_mfma_f32_16x16x32_bf16 v[32:35], v[194:197], v[230:233], v[32:35]
	v_mfma_f32_16x16x32_bf16 v[28:31], v[194:197], v[242:245], v[28:31]
	v_mfma_f32_16x16x32_bf16 v[24:27], v[202:205], v[230:233], v[24:27]
	v_mfma_f32_16x16x32_bf16 v[20:23], v[202:205], v[242:245], v[20:23]
	v_mfma_f32_16x16x32_bf16 v[16:19], v[210:213], v[230:233], v[16:19]
	v_mfma_f32_16x16x32_bf16 v[12:15], v[210:213], v[242:245], v[12:15]
	v_mfma_f32_16x16x32_bf16 v[8:11], v[218:221], v[230:233], v[8:11]
	v_mfma_f32_16x16x32_bf16 v[4:7], v[218:221], v[242:245], v[4:7]
	s_add_i32 s1, s1, 2
	s_add_u32 s12, s12, 0x100
	s_addc_u32 s13, s13, 0
	s_cmp_lt_u32 s1, 12
	s_cbranch_scc0 .Lpk_exitb_3
	.p2align	6

; #define LDA8(dst, b, h) _Pragma("unroll") for (int m = 0; m < 4; ++m) _Pragma("unroll") for (int k = 0; k < 2; ++k) \
;     dst[m][k] = *(const bf16x8*)((const char*)SA8(b, h) + lds_byte8(wr * 64 + m * 16 + fr, k * 32 + fq * 8))
; #define LDB8(dst, b, h) _Pragma("unroll") for (int n = 0; n < 2; ++n) _Pragma("unroll") for (int k = 0; k < 2; ++k) \
;     dst[n][k] = *(const bf16x8*)((const char*)SB8(b, h) + lds_byte8(wc * 32 + n * 16 + fr, k * 32 + fq * 8))
; #define WAIT_V8(n) asm volatile("s_waitcnt vmcnt(" #n ")" ::: "memory")
; #define WAIT_L8(n) asm volatile("s_waitcnt lgkmcnt(" #n ")" ::: "memory")
; #define BAR8 __builtin_amdgcn_s_barrier()
; #define SCHED8 __builtin_amdgcn_sched_barrier(0)
;     ...
;   if (wr == 1) BAR8;
;   WAIT_V8(4); BAR8;
;   STAGE8(SB8(1, 0), Bt, K, bcol, 1); STAGE8(SA8(1, 0), A, lda, brow, 1); STAGE8(SB8(1, 1), Bt, K, bcol + 128, 1);
;   WAIT_V8(6); BAR8;
;   for (int tt = 0; tt < nt - 2; tt += 2) {
;     LDB8(B0, 0, 0); SCHED8; LDA8(At, 0, 0); STAGE8(SA8(1, 1), A, lda, brow + 128, tt + 1);
;     WAIT_L8(8); BAR8; WAIT_L8(0); MMA8(0, 0, At, B0); BAR8; SCHED8;
;     LDB8(B1, 0, 1); STAGE8(SB8(0, 0), Bt, K, bcol, tt + 2);
.LBB0_1014:
	s_or_b64 exec, exec, s[14:15]
	v_readlane_b32 s40, v254, 35
	v_readlane_b32 s42, v254, 37
	v_readlane_b32 s43, v254, 38
	s_waitcnt vmcnt(0)
	s_mov_b64 s[42:43], 0x80
	v_lshl_add_u64 v[10:11], v[10:11], 0, s[42:43]
	s_or_b32 m0, s100, 0x18000
	s_waitcnt vmcnt(4)
	s_barrier
	global_load_lds_dwordx4 v[10:11], off
	v_lshl_add_u64 v[10:11], v[12:13], 0, s[42:43]
	s_or_b32 m0, s100, 0x1a000
	s_nop 0
	global_load_lds_dwordx4 v[10:11], off
	v_lshl_add_u64 v[10:11], v[14:15], 0, s[42:43]
	s_or_b32 m0, s100, 0x8000
	s_nop 0
	global_load_lds_dwordx4 v[10:11], off
	v_lshl_add_u64 v[10:11], v[16:17], 0, s[42:43]
	s_or_b32 m0, s100, 0xa000
	s_nop 0
	global_load_lds_dwordx4 v[10:11], off
	s_or_b32 m0, s100, 0x1c000
	v_lshl_add_u64 v[10:11], v[18:19], 0, s[42:43]
	global_load_lds_dwordx4 v[10:11], off
	v_lshl_add_u64 v[10:11], v[20:21], 0, s[42:43]
	s_or_b32 m0, s100, 0x1e000
	v_and_b32_e32 v147, 15, v3
	global_load_lds_dwordx4 v[10:11], off
	v_bfe_u32 v148, v3, 4, 2
	v_lshlrev_b32_e32 v10, 4, v148
	v_lshlrev_b32_e32 v11, 6, v147
	v_lshlrev_b32_e32 v14, 2, v3
	v_or_b32_e32 v13, v10, v11
	v_and_b32_e32 v14, 32, v14
	s_mov_b32 s21, 0x10000
	v_bitop3_b32 v16, v13, s21, v14 bitop3:0xde
	s_mov_b32 s21, 0x14000
	s_and_b32 s14, s27, 63
	v_bitop3_b32 v15, v10, v14, v11 bitop3:0x36
	v_bitop3_b32 v17, v13, s21, v14 bitop3:0xde
	s_mov_b32 s21, 0x18000
	v_lshlrev_b32_e32 v11, 6, v3
	s_lshl_b32 s14, s14, 19
	s_mov_b32 s15, s40
	v_bitop3_b32 v18, v13, s21, v14 bitop3:0xde
	s_mov_b32 s21, 0x1c000
	v_and_b32_e32 v11, 0x3c0, v11
	v_bitop3_b32 v13, v13, s21, v14 bitop3:0xde
	v_bitop3_b32 v14, v11, v14, v10 bitop3:0x36
	v_lshl_add_u64 v[10:11], s[14:15], 0, v[136:137]
	v_readlane_b32 s41, v254, 36
	s_and_b32 s40, s33, 0xffffff00
	v_lshl_add_u64 v[10:11], v[10:11], 0, v[8:9]
	s_ashr_i32 s41, s40, 31
	v_lshl_add_u64 v[138:139], s[12:13], 0, v[10:11]
	v_lshl_add_u64 v[10:11], s[14:15], 0, v[132:133]
	s_lshl_b64 s[40:41], s[40:41], 11
	v_lshl_add_u64 v[10:11], v[10:11], 0, v[6:7]
	v_lshl_add_u64 v[140:141], s[12:13], 0, v[10:11]
	v_lshl_add_u64 v[10:11], s[40:41], 0, v[132:133]
	v_lshl_add_u64 v[6:7], v[10:11], 0, v[6:7]
	v_bfe_u32 v146, v3, 6, 2
	s_waitcnt vmcnt(6)
	v_lshlrev_b32_e32 v149, 6, v5
	v_lshlrev_b32_e32 v5, 13, v5
	v_lshl_add_u64 v[142:143], s[4:5], 0, v[6:7]
	v_lshl_add_u64 v[6:7], s[40:41], 0, v[136:137]
	v_lshlrev_b32_e32 v12, 12, v146
	v_or_b32_e32 v19, 0x800, v5
	v_or_b32_e32 v20, 0x1000, v5
	v_or_b32_e32 v21, 0x1800, v5
	v_lshl_add_u64 v[6:7], v[6:7], 0, v[8:9]
	v_lshl_add_u64 v[144:145], s[4:5], 0, v[6:7]
	s_mov_b32 s14, -2
	s_mov_b64 s[12:13], 0
	v_add_u32_e32 v171, v16, v12
	v_add_u32_e32 v156, v15, v5
	v_add_u32_e32 v155, v14, v19
	v_add_u32_e32 v154, v14, v20
	v_add_u32_e32 v153, v14, v21
	v_add_u32_e32 v168, v17, v12
	v_add_u32_e32 v161, v18, v12
	v_add_u32_e32 v158, v13, v12
	s_mov_b64 s[40:41], 0xc6a0100
	s_mov_b64 s[42:43], 0xc6e0100
	s_mov_b64 s[44:45], 0xc6a0180
	s_mov_b64 s[46:47], 0xc6e0180
	s_barrier
	ds_read_b128 v[174:177], v171
	ds_read_b128 v[178:181], v171 offset:1024
	ds_read_b128 v[182:185], v171 offset:2048
	ds_read_b128 v[186:189], v171 offset:3072
	v_lshl_add_u64 v[222:223], v[140:141], 0, s[12:13]
	v_lshl_add_u64 v[226:227], v[222:223], 0, s[34:35]
	s_or_b32 m0, s100, 0xc000
	v_lshl_add_u64 v[236:237], v[138:139], 0, s[12:13]
	ds_read_b128 v[190:193], v156
	ds_read_b128 v[194:197], v156 offset:1024
	ds_read_b128 v[198:201], v155
	ds_read_b128 v[202:205], v155 offset:1024
	ds_read_b128 v[206:209], v154
	ds_read_b128 v[210:213], v154 offset:1024
	ds_read_b128 v[214:217], v153
	ds_read_b128 v[218:221], v153 offset:1024
	global_load_lds_dwordx4 v[226:227], off
	s_or_b32 m0, s100, 0xe000
	v_lshl_add_u64 v[226:227], v[236:237], 0, s[34:35]
	global_load_lds_dwordx4 v[226:227], off
	s_waitcnt lgkmcnt(8)
	s_barrier
	s_waitcnt lgkmcnt(0)
	v_mfma_f32_16x16x32_f16 v[128:131], v[190:193], v[174:177], 0
	v_mfma_f32_16x16x32_f16 v[124:127], v[190:193], v[182:185], 0
	v_mfma_f32_16x16x32_f16 v[120:123], v[198:201], v[174:177], 0
	v_mfma_f32_16x16x32_f16 v[116:119], v[198:201], v[182:185], 0
	v_mfma_f32_16x16x32_f16 v[112:115], v[206:209], v[174:177], 0
	v_mfma_f32_16x16x32_f16 v[108:111], v[206:209], v[182:185], 0
	v_mfma_f32_16x16x32_f16 v[104:107], v[214:217], v[174:177], 0
	v_mfma_f32_16x16x32_f16 v[100:103], v[214:217], v[182:185], 0
	v_mfma_f32_16x16x32_f16 v[128:131], v[194:197], v[178:181], v[128:131]
	v_mfma_f32_16x16x32_f16 v[124:127], v[194:197], v[186:189], v[124:127]
	v_mfma_f32_16x16x32_f16 v[120:123], v[202:205], v[178:181], v[120:123]
	v_mfma_f32_16x16x32_f16 v[116:119], v[202:205], v[186:189], v[116:119]
	v_mfma_f32_16x16x32_f16 v[112:115], v[210:213], v[178:181], v[112:115]
	v_mfma_f32_16x16x32_f16 v[108:111], v[210:213], v[186:189], v[108:111]
	v_mfma_f32_16x16x32_f16 v[104:107], v[218:221], v[178:181], v[104:107]
	v_mfma_f32_16x16x32_f16 v[100:103], v[218:221], v[186:189], v[100:103]
	s_barrier
	v_lshl_add_u64 v[246:247], v[142:143], 0, s[12:13]
	v_lshl_add_u64 v[248:249], v[246:247], 0, s[40:41]
	s_or_b32 m0, s100, 0x10000
	ds_read_b128 v[226:229], v168
	ds_read_b128 v[230:233], v168 offset:1024
	ds_read_b128 v[238:241], v168 offset:2048
	ds_read_b128 v[242:245], v168 offset:3072
	global_load_lds_dwordx4 v[248:249], off
	v_lshl_add_u64 v[248:249], v[144:145], 0, s[12:13]
	s_or_b32 m0, s100, 0x12000
	v_lshl_add_u64 v[250:251], v[248:249], 0, s[40:41]
	global_load_lds_dwordx4 v[250:251], off
	s_barrier
; #define LDA8(dst, b, h) _Pragma("unroll") for (int m = 0; m < 4; ++m) _Pragma("unroll") for (int k = 0; k < 2; ++k) \
;     dst[m][k] = *(const bf16x8*)((const char*)SA8(b, h) + lds_byte8(wr * 64 + m * 16 + fr, k * 32 + fq * 8))
; #define LDB8(dst, b, h) _Pragma("unroll") for (int n = 0; n < 2; ++n) _Pragma("unroll") for (int k = 0; k < 2; ++k) \
;     dst[n][k] = *(const bf16x8*)((const char*)SB8(b, h) + lds_byte8(wc * 32 + n * 16 + fr, k * 32 + fq * 8))
; #define WAIT_V8(n) asm volatile("s_waitcnt vmcnt(" #n ")" ::: "memory")
; #define WAIT_L8(n) asm volatile("s_waitcnt lgkmcnt(" #n ")" ::: "memory")
; #define BAR8 __builtin_amdgcn_s_barrier()
; #define SCHED8 __builtin_amdgcn_sched_barrier(0)
;     ...
;     BAR8; WAIT_L8(0); MMA8(0, 1, At, B1); BAR8;
;     LDA8(At, 0, 1); STAGE8(SA8(0, 0), A, lda, brow, tt + 2);
;     BAR8; WAIT_L8(0); MMA8(1, 0, At, B0); BAR8; SCHED8;
;     STAGE8(SB8(0, 1), Bt, K, bcol + 128, tt + 2);
;     WAIT_V8(6); BAR8; MMA8(1, 1, At, B1); BAR8;
;     LDB8(B0, 1, 0); SCHED8; LDA8(At, 1, 0); STAGE8(SA8(0, 1), A, lda, brow + 128, tt + 2);
;     WAIT_L8(8); BAR8; WAIT_L8(0); MMA8(0, 0, At, B0); BAR8; SCHED8;
	s_waitcnt lgkmcnt(0)
	v_mfma_f32_16x16x32_f16 v[96:99], v[190:193], v[226:229], 0
	v_mfma_f32_16x16x32_f16 v[92:95], v[190:193], v[238:241], 0
	v_mfma_f32_16x16x32_f16 v[88:91], v[198:201], v[226:229], 0
	v_mfma_f32_16x16x32_f16 v[84:87], v[198:201], v[238:241], 0
	v_mfma_f32_16x16x32_f16 v[80:83], v[206:209], v[226:229], 0
	v_mfma_f32_16x16x32_f16 v[76:79], v[206:209], v[238:241], 0
	v_mfma_f32_16x16x32_f16 v[72:75], v[214:217], v[226:229], 0
	v_mfma_f32_16x16x32_f16 v[68:71], v[214:217], v[238:241], 0
	v_mfma_f32_16x16x32_f16 v[96:99], v[194:197], v[230:233], v[96:99]
	v_mfma_f32_16x16x32_f16 v[92:95], v[194:197], v[242:245], v[92:95]
	v_mfma_f32_16x16x32_f16 v[88:91], v[202:205], v[230:233], v[88:91]
	v_mfma_f32_16x16x32_f16 v[84:87], v[202:205], v[242:245], v[84:87]
	v_mfma_f32_16x16x32_f16 v[80:83], v[210:213], v[230:233], v[80:83]
	v_mfma_f32_16x16x32_f16 v[76:79], v[210:213], v[242:245], v[76:79]
	v_mfma_f32_16x16x32_f16 v[72:75], v[218:221], v[230:233], v[72:75]
	v_mfma_f32_16x16x32_f16 v[68:71], v[218:221], v[242:245], v[68:71]
	v_lshl_add_u64 v[250:251], v[222:223], 0, s[10:11]
	s_mov_b32 m0, s100
	s_barrier
	ds_read_b128 v[190:193], v156 offset:16384
	ds_read_b128 v[194:197], v156 offset:17408
	ds_read_b128 v[198:201], v155 offset:16384
	ds_read_b128 v[202:205], v155 offset:17408
	ds_read_b128 v[206:209], v154 offset:16384
	ds_read_b128 v[210:213], v154 offset:17408
	ds_read_b128 v[214:217], v153 offset:16384
	ds_read_b128 v[218:221], v153 offset:17408
	global_load_lds_dwordx4 v[250:251], off
	s_or_b32 m0, s100, 0x2000
	v_lshl_add_u64 v[250:251], v[236:237], 0, s[10:11]
	global_load_lds_dwordx4 v[250:251], off
	s_barrier
	s_waitcnt lgkmcnt(0)
	v_mfma_f32_16x16x32_f16 v[64:67], v[190:193], v[174:177], 0
	v_mfma_f32_16x16x32_f16 v[60:63], v[190:193], v[182:185], 0
	v_mfma_f32_16x16x32_f16 v[56:59], v[198:201], v[174:177], 0
	v_mfma_f32_16x16x32_f16 v[52:55], v[198:201], v[182:185], 0
	v_mfma_f32_16x16x32_f16 v[48:51], v[206:209], v[174:177], 0
	v_mfma_f32_16x16x32_f16 v[44:47], v[206:209], v[182:185], 0
	v_mfma_f32_16x16x32_f16 v[40:43], v[214:217], v[174:177], 0
	v_mfma_f32_16x16x32_f16 v[36:39], v[214:217], v[182:185], 0
	v_mfma_f32_16x16x32_f16 v[64:67], v[194:197], v[178:181], v[64:67]
	v_mfma_f32_16x16x32_f16 v[60:63], v[194:197], v[186:189], v[60:63]
	v_mfma_f32_16x16x32_f16 v[56:59], v[202:205], v[178:181], v[56:59]
	v_mfma_f32_16x16x32_f16 v[52:55], v[202:205], v[186:189], v[52:55]
	v_mfma_f32_16x16x32_f16 v[48:51], v[210:213], v[178:181], v[48:51]
	v_mfma_f32_16x16x32_f16 v[44:47], v[210:213], v[186:189], v[44:47]
	v_mfma_f32_16x16x32_f16 v[40:43], v[218:221], v[178:181], v[40:43]
	v_mfma_f32_16x16x32_f16 v[36:39], v[218:221], v[186:189], v[36:39]
	s_barrier
	s_or_b32 m0, s100, 0x14000
	v_lshl_add_u64 v[174:175], v[246:247], 0, s[42:43]
	global_load_lds_dwordx4 v[174:175], off
	s_or_b32 m0, s100, 0x16000
	v_lshl_add_u64 v[174:175], v[248:249], 0, s[42:43]
	global_load_lds_dwordx4 v[174:175], off
	s_waitcnt vmcnt(6)
	s_barrier
	v_mfma_f32_16x16x32_f16 v[32:35], v[190:193], v[226:229], 0
	v_mfma_f32_16x16x32_f16 v[28:31], v[190:193], v[238:241], 0
	v_mfma_f32_16x16x32_f16 v[24:27], v[198:201], v[226:229], 0
	v_mfma_f32_16x16x32_f16 v[20:23], v[198:201], v[238:241], 0
	v_mfma_f32_16x16x32_f16 v[16:19], v[206:209], v[226:229], 0
	v_mfma_f32_16x16x32_f16 v[12:15], v[206:209], v[238:241], 0
	v_mfma_f32_16x16x32_f16 v[8:11], v[214:217], v[226:229], 0
	v_mfma_f32_16x16x32_f16 v[4:7], v[214:217], v[238:241], 0
	v_mfma_f32_16x16x32_f16 v[32:35], v[194:197], v[230:233], v[32:35]
	v_mfma_f32_16x16x32_f16 v[28:31], v[194:197], v[242:245], v[28:31]
	v_mfma_f32_16x16x32_f16 v[24:27], v[202:205], v[230:233], v[24:27]
	v_mfma_f32_16x16x32_f16 v[20:23], v[202:205], v[242:245], v[20:23]
	v_mfma_f32_16x16x32_f16 v[16:19], v[210:213], v[230:233], v[16:19]
	v_mfma_f32_16x16x32_f16 v[12:15], v[210:213], v[242:245], v[12:15]
	v_mfma_f32_16x16x32_f16 v[8:11], v[218:221], v[230:233], v[8:11]
	v_mfma_f32_16x16x32_f16 v[4:7], v[218:221], v[242:245], v[4:7]
	s_barrier
	ds_read_b128 v[174:177], v161
	ds_read_b128 v[178:181], v161 offset:1024
	ds_read_b128 v[182:185], v161 offset:2048
	ds_read_b128 v[186:189], v161 offset:3072
	v_lshl_add_u64 v[226:227], v[222:223], 0, s[18:19]
	s_or_b32 m0, s100, 0x4000
	ds_read_b128 v[190:193], v156 offset:32768
	ds_read_b128 v[194:197], v156 offset:33792
	ds_read_b128 v[198:201], v155 offset:32768
	ds_read_b128 v[202:205], v155 offset:33792
	ds_read_b128 v[206:209], v154 offset:32768
	ds_read_b128 v[210:213], v154 offset:33792
	ds_read_b128 v[214:217], v153 offset:32768
	ds_read_b128 v[218:221], v153 offset:33792
	global_load_lds_dwordx4 v[226:227], off
	s_or_b32 m0, s100, 0x6000
	v_lshl_add_u64 v[226:227], v[236:237], 0, s[18:19]
	global_load_lds_dwordx4 v[226:227], off
	s_waitcnt lgkmcnt(8)
	s_barrier
; #define LDA8(dst, b, h) _Pragma("unroll") for (int m = 0; m < 4; ++m) _Pragma("unroll") for (int k = 0; k < 2; ++k) \
;     dst[m][k] = *(const bf16x8*)((const char*)SA8(b, h) + lds_byte8(wr * 64 + m * 16 + fr, k * 32 + fq * 8))
; #define LDB8(dst, b, h) _Pragma("unroll") for (int n = 0; n < 2; ++n) _Pragma("unroll") for (int k = 0; k < 2; ++k) \
;     dst[n][k] = *(const bf16x8*)((const char*)SB8(b, h) + lds_byte8(wc * 32 + n * 16 + fr, k * 32 + fq * 8))
; #define WAIT_V8(n) asm volatile("s_waitcnt vmcnt(" #n ")" ::: "memory")
; #define WAIT_L8(n) asm volatile("s_waitcnt lgkmcnt(" #n ")" ::: "memory")
; #define BAR8 __builtin_amdgcn_s_barrier()
; #define SCHED8 __builtin_amdgcn_sched_barrier(0)
;     ...
;     WAIT_L8(8); BAR8; WAIT_L8(0); MMA8(0, 0, At, B0); BAR8; SCHED8;
;     LDB8(B1, 1, 1); STAGE8(SB8(1, 0), Bt, K, bcol, tt + 3);
;     BAR8; WAIT_L8(0); MMA8(0, 1, At, B1); BAR8;
;     LDA8(At, 1, 1); STAGE8(SA8(1, 0), A, lda, brow, tt + 3);
;     BAR8; WAIT_L8(0); MMA8(1, 0, At, B0); BAR8; SCHED8;
;     STAGE8(SB8(1, 1), Bt, K, bcol + 128, tt + 3);
;     WAIT_V8(6); BAR8; MMA8(1, 1, At, B1); BAR8;
	s_waitcnt lgkmcnt(0)
	v_mfma_f32_16x16x32_f16 v[128:131], v[190:193], v[174:177], v[128:131]
	v_mfma_f32_16x16x32_f16 v[124:127], v[190:193], v[182:185], v[124:127]
	v_mfma_f32_16x16x32_f16 v[120:123], v[198:201], v[174:177], v[120:123]
	v_mfma_f32_16x16x32_f16 v[116:119], v[198:201], v[182:185], v[116:119]
	v_mfma_f32_16x16x32_f16 v[112:115], v[206:209], v[174:177], v[112:115]
	v_mfma_f32_16x16x32_f16 v[108:111], v[206:209], v[182:185], v[108:111]
	v_mfma_f32_16x16x32_f16 v[104:107], v[214:217], v[174:177], v[104:107]
	v_mfma_f32_16x16x32_f16 v[100:103], v[214:217], v[182:185], v[100:103]
	v_mfma_f32_16x16x32_f16 v[128:131], v[194:197], v[178:181], v[128:131]
	v_mfma_f32_16x16x32_f16 v[124:127], v[194:197], v[186:189], v[124:127]
	v_mfma_f32_16x16x32_f16 v[120:123], v[202:205], v[178:181], v[120:123]
	v_mfma_f32_16x16x32_f16 v[116:119], v[202:205], v[186:189], v[116:119]
	v_mfma_f32_16x16x32_f16 v[112:115], v[210:213], v[178:181], v[112:115]
	v_mfma_f32_16x16x32_f16 v[108:111], v[210:213], v[186:189], v[108:111]
	v_mfma_f32_16x16x32_f16 v[104:107], v[218:221], v[178:181], v[104:107]
	v_mfma_f32_16x16x32_f16 v[100:103], v[218:221], v[186:189], v[100:103]
	s_barrier
	v_lshl_add_u64 v[250:251], v[246:247], 0, s[44:45]
	s_or_b32 m0, s100, 0x18000
	ds_read_b128 v[226:229], v158
	ds_read_b128 v[230:233], v158 offset:1024
	ds_read_b128 v[238:241], v158 offset:2048
	ds_read_b128 v[242:245], v158 offset:3072
	global_load_lds_dwordx4 v[250:251], off
	s_or_b32 m0, s100, 0x1a000
	v_lshl_add_u64 v[250:251], v[248:249], 0, s[44:45]
	global_load_lds_dwordx4 v[250:251], off
	s_barrier
	s_waitcnt lgkmcnt(0)
	v_mfma_f32_16x16x32_f16 v[96:99], v[190:193], v[226:229], v[96:99]
	v_mfma_f32_16x16x32_f16 v[92:95], v[190:193], v[238:241], v[92:95]
	v_mfma_f32_16x16x32_f16 v[88:91], v[198:201], v[226:229], v[88:91]
	v_mfma_f32_16x16x32_f16 v[84:87], v[198:201], v[238:241], v[84:87]
	v_mfma_f32_16x16x32_f16 v[80:83], v[206:209], v[226:229], v[80:83]
	v_mfma_f32_16x16x32_f16 v[76:79], v[206:209], v[238:241], v[76:79]
	v_mfma_f32_16x16x32_f16 v[72:75], v[214:217], v[226:229], v[72:75]
	v_mfma_f32_16x16x32_f16 v[68:71], v[214:217], v[238:241], v[68:71]
	v_mfma_f32_16x16x32_f16 v[96:99], v[194:197], v[230:233], v[96:99]
	v_mfma_f32_16x16x32_f16 v[92:95], v[194:197], v[242:245], v[92:95]
	v_mfma_f32_16x16x32_f16 v[88:91], v[202:205], v[230:233], v[88:91]
	v_mfma_f32_16x16x32_f16 v[84:87], v[202:205], v[242:245], v[84:87]
	v_mfma_f32_16x16x32_f16 v[80:83], v[210:213], v[230:233], v[80:83]
	v_mfma_f32_16x16x32_f16 v[76:79], v[210:213], v[242:245], v[76:79]
	v_mfma_f32_16x16x32_f16 v[72:75], v[218:221], v[230:233], v[72:75]
	v_mfma_f32_16x16x32_f16 v[68:71], v[218:221], v[242:245], v[68:71]
	v_lshl_add_u64 v[222:223], v[222:223], 0, s[22:23]
	s_or_b32 m0, s100, 0x8000
	s_barrier
	ds_read_b128 v[190:193], v156 offset:49152
	ds_read_b128 v[194:197], v156 offset:50176
	ds_read_b128 v[198:201], v155 offset:49152
	ds_read_b128 v[202:205], v155 offset:50176
	ds_read_b128 v[206:209], v154 offset:49152
	ds_read_b128 v[210:213], v154 offset:50176
	ds_read_b128 v[214:217], v153 offset:49152
	ds_read_b128 v[218:221], v153 offset:50176
	global_load_lds_dwordx4 v[222:223], off
	s_or_b32 m0, s100, 0xa000
	v_lshl_add_u64 v[222:223], v[236:237], 0, s[22:23]
	global_load_lds_dwordx4 v[222:223], off
	s_barrier
	s_waitcnt lgkmcnt(0)
	v_mfma_f32_16x16x32_f16 v[64:67], v[190:193], v[174:177], v[64:67]
	v_mfma_f32_16x16x32_f16 v[60:63], v[190:193], v[182:185], v[60:63]
	v_mfma_f32_16x16x32_f16 v[56:59], v[198:201], v[174:177], v[56:59]
	v_mfma_f32_16x16x32_f16 v[52:55], v[198:201], v[182:185], v[52:55]
	v_mfma_f32_16x16x32_f16 v[48:51], v[206:209], v[174:177], v[48:51]
	v_mfma_f32_16x16x32_f16 v[44:47], v[206:209], v[182:185], v[44:47]
	v_mfma_f32_16x16x32_f16 v[40:43], v[214:217], v[174:177], v[40:43]
	v_mfma_f32_16x16x32_f16 v[36:39], v[214:217], v[182:185], v[36:39]
	v_mfma_f32_16x16x32_f16 v[64:67], v[194:197], v[178:181], v[64:67]
	v_mfma_f32_16x16x32_f16 v[60:63], v[194:197], v[186:189], v[60:63]
	v_mfma_f32_16x16x32_f16 v[56:59], v[202:205], v[178:181], v[56:59]
	v_mfma_f32_16x16x32_f16 v[52:55], v[202:205], v[186:189], v[52:55]
	v_mfma_f32_16x16x32_f16 v[48:51], v[210:213], v[178:181], v[48:51]
	v_mfma_f32_16x16x32_f16 v[44:47], v[210:213], v[186:189], v[44:47]
	v_mfma_f32_16x16x32_f16 v[40:43], v[218:221], v[178:181], v[40:43]
	v_mfma_f32_16x16x32_f16 v[36:39], v[218:221], v[186:189], v[36:39]
	s_barrier
	s_or_b32 m0, s100, 0x1c000
	v_lshl_add_u64 v[174:175], v[246:247], 0, s[46:47]
	global_load_lds_dwordx4 v[174:175], off
	s_or_b32 m0, s100, 0x1e000
	v_lshl_add_u64 v[174:175], v[248:249], 0, s[46:47]
	global_load_lds_dwordx4 v[174:175], off
	s_waitcnt vmcnt(6)
	s_barrier
	v_mfma_f32_16x16x32_f16 v[32:35], v[190:193], v[226:229], v[32:35]
	v_mfma_f32_16x16x32_f16 v[28:31], v[190:193], v[238:241], v[28:31]
	v_mfma_f32_16x16x32_f16 v[24:27], v[198:201], v[226:229], v[24:27]
	v_mfma_f32_16x16x32_f16 v[20:23], v[198:201], v[238:241], v[20:23]
	v_mfma_f32_16x16x32_f16 v[16:19], v[206:209], v[226:229], v[16:19]
	v_mfma_f32_16x16x32_f16 v[12:15], v[206:209], v[238:241], v[12:15]
	v_mfma_f32_16x16x32_f16 v[8:11], v[214:217], v[226:229], v[8:11]
	v_mfma_f32_16x16x32_f16 v[4:7], v[214:217], v[238:241], v[4:7]
	v_mfma_f32_16x16x32_f16 v[32:35], v[194:197], v[230:233], v[32:35]
	v_mfma_f32_16x16x32_f16 v[28:31], v[194:197], v[242:245], v[28:31]
	v_mfma_f32_16x16x32_f16 v[24:27], v[202:205], v[230:233], v[24:27]
	v_mfma_f32_16x16x32_f16 v[20:23], v[202:205], v[242:245], v[20:23]
	v_mfma_f32_16x16x32_f16 v[16:19], v[210:213], v[230:233], v[16:19]
	v_mfma_f32_16x16x32_f16 v[12:15], v[210:213], v[242:245], v[12:15]
	v_mfma_f32_16x16x32_f16 v[8:11], v[218:221], v[230:233], v[8:11]
	v_mfma_f32_16x16x32_f16 v[4:7], v[218:221], v[242:245], v[4:7]
	s_add_i32 s14, s14, 2
	s_add_u32 s12, s12, 0x100
	s_addc_u32 s13, s13, 0
	s_cmp_lt_u32 s14, 12
	s_cbranch_scc0 .Lpk_exitb_4
	.p2align	6

; #define LDA8(dst, b, h) _Pragma("unroll") for (int m = 0; m < 4; ++m) _Pragma("unroll") for (int k = 0; k < 2; ++k) \
;     dst[m][k] = *(const bf16x8*)((const char*)SA8(b, h) + lds_byte8(wr * 64 + m * 16 + fr, k * 32 + fq * 8))
; #define LDB8(dst, b, h) _Pragma("unroll") for (int n = 0; n < 2; ++n) _Pragma("unroll") for (int k = 0; k < 2; ++k) \
;     dst[n][k] = *(const bf16x8*)((const char*)SB8(b, h) + lds_byte8(wc * 32 + n * 16 + fr, k * 32 + fq * 8))
; #define WAIT_V8(n) asm volatile("s_waitcnt vmcnt(" #n ")" ::: "memory")
; #define WAIT_L8(n) asm volatile("s_waitcnt lgkmcnt(" #n ")" ::: "memory")
; #define BAR8 __builtin_amdgcn_s_barrier()
; #define SCHED8 __builtin_amdgcn_sched_barrier(0)
;     ...
;   if (wr == 1) BAR8;
;   WAIT_V8(4); BAR8;
;   STAGE8(SB8(1, 0), Bt, K, bcol, 1); STAGE8(SA8(1, 0), A, lda, brow, 1); STAGE8(SB8(1, 1), Bt, K, bcol + 128, 1);
;   WAIT_V8(6); BAR8;
;   for (int tt = 0; tt < nt - 2; tt += 2) {
;     LDB8(B0, 0, 0); SCHED8; LDA8(At, 0, 0); STAGE8(SA8(1, 1), A, lda, brow + 128, tt + 1);
;     WAIT_L8(8); BAR8; WAIT_L8(0); MMA8(0, 0, At, B0); BAR8; SCHED8;
;     LDB8(B1, 0, 1); STAGE8(SB8(0, 0), Bt, K, bcol, tt + 2);
.LBB0_1151:
	s_or_b64 exec, exec, s[12:13]
	s_lshl_b32 s29, s20, 10
	s_and_b32 s36, s29, 0xfc0000
	s_mov_b64 s[38:39], 0x80
	v_lshl_add_u64 v[14:15], v[14:15], 0, s[38:39]
	s_or_b32 m0, s100, 0x18000
	s_waitcnt vmcnt(4)
	s_barrier
	global_load_lds_dwordx4 v[14:15], off
	v_lshl_add_u64 v[14:15], v[18:19], 0, s[38:39]
	s_or_b32 m0, s100, 0x1a000
	s_nop 0
	global_load_lds_dwordx4 v[14:15], off
	v_lshl_add_u64 v[14:15], v[20:21], 0, s[38:39]
	s_or_b32 m0, s100, 0x8000
	s_nop 0
	global_load_lds_dwordx4 v[14:15], off
	v_lshl_add_u64 v[14:15], v[22:23], 0, s[38:39]
	s_or_b32 m0, s100, 0xa000
	s_nop 0
	global_load_lds_dwordx4 v[14:15], off
	s_or_b32 m0, s100, 0x1c000
	v_lshl_add_u64 v[14:15], v[26:27], 0, s[38:39]
	global_load_lds_dwordx4 v[14:15], off
	v_lshl_add_u64 v[14:15], v[28:29], 0, s[38:39]
	s_or_b32 m0, s100, 0x1e000
	v_and_b32_e32 v147, 15, v3
	global_load_lds_dwordx4 v[14:15], off
	v_bfe_u32 v148, v3, 4, 2
	v_lshlrev_b32_e32 v14, 4, v148
	v_lshlrev_b32_e32 v15, 6, v147
	v_lshlrev_b32_e32 v18, 2, v3
	v_lshlrev_b64 v[136:137], 9, v[16:17]
	v_or_b32_e32 v17, v14, v15
	v_and_b32_e32 v18, 32, v18
	s_mov_b32 s29, 0x10000
	s_and_b32 s12, s21, 0xffffff00
	v_bitop3_b32 v20, v17, s29, v18 bitop3:0xde
	s_mov_b32 s29, 0x14000
	s_ashr_i32 s13, s12, 31
	v_readlane_b32 s40, v254, 35
	v_bitop3_b32 v19, v14, v18, v15 bitop3:0x36
	v_bitop3_b32 v21, v17, s29, v18 bitop3:0xde
	s_mov_b32 s29, 0x18000
	v_lshlrev_b32_e32 v15, 6, v3
	s_lshl_b64 s[12:13], s[12:13], 10
	s_mov_b32 s37, s40
	v_bitop3_b32 v22, v17, s29, v18 bitop3:0xde
	s_mov_b32 s29, 0x1c000
	v_and_b32_e32 v15, 0x3c0, v15
	v_bitop3_b32 v17, v17, s29, v18 bitop3:0xde
	v_bitop3_b32 v18, v15, v18, v14 bitop3:0x36
	v_lshl_add_u64 v[14:15], s[12:13], 0, v[6:7]
	v_lshl_add_u64 v[6:7], s[36:37], 0, v[6:7]
	v_lshl_add_u64 v[14:15], v[14:15], 0, v[8:9]
	v_lshl_add_u64 v[6:7], v[6:7], 0, v[8:9]
	v_bfe_u32 v146, v3, 6, 2
	s_waitcnt vmcnt(6)
	v_lshlrev_b32_e32 v149, 6, v5
	v_lshlrev_b32_e32 v5, 13, v5
	v_lshl_add_u64 v[138:139], s[4:5], 0, v[14:15]
	v_lshl_add_u64 v[14:15], s[12:13], 0, v[10:11]
	v_lshl_add_u64 v[142:143], s[2:3], 0, v[6:7]
	v_lshl_add_u64 v[6:7], s[36:37], 0, v[10:11]
	v_lshlrev_b64 v[134:135], 9, v[24:25]
	v_readlane_b32 s41, v254, 36
	v_readlane_b32 s42, v254, 37
	v_readlane_b32 s43, v254, 38
	v_lshlrev_b32_e32 v16, 12, v146
	v_or_b32_e32 v23, 0x800, v5
	v_or_b32_e32 v24, 0x1000, v5
	v_or_b32_e32 v25, 0x1800, v5
	v_lshl_add_u64 v[14:15], v[14:15], 0, v[12:13]
	v_lshl_add_u64 v[6:7], v[6:7], 0, v[12:13]
	v_lshl_add_u64 v[140:141], s[4:5], 0, v[14:15]
	v_lshl_add_u64 v[144:145], s[2:3], 0, v[6:7]
	s_mov_b32 s29, -2
	s_mov_b64 s[12:13], 0
	v_add_u32_e32 v171, v20, v16
	v_add_u32_e32 v156, v19, v5
	v_add_u32_e32 v155, v18, v23
	v_add_u32_e32 v154, v18, v24
	v_add_u32_e32 v153, v18, v25
	v_add_u32_e32 v167, v21, v16
	v_add_u32_e32 v160, v22, v16
	v_add_u32_e32 v158, v17, v16
	s_mov_b64 s[36:37], 0x3020080
	s_mov_b64 s[38:39], 0xc9a0100
	s_mov_b64 s[40:41], 0x3000100
	s_mov_b64 s[42:43], 0xc9c0100
	s_mov_b64 s[44:45], 0x3020100
	s_mov_b64 s[46:47], 0xc9a0180
	s_mov_b64 s[48:49], 0x3000180
	s_mov_b64 s[50:51], 0xc9c0180
	s_barrier
	ds_read_b128 v[174:177], v171
	ds_read_b128 v[178:181], v171 offset:1024
	ds_read_b128 v[182:185], v171 offset:2048
	ds_read_b128 v[186:189], v171 offset:3072
	v_lshl_add_u64 v[222:223], v[142:143], 0, s[12:13]
	v_lshl_add_u64 v[226:227], v[222:223], 0, s[36:37]
	s_or_b32 m0, s100, 0xc000
	v_lshl_add_u64 v[236:237], v[144:145], 0, s[12:13]
	ds_read_b128 v[190:193], v156
	ds_read_b128 v[194:197], v156 offset:1024
	ds_read_b128 v[198:201], v155
	ds_read_b128 v[202:205], v155 offset:1024
	ds_read_b128 v[206:209], v154
	ds_read_b128 v[210:213], v154 offset:1024
	ds_read_b128 v[214:217], v153
	ds_read_b128 v[218:221], v153 offset:1024
	global_load_lds_dwordx4 v[226:227], off
	s_or_b32 m0, s100, 0xe000
	v_lshl_add_u64 v[226:227], v[236:237], 0, s[36:37]
	global_load_lds_dwordx4 v[226:227], off
	s_waitcnt lgkmcnt(8)
	s_barrier
	s_waitcnt lgkmcnt(0)
	v_mfma_f32_16x16x32_bf16 v[128:131], v[190:193], v[174:177], 0
	v_mfma_f32_16x16x32_bf16 v[124:127], v[190:193], v[182:185], 0
	v_mfma_f32_16x16x32_bf16 v[120:123], v[198:201], v[174:177], 0
	v_mfma_f32_16x16x32_bf16 v[116:119], v[198:201], v[182:185], 0
	v_mfma_f32_16x16x32_bf16 v[112:115], v[206:209], v[174:177], 0
	v_mfma_f32_16x16x32_bf16 v[108:111], v[206:209], v[182:185], 0
	v_mfma_f32_16x16x32_bf16 v[104:107], v[214:217], v[174:177], 0
	v_mfma_f32_16x16x32_bf16 v[100:103], v[214:217], v[182:185], 0
	v_mfma_f32_16x16x32_bf16 v[128:131], v[194:197], v[178:181], v[128:131]
	v_mfma_f32_16x16x32_bf16 v[124:127], v[194:197], v[186:189], v[124:127]
	v_mfma_f32_16x16x32_bf16 v[120:123], v[202:205], v[178:181], v[120:123]
	v_mfma_f32_16x16x32_bf16 v[116:119], v[202:205], v[186:189], v[116:119]
	v_mfma_f32_16x16x32_bf16 v[112:115], v[210:213], v[178:181], v[112:115]
	v_mfma_f32_16x16x32_bf16 v[108:111], v[210:213], v[186:189], v[108:111]
	v_mfma_f32_16x16x32_bf16 v[104:107], v[218:221], v[178:181], v[104:107]
	v_mfma_f32_16x16x32_bf16 v[100:103], v[218:221], v[186:189], v[100:103]
	s_barrier
	v_lshl_add_u64 v[246:247], v[138:139], 0, s[12:13]
	v_lshl_add_u64 v[248:249], v[246:247], 0, s[38:39]
	s_or_b32 m0, s100, 0x10000
	ds_read_b128 v[226:229], v167
	ds_read_b128 v[230:233], v167 offset:1024
	ds_read_b128 v[238:241], v167 offset:2048
	ds_read_b128 v[242:245], v167 offset:3072
	global_load_lds_dwordx4 v[248:249], off
	v_lshl_add_u64 v[248:249], v[140:141], 0, s[12:13]
	s_or_b32 m0, s100, 0x12000
	v_lshl_add_u64 v[250:251], v[248:249], 0, s[38:39]
	global_load_lds_dwordx4 v[250:251], off
	s_barrier
; #define LDA8(dst, b, h) _Pragma("unroll") for (int m = 0; m < 4; ++m) _Pragma("unroll") for (int k = 0; k < 2; ++k) \
;     dst[m][k] = *(const bf16x8*)((const char*)SA8(b, h) + lds_byte8(wr * 64 + m * 16 + fr, k * 32 + fq * 8))
; #define LDB8(dst, b, h) _Pragma("unroll") for (int n = 0; n < 2; ++n) _Pragma("unroll") for (int k = 0; k < 2; ++k) \
;     dst[n][k] = *(const bf16x8*)((const char*)SB8(b, h) + lds_byte8(wc * 32 + n * 16 + fr, k * 32 + fq * 8))
; #define WAIT_V8(n) asm volatile("s_waitcnt vmcnt(" #n ")" ::: "memory")
; #define WAIT_L8(n) asm volatile("s_waitcnt lgkmcnt(" #n ")" ::: "memory")
; #define BAR8 __builtin_amdgcn_s_barrier()
; #define SCHED8 __builtin_amdgcn_sched_barrier(0)
;     ...
;     BAR8; WAIT_L8(0); MMA8(0, 1, At, B1); BAR8;
;     LDA8(At, 0, 1); STAGE8(SA8(0, 0), A, lda, brow, tt + 2);
;     BAR8; WAIT_L8(0); MMA8(1, 0, At, B0); BAR8; SCHED8;
;     STAGE8(SB8(0, 1), Bt, K, bcol + 128, tt + 2);
;     WAIT_V8(6); BAR8; MMA8(1, 1, At, B1); BAR8;
;     LDB8(B0, 1, 0); SCHED8; LDA8(At, 1, 0); STAGE8(SA8(0, 1), A, lda, brow + 128, tt + 2);
;     WAIT_L8(8); BAR8; WAIT_L8(0); MMA8(0, 0, At, B0); BAR8; SCHED8;
	s_waitcnt lgkmcnt(0)
	v_mfma_f32_16x16x32_bf16 v[96:99], v[190:193], v[226:229], 0
	v_mfma_f32_16x16x32_bf16 v[92:95], v[190:193], v[238:241], 0
	v_mfma_f32_16x16x32_bf16 v[88:91], v[198:201], v[226:229], 0
	v_mfma_f32_16x16x32_bf16 v[84:87], v[198:201], v[238:241], 0
	v_mfma_f32_16x16x32_bf16 v[80:83], v[206:209], v[226:229], 0
	v_mfma_f32_16x16x32_bf16 v[76:79], v[206:209], v[238:241], 0
	v_mfma_f32_16x16x32_bf16 v[72:75], v[214:217], v[226:229], 0
	v_mfma_f32_16x16x32_bf16 v[68:71], v[214:217], v[238:241], 0
	v_mfma_f32_16x16x32_bf16 v[96:99], v[194:197], v[230:233], v[96:99]
	v_mfma_f32_16x16x32_bf16 v[92:95], v[194:197], v[242:245], v[92:95]
	v_mfma_f32_16x16x32_bf16 v[88:91], v[202:205], v[230:233], v[88:91]
	v_mfma_f32_16x16x32_bf16 v[84:87], v[202:205], v[242:245], v[84:87]
	v_mfma_f32_16x16x32_bf16 v[80:83], v[210:213], v[230:233], v[80:83]
	v_mfma_f32_16x16x32_bf16 v[76:79], v[210:213], v[242:245], v[76:79]
	v_mfma_f32_16x16x32_bf16 v[72:75], v[218:221], v[230:233], v[72:75]
	v_mfma_f32_16x16x32_bf16 v[68:71], v[218:221], v[242:245], v[68:71]
	v_lshl_add_u64 v[250:251], v[222:223], 0, s[40:41]
	s_mov_b32 m0, s100
	s_barrier
	ds_read_b128 v[190:193], v156 offset:16384
	ds_read_b128 v[194:197], v156 offset:17408
	ds_read_b128 v[198:201], v155 offset:16384
	ds_read_b128 v[202:205], v155 offset:17408
	ds_read_b128 v[206:209], v154 offset:16384
	ds_read_b128 v[210:213], v154 offset:17408
	ds_read_b128 v[214:217], v153 offset:16384
	ds_read_b128 v[218:221], v153 offset:17408
	global_load_lds_dwordx4 v[250:251], off
	s_or_b32 m0, s100, 0x2000
	v_lshl_add_u64 v[250:251], v[236:237], 0, s[40:41]
	global_load_lds_dwordx4 v[250:251], off
	s_barrier
	s_waitcnt lgkmcnt(0)
	v_mfma_f32_16x16x32_bf16 v[64:67], v[190:193], v[174:177], 0
	v_mfma_f32_16x16x32_bf16 v[60:63], v[190:193], v[182:185], 0
	v_mfma_f32_16x16x32_bf16 v[56:59], v[198:201], v[174:177], 0
	v_mfma_f32_16x16x32_bf16 v[52:55], v[198:201], v[182:185], 0
	v_mfma_f32_16x16x32_bf16 v[48:51], v[206:209], v[174:177], 0
	v_mfma_f32_16x16x32_bf16 v[44:47], v[206:209], v[182:185], 0
	v_mfma_f32_16x16x32_bf16 v[40:43], v[214:217], v[174:177], 0
	v_mfma_f32_16x16x32_bf16 v[36:39], v[214:217], v[182:185], 0
	v_mfma_f32_16x16x32_bf16 v[64:67], v[194:197], v[178:181], v[64:67]
	v_mfma_f32_16x16x32_bf16 v[60:63], v[194:197], v[186:189], v[60:63]
	v_mfma_f32_16x16x32_bf16 v[56:59], v[202:205], v[178:181], v[56:59]
	v_mfma_f32_16x16x32_bf16 v[52:55], v[202:205], v[186:189], v[52:55]
	v_mfma_f32_16x16x32_bf16 v[48:51], v[210:213], v[178:181], v[48:51]
	v_mfma_f32_16x16x32_bf16 v[44:47], v[210:213], v[186:189], v[44:47]
	v_mfma_f32_16x16x32_bf16 v[40:43], v[218:221], v[178:181], v[40:43]
	v_mfma_f32_16x16x32_bf16 v[36:39], v[218:221], v[186:189], v[36:39]
	s_barrier
	s_or_b32 m0, s100, 0x14000
	v_lshl_add_u64 v[174:175], v[246:247], 0, s[42:43]
	global_load_lds_dwordx4 v[174:175], off
	s_or_b32 m0, s100, 0x16000
	v_lshl_add_u64 v[174:175], v[248:249], 0, s[42:43]
	global_load_lds_dwordx4 v[174:175], off
	s_waitcnt vmcnt(6)
	s_barrier
	v_mfma_f32_16x16x32_bf16 v[32:35], v[190:193], v[226:229], 0
	v_mfma_f32_16x16x32_bf16 v[28:31], v[190:193], v[238:241], 0
	v_mfma_f32_16x16x32_bf16 v[24:27], v[198:201], v[226:229], 0
	v_mfma_f32_16x16x32_bf16 v[20:23], v[198:201], v[238:241], 0
	v_mfma_f32_16x16x32_bf16 v[16:19], v[206:209], v[226:229], 0
	v_mfma_f32_16x16x32_bf16 v[12:15], v[206:209], v[238:241], 0
	v_mfma_f32_16x16x32_bf16 v[8:11], v[214:217], v[226:229], 0
	v_mfma_f32_16x16x32_bf16 v[4:7], v[214:217], v[238:241], 0
	v_mfma_f32_16x16x32_bf16 v[32:35], v[194:197], v[230:233], v[32:35]
	v_mfma_f32_16x16x32_bf16 v[28:31], v[194:197], v[242:245], v[28:31]
	v_mfma_f32_16x16x32_bf16 v[24:27], v[202:205], v[230:233], v[24:27]
	v_mfma_f32_16x16x32_bf16 v[20:23], v[202:205], v[242:245], v[20:23]
	v_mfma_f32_16x16x32_bf16 v[16:19], v[210:213], v[230:233], v[16:19]
	v_mfma_f32_16x16x32_bf16 v[12:15], v[210:213], v[242:245], v[12:15]
	v_mfma_f32_16x16x32_bf16 v[8:11], v[218:221], v[230:233], v[8:11]
	v_mfma_f32_16x16x32_bf16 v[4:7], v[218:221], v[242:245], v[4:7]
	s_barrier
	ds_read_b128 v[174:177], v160
	ds_read_b128 v[178:181], v160 offset:1024
	ds_read_b128 v[182:185], v160 offset:2048
	ds_read_b128 v[186:189], v160 offset:3072
	v_lshl_add_u64 v[226:227], v[222:223], 0, s[44:45]
	s_or_b32 m0, s100, 0x4000
	ds_read_b128 v[190:193], v156 offset:32768
	ds_read_b128 v[194:197], v156 offset:33792
	ds_read_b128 v[198:201], v155 offset:32768
	ds_read_b128 v[202:205], v155 offset:33792
	ds_read_b128 v[206:209], v154 offset:32768
	ds_read_b128 v[210:213], v154 offset:33792
	ds_read_b128 v[214:217], v153 offset:32768
	ds_read_b128 v[218:221], v153 offset:33792
	global_load_lds_dwordx4 v[226:227], off
	s_or_b32 m0, s100, 0x6000
	v_lshl_add_u64 v[226:227], v[236:237], 0, s[44:45]
	global_load_lds_dwordx4 v[226:227], off
	s_waitcnt lgkmcnt(8)
	s_barrier
; #define LDA8(dst, b, h) _Pragma("unroll") for (int m = 0; m < 4; ++m) _Pragma("unroll") for (int k = 0; k < 2; ++k) \
;     dst[m][k] = *(const bf16x8*)((const char*)SA8(b, h) + lds_byte8(wr * 64 + m * 16 + fr, k * 32 + fq * 8))
; #define LDB8(dst, b, h) _Pragma("unroll") for (int n = 0; n < 2; ++n) _Pragma("unroll") for (int k = 0; k < 2; ++k) \
;     dst[n][k] = *(const bf16x8*)((const char*)SB8(b, h) + lds_byte8(wc * 32 + n * 16 + fr, k * 32 + fq * 8))
; #define WAIT_V8(n) asm volatile("s_waitcnt vmcnt(" #n ")" ::: "memory")
; #define WAIT_L8(n) asm volatile("s_waitcnt lgkmcnt(" #n ")" ::: "memory")
; #define BAR8 __builtin_amdgcn_s_barrier()
; #define SCHED8 __builtin_amdgcn_sched_barrier(0)
;     ...
;     WAIT_L8(8); BAR8; WAIT_L8(0); MMA8(0, 0, At, B0); BAR8; SCHED8;
;     LDB8(B1, 1, 1); STAGE8(SB8(1, 0), Bt, K, bcol, tt + 3);
;     BAR8; WAIT_L8(0); MMA8(0, 1, At, B1); BAR8;
;     LDA8(At, 1, 1); STAGE8(SA8(1, 0), A, lda, brow, tt + 3);
;     BAR8; WAIT_L8(0); MMA8(1, 0, At, B0); BAR8; SCHED8;
;     STAGE8(SB8(1, 1), Bt, K, bcol + 128, tt + 3);
;     WAIT_V8(6); BAR8; MMA8(1, 1, At, B1); BAR8;
	s_waitcnt lgkmcnt(0)
	v_mfma_f32_16x16x32_bf16 v[128:131], v[190:193], v[174:177], v[128:131]
	v_mfma_f32_16x16x32_bf16 v[124:127], v[190:193], v[182:185], v[124:127]
	v_mfma_f32_16x16x32_bf16 v[120:123], v[198:201], v[174:177], v[120:123]
	v_mfma_f32_16x16x32_bf16 v[116:119], v[198:201], v[182:185], v[116:119]
	v_mfma_f32_16x16x32_bf16 v[112:115], v[206:209], v[174:177], v[112:115]
	v_mfma_f32_16x16x32_bf16 v[108:111], v[206:209], v[182:185], v[108:111]
	v_mfma_f32_16x16x32_bf16 v[104:107], v[214:217], v[174:177], v[104:107]
	v_mfma_f32_16x16x32_bf16 v[100:103], v[214:217], v[182:185], v[100:103]
	v_mfma_f32_16x16x32_bf16 v[128:131], v[194:197], v[178:181], v[128:131]
	v_mfma_f32_16x16x32_bf16 v[124:127], v[194:197], v[186:189], v[124:127]
	v_mfma_f32_16x16x32_bf16 v[120:123], v[202:205], v[178:181], v[120:123]
	v_mfma_f32_16x16x32_bf16 v[116:119], v[202:205], v[186:189], v[116:119]
	v_mfma_f32_16x16x32_bf16 v[112:115], v[210:213], v[178:181], v[112:115]
	v_mfma_f32_16x16x32_bf16 v[108:111], v[210:213], v[186:189], v[108:111]
	v_mfma_f32_16x16x32_bf16 v[104:107], v[218:221], v[178:181], v[104:107]
	v_mfma_f32_16x16x32_bf16 v[100:103], v[218:221], v[186:189], v[100:103]
	s_barrier
	v_lshl_add_u64 v[250:251], v[246:247], 0, s[46:47]
	s_or_b32 m0, s100, 0x18000
	ds_read_b128 v[226:229], v158
	ds_read_b128 v[230:233], v158 offset:1024
	ds_read_b128 v[238:241], v158 offset:2048
	ds_read_b128 v[242:245], v158 offset:3072
	global_load_lds_dwordx4 v[250:251], off
	s_or_b32 m0, s100, 0x1a000
	v_lshl_add_u64 v[250:251], v[248:249], 0, s[46:47]
	global_load_lds_dwordx4 v[250:251], off
	s_barrier
	s_waitcnt lgkmcnt(0)
	v_mfma_f32_16x16x32_bf16 v[96:99], v[190:193], v[226:229], v[96:99]
	v_mfma_f32_16x16x32_bf16 v[92:95], v[190:193], v[238:241], v[92:95]
	v_mfma_f32_16x16x32_bf16 v[88:91], v[198:201], v[226:229], v[88:91]
	v_mfma_f32_16x16x32_bf16 v[84:87], v[198:201], v[238:241], v[84:87]
	v_mfma_f32_16x16x32_bf16 v[80:83], v[206:209], v[226:229], v[80:83]
	v_mfma_f32_16x16x32_bf16 v[76:79], v[206:209], v[238:241], v[76:79]
	v_mfma_f32_16x16x32_bf16 v[72:75], v[214:217], v[226:229], v[72:75]
	v_mfma_f32_16x16x32_bf16 v[68:71], v[214:217], v[238:241], v[68:71]
	v_mfma_f32_16x16x32_bf16 v[96:99], v[194:197], v[230:233], v[96:99]
	v_mfma_f32_16x16x32_bf16 v[92:95], v[194:197], v[242:245], v[92:95]
	v_mfma_f32_16x16x32_bf16 v[88:91], v[202:205], v[230:233], v[88:91]
	v_mfma_f32_16x16x32_bf16 v[84:87], v[202:205], v[242:245], v[84:87]
	v_mfma_f32_16x16x32_bf16 v[80:83], v[210:213], v[230:233], v[80:83]
	v_mfma_f32_16x16x32_bf16 v[76:79], v[210:213], v[242:245], v[76:79]
	v_mfma_f32_16x16x32_bf16 v[72:75], v[218:221], v[230:233], v[72:75]
	v_mfma_f32_16x16x32_bf16 v[68:71], v[218:221], v[242:245], v[68:71]
	v_lshl_add_u64 v[222:223], v[222:223], 0, s[48:49]
	s_or_b32 m0, s100, 0x8000
	s_barrier
	ds_read_b128 v[190:193], v156 offset:49152
	ds_read_b128 v[194:197], v156 offset:50176
	ds_read_b128 v[198:201], v155 offset:49152
	ds_read_b128 v[202:205], v155 offset:50176
	ds_read_b128 v[206:209], v154 offset:49152
	ds_read_b128 v[210:213], v154 offset:50176
	ds_read_b128 v[214:217], v153 offset:49152
	ds_read_b128 v[218:221], v153 offset:50176
	global_load_lds_dwordx4 v[222:223], off
	s_or_b32 m0, s100, 0xa000
	v_lshl_add_u64 v[222:223], v[236:237], 0, s[48:49]
	global_load_lds_dwordx4 v[222:223], off
	s_barrier
	s_waitcnt lgkmcnt(0)
	v_mfma_f32_16x16x32_bf16 v[64:67], v[190:193], v[174:177], v[64:67]
	v_mfma_f32_16x16x32_bf16 v[60:63], v[190:193], v[182:185], v[60:63]
	v_mfma_f32_16x16x32_bf16 v[56:59], v[198:201], v[174:177], v[56:59]
	v_mfma_f32_16x16x32_bf16 v[52:55], v[198:201], v[182:185], v[52:55]
	v_mfma_f32_16x16x32_bf16 v[48:51], v[206:209], v[174:177], v[48:51]
	v_mfma_f32_16x16x32_bf16 v[44:47], v[206:209], v[182:185], v[44:47]
	v_mfma_f32_16x16x32_bf16 v[40:43], v[214:217], v[174:177], v[40:43]
	v_mfma_f32_16x16x32_bf16 v[36:39], v[214:217], v[182:185], v[36:39]
	v_mfma_f32_16x16x32_bf16 v[64:67], v[194:197], v[178:181], v[64:67]
	v_mfma_f32_16x16x32_bf16 v[60:63], v[194:197], v[186:189], v[60:63]
	v_mfma_f32_16x16x32_bf16 v[56:59], v[202:205], v[178:181], v[56:59]
	v_mfma_f32_16x16x32_bf16 v[52:55], v[202:205], v[186:189], v[52:55]
	v_mfma_f32_16x16x32_bf16 v[48:51], v[210:213], v[178:181], v[48:51]
	v_mfma_f32_16x16x32_bf16 v[44:47], v[210:213], v[186:189], v[44:47]
	v_mfma_f32_16x16x32_bf16 v[40:43], v[218:221], v[178:181], v[40:43]
	v_mfma_f32_16x16x32_bf16 v[36:39], v[218:221], v[186:189], v[36:39]
	s_barrier
	s_or_b32 m0, s100, 0x1c000
	v_lshl_add_u64 v[174:175], v[246:247], 0, s[50:51]
	global_load_lds_dwordx4 v[174:175], off
	s_or_b32 m0, s100, 0x1e000
	v_lshl_add_u64 v[174:175], v[248:249], 0, s[50:51]
	global_load_lds_dwordx4 v[174:175], off
	s_waitcnt vmcnt(6)
	s_barrier
	v_mfma_f32_16x16x32_bf16 v[32:35], v[190:193], v[226:229], v[32:35]
	v_mfma_f32_16x16x32_bf16 v[28:31], v[190:193], v[238:241], v[28:31]
	v_mfma_f32_16x16x32_bf16 v[24:27], v[198:201], v[226:229], v[24:27]
	v_mfma_f32_16x16x32_bf16 v[20:23], v[198:201], v[238:241], v[20:23]
	v_mfma_f32_16x16x32_bf16 v[16:19], v[206:209], v[226:229], v[16:19]
	v_mfma_f32_16x16x32_bf16 v[12:15], v[206:209], v[238:241], v[12:15]
	v_mfma_f32_16x16x32_bf16 v[8:11], v[214:217], v[226:229], v[8:11]
	v_mfma_f32_16x16x32_bf16 v[4:7], v[214:217], v[238:241], v[4:7]
	v_mfma_f32_16x16x32_bf16 v[32:35], v[194:197], v[230:233], v[32:35]
	v_mfma_f32_16x16x32_bf16 v[28:31], v[194:197], v[242:245], v[28:31]
	v_mfma_f32_16x16x32_bf16 v[24:27], v[202:205], v[230:233], v[24:27]
	v_mfma_f32_16x16x32_bf16 v[20:23], v[202:205], v[242:245], v[20:23]
	v_mfma_f32_16x16x32_bf16 v[16:19], v[210:213], v[230:233], v[16:19]
	v_mfma_f32_16x16x32_bf16 v[12:15], v[210:213], v[242:245], v[12:15]
	v_mfma_f32_16x16x32_bf16 v[8:11], v[218:221], v[230:233], v[8:11]
	v_mfma_f32_16x16x32_bf16 v[4:7], v[218:221], v[242:245], v[4:7]
	s_add_i32 s29, s29, 2
	s_add_u32 s12, s12, 0x100
	s_addc_u32 s13, s13, 0
	s_cmp_lt_u32 s29, 4
	s_cbranch_scc0 .Lpk_exitb_5
	.p2align	6

; DI int tid_opaque() { int t = threadIdx.x; asm volatile("" : "+v"(t)); return t; }
; #define WAIT_V8(n) asm volatile("s_waitcnt vmcnt(" #n ")" ::: "memory")
; #define BAR8 __builtin_amdgcn_s_barrier()
;   constexpr int HT = 128 * 64;
;   bf16_t* shm = (bf16_t*)smem;
;   const int t = tid_opaque();
;     ...
;   if (wr == 1) BAR8;
;   WAIT_V8(4); BAR8;
;   STAGE8(SB8(1, 0), Bt, K, bcol, 1); STAGE8(SA8(1, 0), A, lda, brow, 1); STAGE8(SB8(1, 1), Bt, K, bcol + 128, 1);
;   WAIT_V8(6); BAR8;
.LBB0_1258:
	s_or_b64 exec, exec, s[8:9]
	v_add_u32_e32 v0, v150, v0
	v_and_b32_e32 v0, 0xfffffc00, v0
	v_sub_u32_e32 v0, v150, v0
	v_lshrrev_b32_e32 v6, 4, v0
	v_add_u32_e32 v1, v3, v1
	v_bitop3_b32 v7, v6, v0, 32 bitop3:0x6c
	v_ashrrev_i32_e32 v0, 31, v0
	v_ashrrev_i32_e32 v1, 6, v1
	v_lshrrev_b32_e32 v0, 26, v0
	v_lshlrev_b32_e32 v6, 3, v1
	v_add_u32_e32 v0, v7, v0
	v_and_b32_e32 v6, -16, v6
	v_ashrrev_i32_e32 v0, 6, v0
	s_and_b32 s1, s12, 63
	s_and_b32 s8, s20, 0xffffff00
	v_add_u32_e32 v6, v0, v6
	v_mul_i32_i24_e32 v0, 64, v0
	s_lshl_b32 s12, s1, 19
	s_ashr_i32 s9, s8, 31
	s_ashr_i32 s1, s0, 31
	v_lshlrev_b32_e32 v1, 5, v1
	v_sub_u32_e32 v0, v7, v0
	v_mov_b32_e32 v13, 1
	s_lshl_b64 s[14:15], s[8:9], 11
	s_lshl_b64 s[8:9], s[0:1], 11
	v_and_b32_e32 v1, 32, v1
	v_ashrrev_i16_sdwa v0, v13, sext(v0) dst_sel:DWORD dst_unused:UNUSED_PAD src0_sel:DWORD src1_sel:BYTE_0
	s_add_u32 s8, s4, s8
	v_add_u32_sdwa v0, v1, sext(v0) dst_sel:DWORD dst_unused:UNUSED_PAD src0_sel:DWORD src1_sel:WORD_0
	v_ashrrev_i32_e32 v7, 31, v6
	v_readlane_b32 s40, v254, 35
	s_addc_u32 s9, s5, s9
	v_lshlrev_b64 v[132:133], 11, v[6:7]
	v_ashrrev_i32_e32 v1, 31, v0
	v_readlane_b32 s41, v254, 36
	v_lshl_add_u64 v[6:7], s[8:9], 0, v[132:133]
	v_lshlrev_b64 v[8:9], 1, v[0:1]
	s_mov_b32 s13, s40
	v_lshl_add_u64 v[6:7], v[6:7], 0, v[8:9]
	s_mov_b64 s[40:41], 0x80
	v_lshl_add_u64 v[6:7], v[6:7], 0, s[40:41]
	s_or_b32 m0, s100, 0x18000
	s_waitcnt vmcnt(4)
	s_barrier
	global_load_lds_dwordx4 v[6:7], off
	v_ashrrev_i32_e32 v6, 31, v152
	v_lshrrev_b32_e32 v6, 22, v6
	v_add_u32_e32 v6, v152, v6
	v_ashrrev_i32_e32 v7, 10, v6
	v_mul_i32_i24_e32 v6, 0x400, v7
	v_sub_u32_e32 v6, v152, v6
	v_lshrrev_b32_e32 v10, 4, v6
	v_bitop3_b32 v10, v10, v6, 32 bitop3:0x6c
	v_ashrrev_i32_e32 v11, 31, v10
	v_lshrrev_b32_e32 v11, 26, v11
	v_add_u32_e32 v11, v10, v11
	v_lshlrev_b32_e32 v6, 3, v7
	v_ashrrev_i32_e32 v12, 6, v11
	v_and_b32_e32 v11, 0xc0, v11
	v_and_b32_e32 v6, -16, v6
	v_lshlrev_b32_e32 v7, 5, v7
	v_sub_u32_e32 v10, v10, v11
	v_add_u32_e32 v6, v12, v6
	v_and_b32_e32 v7, 32, v7
	v_ashrrev_i16_sdwa v10, v13, sext(v10) dst_sel:DWORD dst_unused:UNUSED_PAD src0_sel:DWORD src1_sel:BYTE_0
	v_add_u32_sdwa v134, v7, sext(v10) dst_sel:DWORD dst_unused:UNUSED_PAD src0_sel:DWORD src1_sel:WORD_0
	v_ashrrev_i32_e32 v7, 31, v6
	v_lshlrev_b64 v[136:137], 11, v[6:7]
	v_ashrrev_i32_e32 v135, 31, v134
	v_lshl_add_u64 v[6:7], s[8:9], 0, v[136:137]
	v_lshlrev_b64 v[10:11], 1, v[134:135]
	s_or_b32 m0, s100, 0x1a000
	s_lshl_b32 s1, s27, 11
	v_lshl_add_u64 v[6:7], v[6:7], 0, v[10:11]
	s_waitcnt lgkmcnt(0)
	s_add_u32 s8, s2, s1
	v_lshl_add_u64 v[6:7], v[6:7], 0, s[40:41]
	s_addc_u32 s9, s3, 0
	global_load_lds_dwordx4 v[6:7], off
	v_lshl_add_u64 v[6:7], s[8:9], 0, v[132:133]
	v_lshl_add_u64 v[6:7], v[6:7], 0, v[8:9]
	s_or_b32 s36, s0, 0x80
	v_lshl_add_u64 v[6:7], v[6:7], 0, s[40:41]
	s_or_b32 m0, s100, 0x8000
	s_ashr_i32 s37, s36, 31
	global_load_lds_dwordx4 v[6:7], off
	v_lshl_add_u64 v[6:7], s[8:9], 0, v[136:137]
	s_lshl_b64 s[36:37], s[36:37], 11
	v_lshl_add_u64 v[6:7], v[6:7], 0, v[10:11]
	s_add_u32 s36, s4, s36
	v_lshl_add_u64 v[6:7], v[6:7], 0, s[40:41]
	s_addc_u32 s37, s5, s37
	s_or_b32 m0, s100, 0xa000
	s_nop 0
	global_load_lds_dwordx4 v[6:7], off
	v_lshl_add_u64 v[6:7], s[36:37], 0, v[132:133]
	v_lshl_add_u64 v[6:7], v[6:7], 0, v[8:9]
	v_lshl_add_u64 v[6:7], v[6:7], 0, s[40:41]
	s_or_b32 m0, s100, 0x1c000
	s_nop 0
	global_load_lds_dwordx4 v[6:7], off
	v_lshl_add_u64 v[6:7], s[36:37], 0, v[136:137]
	v_lshl_add_u64 v[6:7], v[6:7], 0, v[10:11]
	v_lshl_add_u64 v[6:7], v[6:7], 0, s[40:41]
	s_or_b32 m0, s100, 0x1e000
	v_and_b32_e32 v147, 15, v3
	global_load_lds_dwordx4 v[6:7], off
	v_bfe_u32 v148, v3, 4, 2
	v_lshlrev_b32_e32 v6, 4, v148
	v_lshlrev_b32_e32 v7, 6, v147
	v_lshlrev_b32_e32 v14, 2, v3
	v_or_b32_e32 v13, v6, v7
	v_and_b32_e32 v14, 32, v14
	s_mov_b32 s1, 0x10000
	v_bitop3_b32 v16, v13, s1, v14 bitop3:0xde
	s_mov_b32 s1, 0x14000
	v_bitop3_b32 v15, v6, v14, v7 bitop3:0x36
	v_bitop3_b32 v17, v13, s1, v14 bitop3:0xde
	s_mov_b32 s1, 0x18000
	v_lshlrev_b32_e32 v7, 6, v3
	v_bitop3_b32 v18, v13, s1, v14 bitop3:0xde
	s_mov_b32 s1, 0x1c000
	v_and_b32_e32 v7, 0x3c0, v7
	v_bitop3_b32 v13, v13, s1, v14 bitop3:0xde
	v_bitop3_b32 v14, v7, v14, v6 bitop3:0x36
	v_lshl_add_u64 v[6:7], s[12:13], 0, v[132:133]
	v_lshl_add_u64 v[6:7], v[6:7], 0, v[8:9]
	v_lshl_add_u64 v[138:139], s[2:3], 0, v[6:7]
	v_lshl_add_u64 v[6:7], s[12:13], 0, v[136:137]
	v_lshl_add_u64 v[6:7], v[6:7], 0, v[10:11]
	v_lshl_add_u64 v[140:141], s[2:3], 0, v[6:7]
	v_lshl_add_u64 v[6:7], s[14:15], 0, v[132:133]
	v_lshl_add_u64 v[6:7], v[6:7], 0, v[8:9]
	v_bfe_u32 v146, v3, 6, 2
	s_waitcnt vmcnt(6)
	v_lshlrev_b32_e32 v149, 6, v5
	v_lshlrev_b32_e32 v5, 13, v5
	v_lshl_add_u64 v[142:143], s[6:7], 0, v[6:7]
	v_lshl_add_u64 v[6:7], s[14:15], 0, v[136:137]
	v_readlane_b32 s42, v254, 37
	v_readlane_b32 s43, v254, 38
	v_lshlrev_b32_e32 v12, 12, v146
	v_or_b32_e32 v19, 0x800, v5
	v_or_b32_e32 v20, 0x1000, v5
	v_or_b32_e32 v21, 0x1800, v5
	v_lshl_add_u64 v[6:7], v[6:7], 0, v[10:11]
	v_lshl_add_u64 v[144:145], s[6:7], 0, v[6:7]
	s_mov_b32 s1, -2
	s_mov_b64 s[12:13], 0
	v_add_u32_e32 v171, v16, v12
	v_add_u32_e32 v161, v15, v5
	v_add_u32_e32 v160, v14, v19
	v_add_u32_e32 v159, v14, v20
	v_add_u32_e32 v158, v14, v21
	v_add_u32_e32 v169, v17, v12
	v_add_u32_e32 v163, v18, v12
	v_add_u32_e32 v162, v13, v12
	s_mov_b64 s[36:37], 0xcaa0100
	s_mov_b64 s[40:41], 0xcae0100
	s_mov_b64 s[42:43], 0xcaa0180
	s_mov_b64 s[44:45], 0xcae0180
	s_barrier
; #define LDA8(dst, b, h) _Pragma("unroll") for (int m = 0; m < 4; ++m) _Pragma("unroll") for (int k = 0; k < 2; ++k) \
;     dst[m][k] = *(const bf16x8*)((const char*)SA8(b, h) + lds_byte8(wr * 64 + m * 16 + fr, k * 32 + fq * 8))
; #define LDB8(dst, b, h) _Pragma("unroll") for (int n = 0; n < 2; ++n) _Pragma("unroll") for (int k = 0; k < 2; ++k) \
;     dst[n][k] = *(const bf16x8*)((const char*)SB8(b, h) + lds_byte8(wc * 32 + n * 16 + fr, k * 32 + fq * 8))
; #define WAIT_V8(n) asm volatile("s_waitcnt vmcnt(" #n ")" ::: "memory")
; #define WAIT_L8(n) asm volatile("s_waitcnt lgkmcnt(" #n ")" ::: "memory")
; #define BAR8 __builtin_amdgcn_s_barrier()
; #define SCHED8 __builtin_amdgcn_sched_barrier(0)
;     ...
;     LDB8(B0, 0, 0); SCHED8; LDA8(At, 0, 0); STAGE8(SA8(1, 1), A, lda, brow + 128, tt + 1);
;     WAIT_L8(8); BAR8; WAIT_L8(0); MMA8(0, 0, At, B0); BAR8; SCHED8;
;     LDB8(B1, 0, 1); STAGE8(SB8(0, 0), Bt, K, bcol, tt + 2);
;     BAR8; WAIT_L8(0); MMA8(0, 1, At, B1); BAR8;
;     LDA8(At, 0, 1); STAGE8(SA8(0, 0), A, lda, brow, tt + 2);
;     BAR8; WAIT_L8(0); MMA8(1, 0, At, B0); BAR8; SCHED8;
;     STAGE8(SB8(0, 1), Bt, K, bcol + 128, tt + 2);
;     WAIT_V8(6); BAR8; MMA8(1, 1, At, B1); BAR8;
	ds_read_b128 v[174:177], v171
	ds_read_b128 v[178:181], v171 offset:1024
	ds_read_b128 v[182:185], v171 offset:2048
	ds_read_b128 v[186:189], v171 offset:3072
	v_lshl_add_u64 v[222:223], v[138:139], 0, s[12:13]
	v_lshl_add_u64 v[226:227], v[222:223], 0, s[34:35]
	s_or_b32 m0, s100, 0xc000
	v_lshl_add_u64 v[236:237], v[140:141], 0, s[12:13]
	ds_read_b128 v[190:193], v161
	ds_read_b128 v[194:197], v161 offset:1024
	ds_read_b128 v[198:201], v160
	ds_read_b128 v[202:205], v160 offset:1024
	ds_read_b128 v[206:209], v159
	ds_read_b128 v[210:213], v159 offset:1024
	ds_read_b128 v[214:217], v158
	ds_read_b128 v[218:221], v158 offset:1024
	global_load_lds_dwordx4 v[226:227], off
	s_or_b32 m0, s100, 0xe000
	v_lshl_add_u64 v[226:227], v[236:237], 0, s[34:35]
	global_load_lds_dwordx4 v[226:227], off
	s_waitcnt lgkmcnt(8)
	s_barrier
	s_waitcnt lgkmcnt(0)
	v_mfma_f32_16x16x32_f16 v[128:131], v[190:193], v[174:177], 0
	v_mfma_f32_16x16x32_f16 v[124:127], v[190:193], v[182:185], 0
	v_mfma_f32_16x16x32_f16 v[120:123], v[198:201], v[174:177], 0
	v_mfma_f32_16x16x32_f16 v[116:119], v[198:201], v[182:185], 0
	v_mfma_f32_16x16x32_f16 v[112:115], v[206:209], v[174:177], 0
	v_mfma_f32_16x16x32_f16 v[108:111], v[206:209], v[182:185], 0
	v_mfma_f32_16x16x32_f16 v[104:107], v[214:217], v[174:177], 0
	v_mfma_f32_16x16x32_f16 v[100:103], v[214:217], v[182:185], 0
	v_mfma_f32_16x16x32_f16 v[128:131], v[194:197], v[178:181], v[128:131]
	v_mfma_f32_16x16x32_f16 v[124:127], v[194:197], v[186:189], v[124:127]
	v_mfma_f32_16x16x32_f16 v[120:123], v[202:205], v[178:181], v[120:123]
	v_mfma_f32_16x16x32_f16 v[116:119], v[202:205], v[186:189], v[116:119]
	v_mfma_f32_16x16x32_f16 v[112:115], v[210:213], v[178:181], v[112:115]
	v_mfma_f32_16x16x32_f16 v[108:111], v[210:213], v[186:189], v[108:111]
	v_mfma_f32_16x16x32_f16 v[104:107], v[218:221], v[178:181], v[104:107]
	v_mfma_f32_16x16x32_f16 v[100:103], v[218:221], v[186:189], v[100:103]
	s_barrier
	v_lshl_add_u64 v[246:247], v[142:143], 0, s[12:13]
	v_lshl_add_u64 v[248:249], v[246:247], 0, s[36:37]
	s_or_b32 m0, s100, 0x10000
	ds_read_b128 v[226:229], v169
	ds_read_b128 v[230:233], v169 offset:1024
	ds_read_b128 v[238:241], v169 offset:2048
	ds_read_b128 v[242:245], v169 offset:3072
	global_load_lds_dwordx4 v[248:249], off
	v_lshl_add_u64 v[248:249], v[144:145], 0, s[12:13]
	s_or_b32 m0, s100, 0x12000
	v_lshl_add_u64 v[250:251], v[248:249], 0, s[36:37]
	global_load_lds_dwordx4 v[250:251], off
	s_barrier
	s_waitcnt lgkmcnt(0)
	v_mfma_f32_16x16x32_f16 v[96:99], v[190:193], v[226:229], 0
	v_mfma_f32_16x16x32_f16 v[92:95], v[190:193], v[238:241], 0
	v_mfma_f32_16x16x32_f16 v[88:91], v[198:201], v[226:229], 0
	v_mfma_f32_16x16x32_f16 v[84:87], v[198:201], v[238:241], 0
	v_mfma_f32_16x16x32_f16 v[80:83], v[206:209], v[226:229], 0
	v_mfma_f32_16x16x32_f16 v[76:79], v[206:209], v[238:241], 0
	v_mfma_f32_16x16x32_f16 v[72:75], v[214:217], v[226:229], 0
	v_mfma_f32_16x16x32_f16 v[68:71], v[214:217], v[238:241], 0
	v_mfma_f32_16x16x32_f16 v[96:99], v[194:197], v[230:233], v[96:99]
	v_mfma_f32_16x16x32_f16 v[92:95], v[194:197], v[242:245], v[92:95]
	v_mfma_f32_16x16x32_f16 v[88:91], v[202:205], v[230:233], v[88:91]
	v_mfma_f32_16x16x32_f16 v[84:87], v[202:205], v[242:245], v[84:87]
	v_mfma_f32_16x16x32_f16 v[80:83], v[210:213], v[230:233], v[80:83]
	v_mfma_f32_16x16x32_f16 v[76:79], v[210:213], v[242:245], v[76:79]
	v_mfma_f32_16x16x32_f16 v[72:75], v[218:221], v[230:233], v[72:75]
	v_mfma_f32_16x16x32_f16 v[68:71], v[218:221], v[242:245], v[68:71]
	v_lshl_add_u64 v[250:251], v[222:223], 0, s[10:11]
	s_mov_b32 m0, s100
	s_barrier
	ds_read_b128 v[190:193], v161 offset:16384
	ds_read_b128 v[194:197], v161 offset:17408
	ds_read_b128 v[198:201], v160 offset:16384
	ds_read_b128 v[202:205], v160 offset:17408
	ds_read_b128 v[206:209], v159 offset:16384
	ds_read_b128 v[210:213], v159 offset:17408
	ds_read_b128 v[214:217], v158 offset:16384
	ds_read_b128 v[218:221], v158 offset:17408
	global_load_lds_dwordx4 v[250:251], off
	s_or_b32 m0, s100, 0x2000
	v_lshl_add_u64 v[250:251], v[236:237], 0, s[10:11]
	global_load_lds_dwordx4 v[250:251], off
	s_barrier
	s_waitcnt lgkmcnt(0)
	v_mfma_f32_16x16x32_f16 v[64:67], v[190:193], v[174:177], 0
	v_mfma_f32_16x16x32_f16 v[60:63], v[190:193], v[182:185], 0
	v_mfma_f32_16x16x32_f16 v[56:59], v[198:201], v[174:177], 0
	v_mfma_f32_16x16x32_f16 v[52:55], v[198:201], v[182:185], 0
	v_mfma_f32_16x16x32_f16 v[48:51], v[206:209], v[174:177], 0
	v_mfma_f32_16x16x32_f16 v[44:47], v[206:209], v[182:185], 0
	v_mfma_f32_16x16x32_f16 v[40:43], v[214:217], v[174:177], 0
	v_mfma_f32_16x16x32_f16 v[36:39], v[214:217], v[182:185], 0
	v_mfma_f32_16x16x32_f16 v[64:67], v[194:197], v[178:181], v[64:67]
	v_mfma_f32_16x16x32_f16 v[60:63], v[194:197], v[186:189], v[60:63]
	v_mfma_f32_16x16x32_f16 v[56:59], v[202:205], v[178:181], v[56:59]
	v_mfma_f32_16x16x32_f16 v[52:55], v[202:205], v[186:189], v[52:55]
	v_mfma_f32_16x16x32_f16 v[48:51], v[210:213], v[178:181], v[48:51]
	v_mfma_f32_16x16x32_f16 v[44:47], v[210:213], v[186:189], v[44:47]
	v_mfma_f32_16x16x32_f16 v[40:43], v[218:221], v[178:181], v[40:43]
	v_mfma_f32_16x16x32_f16 v[36:39], v[218:221], v[186:189], v[36:39]
	s_barrier
	s_or_b32 m0, s100, 0x14000
	v_lshl_add_u64 v[174:175], v[246:247], 0, s[40:41]
	global_load_lds_dwordx4 v[174:175], off
	s_or_b32 m0, s100, 0x16000
	v_lshl_add_u64 v[174:175], v[248:249], 0, s[40:41]
	global_load_lds_dwordx4 v[174:175], off
	s_waitcnt vmcnt(6)
	s_barrier
; #define LDA8(dst, b, h) _Pragma("unroll") for (int m = 0; m < 4; ++m) _Pragma("unroll") for (int k = 0; k < 2; ++k) \
;     dst[m][k] = *(const bf16x8*)((const char*)SA8(b, h) + lds_byte8(wr * 64 + m * 16 + fr, k * 32 + fq * 8))
; #define LDB8(dst, b, h) _Pragma("unroll") for (int n = 0; n < 2; ++n) _Pragma("unroll") for (int k = 0; k < 2; ++k) \
;     dst[n][k] = *(const bf16x8*)((const char*)SB8(b, h) + lds_byte8(wc * 32 + n * 16 + fr, k * 32 + fq * 8))
; #define WAIT_V8(n) asm volatile("s_waitcnt vmcnt(" #n ")" ::: "memory")
; #define WAIT_L8(n) asm volatile("s_waitcnt lgkmcnt(" #n ")" ::: "memory")
; #define BAR8 __builtin_amdgcn_s_barrier()
; #define SCHED8 __builtin_amdgcn_sched_barrier(0)
;     ...
;     WAIT_V8(6); BAR8; MMA8(1, 1, At, B1); BAR8;
;     LDB8(B0, 1, 0); SCHED8; LDA8(At, 1, 0); STAGE8(SA8(0, 1), A, lda, brow + 128, tt + 2);
;     WAIT_L8(8); BAR8; WAIT_L8(0); MMA8(0, 0, At, B0); BAR8; SCHED8;
;     LDB8(B1, 1, 1); STAGE8(SB8(1, 0), Bt, K, bcol, tt + 3);
;     BAR8; WAIT_L8(0); MMA8(0, 1, At, B1); BAR8;
	v_mfma_f32_16x16x32_f16 v[32:35], v[190:193], v[226:229], 0
	v_mfma_f32_16x16x32_f16 v[28:31], v[190:193], v[238:241], 0
	v_mfma_f32_16x16x32_f16 v[24:27], v[198:201], v[226:229], 0
	v_mfma_f32_16x16x32_f16 v[20:23], v[198:201], v[238:241], 0
	v_mfma_f32_16x16x32_f16 v[16:19], v[206:209], v[226:229], 0
	v_mfma_f32_16x16x32_f16 v[12:15], v[206:209], v[238:241], 0
	v_mfma_f32_16x16x32_f16 v[8:11], v[214:217], v[226:229], 0
	v_mfma_f32_16x16x32_f16 v[4:7], v[214:217], v[238:241], 0
	v_mfma_f32_16x16x32_f16 v[32:35], v[194:197], v[230:233], v[32:35]
	v_mfma_f32_16x16x32_f16 v[28:31], v[194:197], v[242:245], v[28:31]
	v_mfma_f32_16x16x32_f16 v[24:27], v[202:205], v[230:233], v[24:27]
	v_mfma_f32_16x16x32_f16 v[20:23], v[202:205], v[242:245], v[20:23]
	v_mfma_f32_16x16x32_f16 v[16:19], v[210:213], v[230:233], v[16:19]
	v_mfma_f32_16x16x32_f16 v[12:15], v[210:213], v[242:245], v[12:15]
	v_mfma_f32_16x16x32_f16 v[8:11], v[218:221], v[230:233], v[8:11]
	v_mfma_f32_16x16x32_f16 v[4:7], v[218:221], v[242:245], v[4:7]
	s_barrier
	ds_read_b128 v[174:177], v163
	ds_read_b128 v[178:181], v163 offset:1024
	ds_read_b128 v[182:185], v163 offset:2048
	ds_read_b128 v[186:189], v163 offset:3072
	v_lshl_add_u64 v[226:227], v[222:223], 0, s[18:19]
	s_or_b32 m0, s100, 0x4000
	ds_read_b128 v[190:193], v161 offset:32768
	ds_read_b128 v[194:197], v161 offset:33792
	ds_read_b128 v[198:201], v160 offset:32768
	ds_read_b128 v[202:205], v160 offset:33792
	ds_read_b128 v[206:209], v159 offset:32768
	ds_read_b128 v[210:213], v159 offset:33792
	ds_read_b128 v[214:217], v158 offset:32768
	ds_read_b128 v[218:221], v158 offset:33792
	global_load_lds_dwordx4 v[226:227], off
	s_or_b32 m0, s100, 0x6000
	v_lshl_add_u64 v[226:227], v[236:237], 0, s[18:19]
	global_load_lds_dwordx4 v[226:227], off
	s_waitcnt lgkmcnt(8)
	s_barrier
	s_waitcnt lgkmcnt(0)
	v_mfma_f32_16x16x32_f16 v[128:131], v[190:193], v[174:177], v[128:131]
	v_mfma_f32_16x16x32_f16 v[124:127], v[190:193], v[182:185], v[124:127]
	v_mfma_f32_16x16x32_f16 v[120:123], v[198:201], v[174:177], v[120:123]
	v_mfma_f32_16x16x32_f16 v[116:119], v[198:201], v[182:185], v[116:119]
	v_mfma_f32_16x16x32_f16 v[112:115], v[206:209], v[174:177], v[112:115]
	v_mfma_f32_16x16x32_f16 v[108:111], v[206:209], v[182:185], v[108:111]
	v_mfma_f32_16x16x32_f16 v[104:107], v[214:217], v[174:177], v[104:107]
	v_mfma_f32_16x16x32_f16 v[100:103], v[214:217], v[182:185], v[100:103]
	v_mfma_f32_16x16x32_f16 v[128:131], v[194:197], v[178:181], v[128:131]
	v_mfma_f32_16x16x32_f16 v[124:127], v[194:197], v[186:189], v[124:127]
	v_mfma_f32_16x16x32_f16 v[120:123], v[202:205], v[178:181], v[120:123]
	v_mfma_f32_16x16x32_f16 v[116:119], v[202:205], v[186:189], v[116:119]
	v_mfma_f32_16x16x32_f16 v[112:115], v[210:213], v[178:181], v[112:115]
	v_mfma_f32_16x16x32_f16 v[108:111], v[210:213], v[186:189], v[108:111]
	v_mfma_f32_16x16x32_f16 v[104:107], v[218:221], v[178:181], v[104:107]
	v_mfma_f32_16x16x32_f16 v[100:103], v[218:221], v[186:189], v[100:103]
	s_barrier
	v_lshl_add_u64 v[250:251], v[246:247], 0, s[42:43]
	s_or_b32 m0, s100, 0x18000
	ds_read_b128 v[226:229], v162
	ds_read_b128 v[230:233], v162 offset:1024
	ds_read_b128 v[238:241], v162 offset:2048
	ds_read_b128 v[242:245], v162 offset:3072
	global_load_lds_dwordx4 v[250:251], off
	s_or_b32 m0, s100, 0x1a000
	v_lshl_add_u64 v[250:251], v[248:249], 0, s[42:43]
	global_load_lds_dwordx4 v[250:251], off
	s_barrier
; #define LDA8(dst, b, h) _Pragma("unroll") for (int m = 0; m < 4; ++m) _Pragma("unroll") for (int k = 0; k < 2; ++k) \
;     dst[m][k] = *(const bf16x8*)((const char*)SA8(b, h) + lds_byte8(wr * 64 + m * 16 + fr, k * 32 + fq * 8))
; #define WAIT_V8(n) asm volatile("s_waitcnt vmcnt(" #n ")" ::: "memory")
; #define WAIT_L8(n) asm volatile("s_waitcnt lgkmcnt(" #n ")" ::: "memory")
; #define BAR8 __builtin_amdgcn_s_barrier()
; #define SCHED8 __builtin_amdgcn_sched_barrier(0)
;     ...
;     BAR8; WAIT_L8(0); MMA8(0, 1, At, B1); BAR8;
;     LDA8(At, 1, 1); STAGE8(SA8(1, 0), A, lda, brow, tt + 3);
;     BAR8; WAIT_L8(0); MMA8(1, 0, At, B0); BAR8; SCHED8;
;     STAGE8(SB8(1, 1), Bt, K, bcol + 128, tt + 3);
;     WAIT_V8(6); BAR8; MMA8(1, 1, At, B1); BAR8;
	s_waitcnt lgkmcnt(0)
	v_mfma_f32_16x16x32_f16 v[96:99], v[190:193], v[226:229], v[96:99]
	v_mfma_f32_16x16x32_f16 v[92:95], v[190:193], v[238:241], v[92:95]
	v_mfma_f32_16x16x32_f16 v[88:91], v[198:201], v[226:229], v[88:91]
	v_mfma_f32_16x16x32_f16 v[84:87], v[198:201], v[238:241], v[84:87]
	v_mfma_f32_16x16x32_f16 v[80:83], v[206:209], v[226:229], v[80:83]
	v_mfma_f32_16x16x32_f16 v[76:79], v[206:209], v[238:241], v[76:79]
	v_mfma_f32_16x16x32_f16 v[72:75], v[214:217], v[226:229], v[72:75]
	v_mfma_f32_16x16x32_f16 v[68:71], v[214:217], v[238:241], v[68:71]
	v_mfma_f32_16x16x32_f16 v[96:99], v[194:197], v[230:233], v[96:99]
	v_mfma_f32_16x16x32_f16 v[92:95], v[194:197], v[242:245], v[92:95]
	v_mfma_f32_16x16x32_f16 v[88:91], v[202:205], v[230:233], v[88:91]
	v_mfma_f32_16x16x32_f16 v[84:87], v[202:205], v[242:245], v[84:87]
	v_mfma_f32_16x16x32_f16 v[80:83], v[210:213], v[230:233], v[80:83]
	v_mfma_f32_16x16x32_f16 v[76:79], v[210:213], v[242:245], v[76:79]
	v_mfma_f32_16x16x32_f16 v[72:75], v[218:221], v[230:233], v[72:75]
	v_mfma_f32_16x16x32_f16 v[68:71], v[218:221], v[242:245], v[68:71]
	v_lshl_add_u64 v[222:223], v[222:223], 0, s[22:23]
	s_or_b32 m0, s100, 0x8000
	s_barrier
	ds_read_b128 v[190:193], v161 offset:49152
	ds_read_b128 v[194:197], v161 offset:50176
	ds_read_b128 v[198:201], v160 offset:49152
	ds_read_b128 v[202:205], v160 offset:50176
	ds_read_b128 v[206:209], v159 offset:49152
	ds_read_b128 v[210:213], v159 offset:50176
	ds_read_b128 v[214:217], v158 offset:49152
	ds_read_b128 v[218:221], v158 offset:50176
	global_load_lds_dwordx4 v[222:223], off
	s_or_b32 m0, s100, 0xa000
	v_lshl_add_u64 v[222:223], v[236:237], 0, s[22:23]
	global_load_lds_dwordx4 v[222:223], off
	s_barrier
	s_waitcnt lgkmcnt(0)
	v_mfma_f32_16x16x32_f16 v[64:67], v[190:193], v[174:177], v[64:67]
	v_mfma_f32_16x16x32_f16 v[60:63], v[190:193], v[182:185], v[60:63]
	v_mfma_f32_16x16x32_f16 v[56:59], v[198:201], v[174:177], v[56:59]
	v_mfma_f32_16x16x32_f16 v[52:55], v[198:201], v[182:185], v[52:55]
	v_mfma_f32_16x16x32_f16 v[48:51], v[206:209], v[174:177], v[48:51]
	v_mfma_f32_16x16x32_f16 v[44:47], v[206:209], v[182:185], v[44:47]
	v_mfma_f32_16x16x32_f16 v[40:43], v[214:217], v[174:177], v[40:43]
	v_mfma_f32_16x16x32_f16 v[36:39], v[214:217], v[182:185], v[36:39]
	v_mfma_f32_16x16x32_f16 v[64:67], v[194:197], v[178:181], v[64:67]
	v_mfma_f32_16x16x32_f16 v[60:63], v[194:197], v[186:189], v[60:63]
	v_mfma_f32_16x16x32_f16 v[56:59], v[202:205], v[178:181], v[56:59]
	v_mfma_f32_16x16x32_f16 v[52:55], v[202:205], v[186:189], v[52:55]
	v_mfma_f32_16x16x32_f16 v[48:51], v[210:213], v[178:181], v[48:51]
	v_mfma_f32_16x16x32_f16 v[44:47], v[210:213], v[186:189], v[44:47]
	v_mfma_f32_16x16x32_f16 v[40:43], v[218:221], v[178:181], v[40:43]
	v_mfma_f32_16x16x32_f16 v[36:39], v[218:221], v[186:189], v[36:39]
	s_barrier
	s_or_b32 m0, s100, 0x1c000
	v_lshl_add_u64 v[174:175], v[246:247], 0, s[44:45]
	global_load_lds_dwordx4 v[174:175], off
	s_or_b32 m0, s100, 0x1e000
	v_lshl_add_u64 v[174:175], v[248:249], 0, s[44:45]
	global_load_lds_dwordx4 v[174:175], off
	s_waitcnt vmcnt(6)
	s_barrier
	v_mfma_f32_16x16x32_f16 v[32:35], v[190:193], v[226:229], v[32:35]
	v_mfma_f32_16x16x32_f16 v[28:31], v[190:193], v[238:241], v[28:31]
	v_mfma_f32_16x16x32_f16 v[24:27], v[198:201], v[226:229], v[24:27]
	v_mfma_f32_16x16x32_f16 v[20:23], v[198:201], v[238:241], v[20:23]
	v_mfma_f32_16x16x32_f16 v[16:19], v[206:209], v[226:229], v[16:19]
	v_mfma_f32_16x16x32_f16 v[12:15], v[206:209], v[238:241], v[12:15]
	v_mfma_f32_16x16x32_f16 v[8:11], v[214:217], v[226:229], v[8:11]
	v_mfma_f32_16x16x32_f16 v[4:7], v[214:217], v[238:241], v[4:7]
	v_mfma_f32_16x16x32_f16 v[32:35], v[194:197], v[230:233], v[32:35]
	v_mfma_f32_16x16x32_f16 v[28:31], v[194:197], v[242:245], v[28:31]
	v_mfma_f32_16x16x32_f16 v[24:27], v[202:205], v[230:233], v[24:27]
	v_mfma_f32_16x16x32_f16 v[20:23], v[202:205], v[242:245], v[20:23]
	v_mfma_f32_16x16x32_f16 v[16:19], v[210:213], v[230:233], v[16:19]
	v_mfma_f32_16x16x32_f16 v[12:15], v[210:213], v[242:245], v[12:15]
	v_mfma_f32_16x16x32_f16 v[8:11], v[218:221], v[230:233], v[8:11]
	v_mfma_f32_16x16x32_f16 v[4:7], v[218:221], v[242:245], v[4:7]
	s_add_i32 s1, s1, 2
	s_add_u32 s12, s12, 0x100
	s_addc_u32 s13, s13, 0
	s_cmp_lt_u32 s1, 12
	s_cbranch_scc0 .Lpk_exitb_6
	.p2align	6

; #define LDA8(dst, b, h) _Pragma("unroll") for (int m = 0; m < 4; ++m) _Pragma("unroll") for (int k = 0; k < 2; ++k) \
;     dst[m][k] = *(const bf16x8*)((const char*)SA8(b, h) + lds_byte8(wr * 64 + m * 16 + fr, k * 32 + fq * 8))
; #define LDB8(dst, b, h) _Pragma("unroll") for (int n = 0; n < 2; ++n) _Pragma("unroll") for (int k = 0; k < 2; ++k) \
;     dst[n][k] = *(const bf16x8*)((const char*)SB8(b, h) + lds_byte8(wc * 32 + n * 16 + fr, k * 32 + fq * 8))
; #define WAIT_V8(n) asm volatile("s_waitcnt vmcnt(" #n ")" ::: "memory")
; #define WAIT_L8(n) asm volatile("s_waitcnt lgkmcnt(" #n ")" ::: "memory")
; #define BAR8 __builtin_amdgcn_s_barrier()
; #define SCHED8 __builtin_amdgcn_sched_barrier(0)
;     ...
;   if (wr == 1) BAR8;
;   WAIT_V8(4); BAR8;
;   STAGE8(SB8(1, 0), Bt, K, bcol, 1); STAGE8(SA8(1, 0), A, lda, brow, 1); STAGE8(SB8(1, 1), Bt, K, bcol + 128, 1);
;   WAIT_V8(6); BAR8;
;   for (int tt = 0; tt < nt - 2; tt += 2) {
;     LDB8(B0, 0, 0); SCHED8; LDA8(At, 0, 0); STAGE8(SA8(1, 1), A, lda, brow + 128, tt + 1);
;     WAIT_L8(8); BAR8; WAIT_L8(0); MMA8(0, 0, At, B0); BAR8; SCHED8;
;     LDB8(B1, 0, 1); STAGE8(SB8(0, 0), Bt, K, bcol, tt + 2);
.LBB0_1324:
	s_or_b64 exec, exec, s[12:13]
	s_mov_b64 s[36:37], 0x80
	v_lshl_add_u64 v[10:11], v[10:11], 0, s[36:37]
	s_or_b32 m0, s100, 0x18000
	s_waitcnt vmcnt(4)
	s_barrier
	global_load_lds_dwordx4 v[10:11], off
	v_lshl_add_u64 v[10:11], v[12:13], 0, s[36:37]
	s_or_b32 m0, s100, 0x1a000
	s_nop 0
	global_load_lds_dwordx4 v[10:11], off
	v_lshl_add_u64 v[10:11], v[14:15], 0, s[36:37]
	s_or_b32 m0, s100, 0x8000
	s_nop 0
	global_load_lds_dwordx4 v[10:11], off
	v_lshl_add_u64 v[10:11], v[16:17], 0, s[36:37]
	s_or_b32 m0, s100, 0xa000
	s_nop 0
	global_load_lds_dwordx4 v[10:11], off
	s_or_b32 m0, s100, 0x1c000
	v_lshl_add_u64 v[10:11], v[18:19], 0, s[36:37]
	global_load_lds_dwordx4 v[10:11], off
	v_lshl_add_u64 v[10:11], v[20:21], 0, s[36:37]
	s_or_b32 m0, s100, 0x1e000
	v_and_b32_e32 v147, 15, v3
	global_load_lds_dwordx4 v[10:11], off
	v_bfe_u32 v148, v3, 4, 2
	v_lshlrev_b32_e32 v10, 4, v148
	v_lshlrev_b32_e32 v11, 6, v147
	v_lshlrev_b32_e32 v13, 2, v3
	v_or_b32_e32 v12, v10, v11
	v_and_b32_e32 v13, 32, v13
	s_mov_b32 s12, 0x10000
	v_bitop3_b32 v18, v12, s12, v13 bitop3:0xde
	s_mov_b32 s12, 0x14000
	v_bitop3_b32 v17, v10, v13, v11 bitop3:0x36
	v_bitop3_b32 v19, v12, s12, v13 bitop3:0xde
	s_mov_b32 s12, 0x18000
	v_lshlrev_b32_e32 v11, 6, v3
	v_bitop3_b32 v20, v12, s12, v13 bitop3:0xde
	s_mov_b32 s12, 0x1c000
	v_and_b32_e32 v11, 0x3c0, v11
	s_movk_i32 s31, 0x1600
	s_and_b32 s29, s21, 0xffffff00
	v_bitop3_b32 v21, v12, s12, v13 bitop3:0xde
	v_bitop3_b32 v24, v11, v13, v10 bitop3:0x36
	v_mad_i64_i32 v[10:11], s[12:13], v5, s31, 0
	v_mov_b32_e32 v5, 0x1600
	v_mad_i64_i32 v[12:13], s[12:13], s29, v5, v[10:11]
	v_lshl_add_u64 v[12:13], v[12:13], 0, v[6:7]
	v_lshl_add_u64 v[138:139], s[4:5], 0, v[12:13]
	v_mad_i64_i32 v[12:13], s[12:13], v22, s31, 0
	v_mad_i64_i32 v[14:15], s[12:13], s29, v5, v[12:13]
	s_bfe_u32 s29, s20, 0x60008
	v_mov_b32_e32 v5, 0x160000
	v_mad_u64_u32 v[10:11], s[12:13], s29, v5, v[10:11]
	v_lshl_add_u64 v[6:7], v[10:11], 0, v[6:7]
	v_bfe_u32 v146, v3, 6, 2
	s_waitcnt vmcnt(6)
	v_lshlrev_b32_e32 v149, 6, v23
	v_lshlrev_b32_e32 v23, 13, v23
	v_lshl_add_u64 v[142:143], s[2:3], 0, v[6:7]
	v_mad_u64_u32 v[6:7], s[12:13], s29, v5, v[12:13]
	v_lshlrev_b32_e32 v16, 12, v146
	v_or_b32_e32 v25, 0x800, v23
	v_or_b32_e32 v26, 0x1000, v23
	v_or_b32_e32 v27, 0x1800, v23
	v_lshl_add_u64 v[14:15], v[14:15], 0, v[8:9]
	v_lshl_add_u64 v[6:7], v[6:7], 0, v[8:9]
	s_ashr_i32 s9, s8, 31
	v_lshl_add_u64 v[140:141], s[4:5], 0, v[14:15]
	v_lshl_add_u64 v[144:145], s[2:3], 0, v[6:7]
	s_mov_b32 s29, -2
	s_mov_b64 s[12:13], 0
	v_add_u32_e32 v171, v18, v16
	v_add_u32_e32 v156, v17, v23
	v_add_u32_e32 v155, v24, v25
	v_add_u32_e32 v154, v24, v26
	v_add_u32_e32 v153, v24, v27
	v_add_u32_e32 v169, v19, v16
	v_add_u32_e32 v159, v20, v16
	v_add_u32_e32 v158, v21, v16
	s_mov_b64 s[36:37], 0x20b0080
	s_mov_b64 s[38:39], 0xd5a0100
	s_mov_b64 s[40:41], 0x2000100
	s_mov_b64 s[42:43], 0xd650100
	s_mov_b64 s[44:45], 0x20b0100
	s_mov_b64 s[46:47], 0xd5a0180
	s_mov_b64 s[48:49], 0x2000180
	s_mov_b64 s[50:51], 0xd650180
	s_barrier
	ds_read_b128 v[174:177], v171
	ds_read_b128 v[178:181], v171 offset:1024
	ds_read_b128 v[182:185], v171 offset:2048
	ds_read_b128 v[186:189], v171 offset:3072
	v_lshl_add_u64 v[222:223], v[142:143], 0, s[12:13]
	v_lshl_add_u64 v[226:227], v[222:223], 0, s[36:37]
	s_or_b32 m0, s100, 0xc000
	v_lshl_add_u64 v[236:237], v[144:145], 0, s[12:13]
	ds_read_b128 v[190:193], v156
	ds_read_b128 v[194:197], v156 offset:1024
	ds_read_b128 v[198:201], v155
	ds_read_b128 v[202:205], v155 offset:1024
	ds_read_b128 v[206:209], v154
	ds_read_b128 v[210:213], v154 offset:1024
	ds_read_b128 v[214:217], v153
	ds_read_b128 v[218:221], v153 offset:1024
	global_load_lds_dwordx4 v[226:227], off
	s_or_b32 m0, s100, 0xe000
	v_lshl_add_u64 v[226:227], v[236:237], 0, s[36:37]
	global_load_lds_dwordx4 v[226:227], off
	s_waitcnt lgkmcnt(8)
	s_barrier
	s_waitcnt lgkmcnt(0)
	v_mfma_f32_16x16x32_bf16 v[128:131], v[190:193], v[174:177], 0
	v_mfma_f32_16x16x32_bf16 v[124:127], v[190:193], v[182:185], 0
	v_mfma_f32_16x16x32_bf16 v[120:123], v[198:201], v[174:177], 0
	v_mfma_f32_16x16x32_bf16 v[116:119], v[198:201], v[182:185], 0
	v_mfma_f32_16x16x32_bf16 v[112:115], v[206:209], v[174:177], 0
	v_mfma_f32_16x16x32_bf16 v[108:111], v[206:209], v[182:185], 0
	v_mfma_f32_16x16x32_bf16 v[104:107], v[214:217], v[174:177], 0
	v_mfma_f32_16x16x32_bf16 v[100:103], v[214:217], v[182:185], 0
	v_mfma_f32_16x16x32_bf16 v[128:131], v[194:197], v[178:181], v[128:131]
	v_mfma_f32_16x16x32_bf16 v[124:127], v[194:197], v[186:189], v[124:127]
	v_mfma_f32_16x16x32_bf16 v[120:123], v[202:205], v[178:181], v[120:123]
	v_mfma_f32_16x16x32_bf16 v[116:119], v[202:205], v[186:189], v[116:119]
	v_mfma_f32_16x16x32_bf16 v[112:115], v[210:213], v[178:181], v[112:115]
	v_mfma_f32_16x16x32_bf16 v[108:111], v[210:213], v[186:189], v[108:111]
	v_mfma_f32_16x16x32_bf16 v[104:107], v[218:221], v[178:181], v[104:107]
	v_mfma_f32_16x16x32_bf16 v[100:103], v[218:221], v[186:189], v[100:103]
	s_barrier
	v_lshl_add_u64 v[246:247], v[138:139], 0, s[12:13]
	v_lshl_add_u64 v[248:249], v[246:247], 0, s[38:39]
	s_or_b32 m0, s100, 0x10000
	ds_read_b128 v[226:229], v169
	ds_read_b128 v[230:233], v169 offset:1024
	ds_read_b128 v[238:241], v169 offset:2048
	ds_read_b128 v[242:245], v169 offset:3072
	global_load_lds_dwordx4 v[248:249], off
	v_lshl_add_u64 v[248:249], v[140:141], 0, s[12:13]
	s_or_b32 m0, s100, 0x12000
	v_lshl_add_u64 v[250:251], v[248:249], 0, s[38:39]
	global_load_lds_dwordx4 v[250:251], off
	s_barrier
; #define LDA8(dst, b, h) _Pragma("unroll") for (int m = 0; m < 4; ++m) _Pragma("unroll") for (int k = 0; k < 2; ++k) \
;     dst[m][k] = *(const bf16x8*)((const char*)SA8(b, h) + lds_byte8(wr * 64 + m * 16 + fr, k * 32 + fq * 8))
; #define LDB8(dst, b, h) _Pragma("unroll") for (int n = 0; n < 2; ++n) _Pragma("unroll") for (int k = 0; k < 2; ++k) \
;     dst[n][k] = *(const bf16x8*)((const char*)SB8(b, h) + lds_byte8(wc * 32 + n * 16 + fr, k * 32 + fq * 8))
; #define WAIT_V8(n) asm volatile("s_waitcnt vmcnt(" #n ")" ::: "memory")
; #define WAIT_L8(n) asm volatile("s_waitcnt lgkmcnt(" #n ")" ::: "memory")
; #define BAR8 __builtin_amdgcn_s_barrier()
; #define SCHED8 __builtin_amdgcn_sched_barrier(0)
;     ...
;     BAR8; WAIT_L8(0); MMA8(0, 1, At, B1); BAR8;
;     LDA8(At, 0, 1); STAGE8(SA8(0, 0), A, lda, brow, tt + 2);
;     BAR8; WAIT_L8(0); MMA8(1, 0, At, B0); BAR8; SCHED8;
;     STAGE8(SB8(0, 1), Bt, K, bcol + 128, tt + 2);
;     WAIT_V8(6); BAR8; MMA8(1, 1, At, B1); BAR8;
;     LDB8(B0, 1, 0); SCHED8; LDA8(At, 1, 0); STAGE8(SA8(0, 1), A, lda, brow + 128, tt + 2);
;     WAIT_L8(8); BAR8; WAIT_L8(0); MMA8(0, 0, At, B0); BAR8; SCHED8;
	s_waitcnt lgkmcnt(0)
	v_mfma_f32_16x16x32_bf16 v[96:99], v[190:193], v[226:229], 0
	v_mfma_f32_16x16x32_bf16 v[92:95], v[190:193], v[238:241], 0
	v_mfma_f32_16x16x32_bf16 v[88:91], v[198:201], v[226:229], 0
	v_mfma_f32_16x16x32_bf16 v[84:87], v[198:201], v[238:241], 0
	v_mfma_f32_16x16x32_bf16 v[80:83], v[206:209], v[226:229], 0
	v_mfma_f32_16x16x32_bf16 v[76:79], v[206:209], v[238:241], 0
	v_mfma_f32_16x16x32_bf16 v[72:75], v[214:217], v[226:229], 0
	v_mfma_f32_16x16x32_bf16 v[68:71], v[214:217], v[238:241], 0
	v_mfma_f32_16x16x32_bf16 v[96:99], v[194:197], v[230:233], v[96:99]
	v_mfma_f32_16x16x32_bf16 v[92:95], v[194:197], v[242:245], v[92:95]
	v_mfma_f32_16x16x32_bf16 v[88:91], v[202:205], v[230:233], v[88:91]
	v_mfma_f32_16x16x32_bf16 v[84:87], v[202:205], v[242:245], v[84:87]
	v_mfma_f32_16x16x32_bf16 v[80:83], v[210:213], v[230:233], v[80:83]
	v_mfma_f32_16x16x32_bf16 v[76:79], v[210:213], v[242:245], v[76:79]
	v_mfma_f32_16x16x32_bf16 v[72:75], v[218:221], v[230:233], v[72:75]
	v_mfma_f32_16x16x32_bf16 v[68:71], v[218:221], v[242:245], v[68:71]
	v_lshl_add_u64 v[250:251], v[222:223], 0, s[40:41]
	s_mov_b32 m0, s100
	s_barrier
	ds_read_b128 v[190:193], v156 offset:16384
	ds_read_b128 v[194:197], v156 offset:17408
	ds_read_b128 v[198:201], v155 offset:16384
	ds_read_b128 v[202:205], v155 offset:17408
	ds_read_b128 v[206:209], v154 offset:16384
	ds_read_b128 v[210:213], v154 offset:17408
	ds_read_b128 v[214:217], v153 offset:16384
	ds_read_b128 v[218:221], v153 offset:17408
	global_load_lds_dwordx4 v[250:251], off
	s_or_b32 m0, s100, 0x2000
	v_lshl_add_u64 v[250:251], v[236:237], 0, s[40:41]
	global_load_lds_dwordx4 v[250:251], off
	s_barrier
	s_waitcnt lgkmcnt(0)
	v_mfma_f32_16x16x32_bf16 v[64:67], v[190:193], v[174:177], 0
	v_mfma_f32_16x16x32_bf16 v[60:63], v[190:193], v[182:185], 0
	v_mfma_f32_16x16x32_bf16 v[56:59], v[198:201], v[174:177], 0
	v_mfma_f32_16x16x32_bf16 v[52:55], v[198:201], v[182:185], 0
	v_mfma_f32_16x16x32_bf16 v[48:51], v[206:209], v[174:177], 0
	v_mfma_f32_16x16x32_bf16 v[44:47], v[206:209], v[182:185], 0
	v_mfma_f32_16x16x32_bf16 v[40:43], v[214:217], v[174:177], 0
	v_mfma_f32_16x16x32_bf16 v[36:39], v[214:217], v[182:185], 0
	v_mfma_f32_16x16x32_bf16 v[64:67], v[194:197], v[178:181], v[64:67]
	v_mfma_f32_16x16x32_bf16 v[60:63], v[194:197], v[186:189], v[60:63]
	v_mfma_f32_16x16x32_bf16 v[56:59], v[202:205], v[178:181], v[56:59]
	v_mfma_f32_16x16x32_bf16 v[52:55], v[202:205], v[186:189], v[52:55]
	v_mfma_f32_16x16x32_bf16 v[48:51], v[210:213], v[178:181], v[48:51]
	v_mfma_f32_16x16x32_bf16 v[44:47], v[210:213], v[186:189], v[44:47]
	v_mfma_f32_16x16x32_bf16 v[40:43], v[218:221], v[178:181], v[40:43]
	v_mfma_f32_16x16x32_bf16 v[36:39], v[218:221], v[186:189], v[36:39]
	s_barrier
	s_or_b32 m0, s100, 0x14000
	v_lshl_add_u64 v[174:175], v[246:247], 0, s[42:43]
	global_load_lds_dwordx4 v[174:175], off
	s_or_b32 m0, s100, 0x16000
	v_lshl_add_u64 v[174:175], v[248:249], 0, s[42:43]
	global_load_lds_dwordx4 v[174:175], off
	s_waitcnt vmcnt(6)
	s_barrier
	v_mfma_f32_16x16x32_bf16 v[32:35], v[190:193], v[226:229], 0
	v_mfma_f32_16x16x32_bf16 v[28:31], v[190:193], v[238:241], 0
	v_mfma_f32_16x16x32_bf16 v[24:27], v[198:201], v[226:229], 0
	v_mfma_f32_16x16x32_bf16 v[20:23], v[198:201], v[238:241], 0
	v_mfma_f32_16x16x32_bf16 v[16:19], v[206:209], v[226:229], 0
	v_mfma_f32_16x16x32_bf16 v[12:15], v[206:209], v[238:241], 0
	v_mfma_f32_16x16x32_bf16 v[8:11], v[214:217], v[226:229], 0
	v_mfma_f32_16x16x32_bf16 v[4:7], v[214:217], v[238:241], 0
	v_mfma_f32_16x16x32_bf16 v[32:35], v[194:197], v[230:233], v[32:35]
	v_mfma_f32_16x16x32_bf16 v[28:31], v[194:197], v[242:245], v[28:31]
	v_mfma_f32_16x16x32_bf16 v[24:27], v[202:205], v[230:233], v[24:27]
	v_mfma_f32_16x16x32_bf16 v[20:23], v[202:205], v[242:245], v[20:23]
	v_mfma_f32_16x16x32_bf16 v[16:19], v[210:213], v[230:233], v[16:19]
	v_mfma_f32_16x16x32_bf16 v[12:15], v[210:213], v[242:245], v[12:15]
	v_mfma_f32_16x16x32_bf16 v[8:11], v[218:221], v[230:233], v[8:11]
	v_mfma_f32_16x16x32_bf16 v[4:7], v[218:221], v[242:245], v[4:7]
	s_barrier
	ds_read_b128 v[174:177], v159
	ds_read_b128 v[178:181], v159 offset:1024
	ds_read_b128 v[182:185], v159 offset:2048
	ds_read_b128 v[186:189], v159 offset:3072
	v_lshl_add_u64 v[226:227], v[222:223], 0, s[44:45]
	s_or_b32 m0, s100, 0x4000
	ds_read_b128 v[190:193], v156 offset:32768
	ds_read_b128 v[194:197], v156 offset:33792
	ds_read_b128 v[198:201], v155 offset:32768
	ds_read_b128 v[202:205], v155 offset:33792
	ds_read_b128 v[206:209], v154 offset:32768
	ds_read_b128 v[210:213], v154 offset:33792
	ds_read_b128 v[214:217], v153 offset:32768
	ds_read_b128 v[218:221], v153 offset:33792
	global_load_lds_dwordx4 v[226:227], off
	s_or_b32 m0, s100, 0x6000
	v_lshl_add_u64 v[226:227], v[236:237], 0, s[44:45]
	global_load_lds_dwordx4 v[226:227], off
	s_waitcnt lgkmcnt(8)
	s_barrier
; #define LDA8(dst, b, h) _Pragma("unroll") for (int m = 0; m < 4; ++m) _Pragma("unroll") for (int k = 0; k < 2; ++k) \
;     dst[m][k] = *(const bf16x8*)((const char*)SA8(b, h) + lds_byte8(wr * 64 + m * 16 + fr, k * 32 + fq * 8))
; #define LDB8(dst, b, h) _Pragma("unroll") for (int n = 0; n < 2; ++n) _Pragma("unroll") for (int k = 0; k < 2; ++k) \
;     dst[n][k] = *(const bf16x8*)((const char*)SB8(b, h) + lds_byte8(wc * 32 + n * 16 + fr, k * 32 + fq * 8))
; #define WAIT_V8(n) asm volatile("s_waitcnt vmcnt(" #n ")" ::: "memory")
; #define WAIT_L8(n) asm volatile("s_waitcnt lgkmcnt(" #n ")" ::: "memory")
; #define BAR8 __builtin_amdgcn_s_barrier()
; #define SCHED8 __builtin_amdgcn_sched_barrier(0)
;     ...
;     WAIT_L8(8); BAR8; WAIT_L8(0); MMA8(0, 0, At, B0); BAR8; SCHED8;
;     LDB8(B1, 1, 1); STAGE8(SB8(1, 0), Bt, K, bcol, tt + 3);
;     BAR8; WAIT_L8(0); MMA8(0, 1, At, B1); BAR8;
;     LDA8(At, 1, 1); STAGE8(SA8(1, 0), A, lda, brow, tt + 3);
;     BAR8; WAIT_L8(0); MMA8(1, 0, At, B0); BAR8; SCHED8;
;     STAGE8(SB8(1, 1), Bt, K, bcol + 128, tt + 3);
;     WAIT_V8(6); BAR8; MMA8(1, 1, At, B1); BAR8;
	s_waitcnt lgkmcnt(0)
	v_mfma_f32_16x16x32_bf16 v[128:131], v[190:193], v[174:177], v[128:131]
	v_mfma_f32_16x16x32_bf16 v[124:127], v[190:193], v[182:185], v[124:127]
	v_mfma_f32_16x16x32_bf16 v[120:123], v[198:201], v[174:177], v[120:123]
	v_mfma_f32_16x16x32_bf16 v[116:119], v[198:201], v[182:185], v[116:119]
	v_mfma_f32_16x16x32_bf16 v[112:115], v[206:209], v[174:177], v[112:115]
	v_mfma_f32_16x16x32_bf16 v[108:111], v[206:209], v[182:185], v[108:111]
	v_mfma_f32_16x16x32_bf16 v[104:107], v[214:217], v[174:177], v[104:107]
	v_mfma_f32_16x16x32_bf16 v[100:103], v[214:217], v[182:185], v[100:103]
	v_mfma_f32_16x16x32_bf16 v[128:131], v[194:197], v[178:181], v[128:131]
	v_mfma_f32_16x16x32_bf16 v[124:127], v[194:197], v[186:189], v[124:127]
	v_mfma_f32_16x16x32_bf16 v[120:123], v[202:205], v[178:181], v[120:123]
	v_mfma_f32_16x16x32_bf16 v[116:119], v[202:205], v[186:189], v[116:119]
	v_mfma_f32_16x16x32_bf16 v[112:115], v[210:213], v[178:181], v[112:115]
	v_mfma_f32_16x16x32_bf16 v[108:111], v[210:213], v[186:189], v[108:111]
	v_mfma_f32_16x16x32_bf16 v[104:107], v[218:221], v[178:181], v[104:107]
	v_mfma_f32_16x16x32_bf16 v[100:103], v[218:221], v[186:189], v[100:103]
	s_barrier
	v_lshl_add_u64 v[250:251], v[246:247], 0, s[46:47]
	s_or_b32 m0, s100, 0x18000
	ds_read_b128 v[226:229], v158
	ds_read_b128 v[230:233], v158 offset:1024
	ds_read_b128 v[238:241], v158 offset:2048
	ds_read_b128 v[242:245], v158 offset:3072
	global_load_lds_dwordx4 v[250:251], off
	s_or_b32 m0, s100, 0x1a000
	v_lshl_add_u64 v[250:251], v[248:249], 0, s[46:47]
	global_load_lds_dwordx4 v[250:251], off
	s_barrier
	s_waitcnt lgkmcnt(0)
	v_mfma_f32_16x16x32_bf16 v[96:99], v[190:193], v[226:229], v[96:99]
	v_mfma_f32_16x16x32_bf16 v[92:95], v[190:193], v[238:241], v[92:95]
	v_mfma_f32_16x16x32_bf16 v[88:91], v[198:201], v[226:229], v[88:91]
	v_mfma_f32_16x16x32_bf16 v[84:87], v[198:201], v[238:241], v[84:87]
	v_mfma_f32_16x16x32_bf16 v[80:83], v[206:209], v[226:229], v[80:83]
	v_mfma_f32_16x16x32_bf16 v[76:79], v[206:209], v[238:241], v[76:79]
	v_mfma_f32_16x16x32_bf16 v[72:75], v[214:217], v[226:229], v[72:75]
	v_mfma_f32_16x16x32_bf16 v[68:71], v[214:217], v[238:241], v[68:71]
	v_mfma_f32_16x16x32_bf16 v[96:99], v[194:197], v[230:233], v[96:99]
	v_mfma_f32_16x16x32_bf16 v[92:95], v[194:197], v[242:245], v[92:95]
	v_mfma_f32_16x16x32_bf16 v[88:91], v[202:205], v[230:233], v[88:91]
	v_mfma_f32_16x16x32_bf16 v[84:87], v[202:205], v[242:245], v[84:87]
	v_mfma_f32_16x16x32_bf16 v[80:83], v[210:213], v[230:233], v[80:83]
	v_mfma_f32_16x16x32_bf16 v[76:79], v[210:213], v[242:245], v[76:79]
	v_mfma_f32_16x16x32_bf16 v[72:75], v[218:221], v[230:233], v[72:75]
	v_mfma_f32_16x16x32_bf16 v[68:71], v[218:221], v[242:245], v[68:71]
	v_lshl_add_u64 v[222:223], v[222:223], 0, s[48:49]
	s_or_b32 m0, s100, 0x8000
	s_barrier
	ds_read_b128 v[190:193], v156 offset:49152
	ds_read_b128 v[194:197], v156 offset:50176
	ds_read_b128 v[198:201], v155 offset:49152
	ds_read_b128 v[202:205], v155 offset:50176
	ds_read_b128 v[206:209], v154 offset:49152
	ds_read_b128 v[210:213], v154 offset:50176
	ds_read_b128 v[214:217], v153 offset:49152
	ds_read_b128 v[218:221], v153 offset:50176
	global_load_lds_dwordx4 v[222:223], off
	s_or_b32 m0, s100, 0xa000
	v_lshl_add_u64 v[222:223], v[236:237], 0, s[48:49]
	global_load_lds_dwordx4 v[222:223], off
	s_barrier
	s_waitcnt lgkmcnt(0)
	v_mfma_f32_16x16x32_bf16 v[64:67], v[190:193], v[174:177], v[64:67]
	v_mfma_f32_16x16x32_bf16 v[60:63], v[190:193], v[182:185], v[60:63]
	v_mfma_f32_16x16x32_bf16 v[56:59], v[198:201], v[174:177], v[56:59]
	v_mfma_f32_16x16x32_bf16 v[52:55], v[198:201], v[182:185], v[52:55]
	v_mfma_f32_16x16x32_bf16 v[48:51], v[206:209], v[174:177], v[48:51]
	v_mfma_f32_16x16x32_bf16 v[44:47], v[206:209], v[182:185], v[44:47]
	v_mfma_f32_16x16x32_bf16 v[40:43], v[214:217], v[174:177], v[40:43]
	v_mfma_f32_16x16x32_bf16 v[36:39], v[214:217], v[182:185], v[36:39]
	v_mfma_f32_16x16x32_bf16 v[64:67], v[194:197], v[178:181], v[64:67]
	v_mfma_f32_16x16x32_bf16 v[60:63], v[194:197], v[186:189], v[60:63]
	v_mfma_f32_16x16x32_bf16 v[56:59], v[202:205], v[178:181], v[56:59]
	v_mfma_f32_16x16x32_bf16 v[52:55], v[202:205], v[186:189], v[52:55]
	v_mfma_f32_16x16x32_bf16 v[48:51], v[210:213], v[178:181], v[48:51]
	v_mfma_f32_16x16x32_bf16 v[44:47], v[210:213], v[186:189], v[44:47]
	v_mfma_f32_16x16x32_bf16 v[40:43], v[218:221], v[178:181], v[40:43]
	v_mfma_f32_16x16x32_bf16 v[36:39], v[218:221], v[186:189], v[36:39]
	s_barrier
	s_or_b32 m0, s100, 0x1c000
	v_lshl_add_u64 v[174:175], v[246:247], 0, s[50:51]
	global_load_lds_dwordx4 v[174:175], off
	s_or_b32 m0, s100, 0x1e000
	v_lshl_add_u64 v[174:175], v[248:249], 0, s[50:51]
	global_load_lds_dwordx4 v[174:175], off
	s_waitcnt vmcnt(6)
	s_barrier
	v_mfma_f32_16x16x32_bf16 v[32:35], v[190:193], v[226:229], v[32:35]
	v_mfma_f32_16x16x32_bf16 v[28:31], v[190:193], v[238:241], v[28:31]
	v_mfma_f32_16x16x32_bf16 v[24:27], v[198:201], v[226:229], v[24:27]
	v_mfma_f32_16x16x32_bf16 v[20:23], v[198:201], v[238:241], v[20:23]
	v_mfma_f32_16x16x32_bf16 v[16:19], v[206:209], v[226:229], v[16:19]
	v_mfma_f32_16x16x32_bf16 v[12:15], v[206:209], v[238:241], v[12:15]
	v_mfma_f32_16x16x32_bf16 v[8:11], v[214:217], v[226:229], v[8:11]
	v_mfma_f32_16x16x32_bf16 v[4:7], v[214:217], v[238:241], v[4:7]
	v_mfma_f32_16x16x32_bf16 v[32:35], v[194:197], v[230:233], v[32:35]
	v_mfma_f32_16x16x32_bf16 v[28:31], v[194:197], v[242:245], v[28:31]
	v_mfma_f32_16x16x32_bf16 v[24:27], v[202:205], v[230:233], v[24:27]
	v_mfma_f32_16x16x32_bf16 v[20:23], v[202:205], v[242:245], v[20:23]
	v_mfma_f32_16x16x32_bf16 v[16:19], v[210:213], v[230:233], v[16:19]
	v_mfma_f32_16x16x32_bf16 v[12:15], v[210:213], v[242:245], v[12:15]
	v_mfma_f32_16x16x32_bf16 v[8:11], v[218:221], v[230:233], v[8:11]
	v_mfma_f32_16x16x32_bf16 v[4:7], v[218:221], v[242:245], v[4:7]
	s_add_i32 s29, s29, 2
	s_add_u32 s12, s12, 0x100
	s_addc_u32 s13, s13, 0
	s_cmp_lt_u32 s29, 40
	s_cbranch_scc0 .Lpk_exitb_7
	.p2align	6
